# plus: light LOAD phases of SP2 GEMM loops issue the 16 ds_reads first, next-tile pointer selection after (in-place temps)
# baseline (speedup 1.0000x reference)
; #define PG8_STAGE(bufoff, gbase, voff) do { _Pragma("unroll") for (int _i = 0; _i < 2; ++_i) \
;         __builtin_amdgcn_global_load_lds((const unsigned*)((const char*)(gbase) + (voff)[_i]), (LAS unsigned*)(lds + (bufoff) + ldsw + _i * 8192), 16, 0, 0); } while (0)
; #define PG8_LDA(dst, b, h) do { _Pragma("unroll") for (int m = 0; m < 4; ++m) _Pragma("unroll") for (int k = 0; k < 2; ++k) dst[m][k] = *(const LAS bf16x8*)(lds + PG8_SA(b, h) + aoff + m * 2048 + k * 1024); } while (0)
; #define PG8_LDB(dst, b, h) do { _Pragma("unroll") for (int n = 0; n < 2; ++n) _Pragma("unroll") for (int k = 0; k < 2; ++k) dst[n][k] = *(const LAS bf16x8*)(lds + PG8_SB(b, h) + boff + n * 2048 + k * 1024); } while (0)
; #define PG8_WAIT_V(n) asm volatile("s_waitcnt vmcnt(" #n ")" ::: "memory")
; #define PG8_WAIT_L(n) asm volatile("s_waitcnt lgkmcnt(" #n ")" ::: "memory")
; #define PG8_BAR __builtin_amdgcn_s_barrier()
; #define PG8_SCHED __builtin_amdgcn_sched_barrier(0)
;     ...
;             const bool last = (t == nt - 2);
;             const char* a1 = cA + (size_t)(t + 1) * kstep;
;             const char* a2 = last ? nA : cA + (size_t)(t + 2) * kstep; const char* b2 = last ? nB : cB + (size_t)(t + 2) * kstep;
;             const char* a3 = a2 + kstep; const char* b3 = b2 + kstep;
;             if constexpr (SP2) {
;             PG8_LDB(B0, 0, 0); PG8_LDB(B1, 0, 1); PG8_SCHED; PG8_LDA(At, 0, 0); PG8_STAGE(PG8_SA(1, 1), a1 + hstepA, voffA);
;             PG8_WAIT_V(8); PG8_WAIT_L(0); PG8_BAR; PG8_MMA(0, 0, At, B0); PG8_MMA(0, 1, At, B1); PG8_BAR; PG8_SCHED;
;             PG8_LDA(At, 0, 1); PG8_STAGE(PG8_SB(0, 0), b2, voffB); PG8_STAGE(PG8_SB(0, 1), b2 + hstepB, voffB); PG8_STAGE(PG8_SA(0, 0), a2, voffA);
;             PG8_WAIT_V(8); PG8_WAIT_L(0); PG8_BAR; PG8_MMA(1, 0, At, B0); PG8_MMA(1, 1, At, B1); PG8_BAR; PG8_SCHED;
.LBB0_165:
	s_add_i32 s62, 0, 0x10000
	s_add_i32 s63, 0, 0x14000
	ds_read_b128 v[162:165], v246
	ds_read_b128 v[166:169], v246 offset:1024
	ds_read_b128 v[170:173], v246 offset:2048
	ds_read_b128 v[174:177], v246 offset:3072
	ds_read_b128 v[178:181], v247
	ds_read_b128 v[182:185], v247 offset:1024
	ds_read_b128 v[186:189], v247 offset:2048
	ds_read_b128 v[190:193], v247 offset:3072
	ds_read_b128 v[194:197], v160
	ds_read_b128 v[198:201], v160 offset:1024
	ds_read_b128 v[202:205], v160 offset:2048
	ds_read_b128 v[206:209], v160 offset:3072
	ds_read_b128 v[210:213], v160 offset:4096
	ds_read_b128 v[214:217], v160 offset:5120
	ds_read_b128 v[218:221], v160 offset:6144
	ds_read_b128 v[226:229], v160 offset:7168
	v_lshl_add_u64 v[230:231], v[148:149], 0, s[38:39]
	s_cmpk_eq_i32 s38, 0xf00
	v_lshl_add_u64 v[230:231], v[230:231], 0, s[4:5]
	s_cselect_b64 vcc, -1, 0
	v_lshl_add_u64 v[232:233], v[154:155], 0, s[38:39]
	v_cndmask_b32_e32 v231, v231, v145, vcc
	v_cndmask_b32_e32 v230, v230, v144, vcc
	v_cndmask_b32_e32 v233, v233, v147, vcc
	v_cndmask_b32_e32 v232, v232, v146, vcc
	s_add_i32 m0, s3, 0xc000
	v_lshl_add_u64 v[234:235], v[152:153], 0, s[38:39]
	global_load_lds_dwordx4 v[234:235], off
	v_lshl_add_u64 v[234:235], v[150:151], 0, s[38:39]
	s_add_i32 m0, s3, 0xe000
	s_nop 0
	global_load_lds_dwordx4 v[234:235], off
	s_waitcnt vmcnt(8)
	s_waitcnt lgkmcnt(0)
	s_barrier
	s_setprio 1
	v_mfma_i32_16x16x64_i8 v[128:131], v[162:165], v[194:197], v[128:131]
	v_mfma_i32_16x16x64_i8 v[124:127], v[170:173], v[194:197], v[124:127]
	v_mfma_i32_16x16x64_i8 v[112:115], v[162:165], v[202:205], v[112:115]
	v_mfma_i32_16x16x64_i8 v[108:111], v[170:173], v[202:205], v[108:111]
	v_mfma_i32_16x16x64_i8 v[96:99], v[162:165], v[210:213], v[96:99]
	v_mfma_i32_16x16x64_i8 v[92:95], v[170:173], v[210:213], v[92:95]
	v_mfma_i32_16x16x64_i8 v[80:83], v[162:165], v[218:221], v[80:83]
	v_mfma_i32_16x16x64_i8 v[76:79], v[170:173], v[218:221], v[76:79]
	v_mfma_i32_16x16x64_i8 v[128:131], v[166:169], v[198:201], v[128:131]
	v_mfma_i32_16x16x64_i8 v[124:127], v[174:177], v[198:201], v[124:127]
	v_mfma_i32_16x16x64_i8 v[112:115], v[166:169], v[206:209], v[112:115]
	v_mfma_i32_16x16x64_i8 v[108:111], v[174:177], v[206:209], v[108:111]
	v_mfma_i32_16x16x64_i8 v[96:99], v[166:169], v[214:217], v[96:99]
	v_mfma_i32_16x16x64_i8 v[92:95], v[174:177], v[214:217], v[92:95]
	v_mfma_i32_16x16x64_i8 v[80:83], v[166:169], v[226:229], v[80:83]
	v_mfma_i32_16x16x64_i8 v[76:79], v[174:177], v[226:229], v[76:79]
	v_mfma_i32_16x16x64_i8 v[120:123], v[178:181], v[194:197], v[120:123]
	v_mfma_i32_16x16x64_i8 v[116:119], v[186:189], v[194:197], v[116:119]
	v_mfma_i32_16x16x64_i8 v[104:107], v[178:181], v[202:205], v[104:107]
	v_mfma_i32_16x16x64_i8 v[100:103], v[186:189], v[202:205], v[100:103]
	v_mfma_i32_16x16x64_i8 v[88:91], v[178:181], v[210:213], v[88:91]
	v_mfma_i32_16x16x64_i8 v[84:87], v[186:189], v[210:213], v[84:87]
	v_mfma_i32_16x16x64_i8 v[72:75], v[178:181], v[218:221], v[72:75]
	v_mfma_i32_16x16x64_i8 v[68:71], v[186:189], v[218:221], v[68:71]
	v_mfma_i32_16x16x64_i8 v[120:123], v[182:185], v[198:201], v[120:123]
	v_mfma_i32_16x16x64_i8 v[116:119], v[190:193], v[198:201], v[116:119]
	v_mfma_i32_16x16x64_i8 v[104:107], v[182:185], v[206:209], v[104:107]
	v_mfma_i32_16x16x64_i8 v[100:103], v[190:193], v[206:209], v[100:103]
	v_mfma_i32_16x16x64_i8 v[88:91], v[182:185], v[214:217], v[88:91]
	v_mfma_i32_16x16x64_i8 v[84:87], v[190:193], v[214:217], v[84:87]
	v_mfma_i32_16x16x64_i8 v[72:75], v[182:185], v[226:229], v[72:75]
	v_mfma_i32_16x16x64_i8 v[68:71], v[190:193], v[226:229], v[68:71]
	s_setprio 0
	s_barrier
	s_add_i32 s62, s62, s2
	v_lshl_add_u64 v[234:235], v[232:233], 0, v[2:3]
	s_mov_b32 m0, s62
	ds_read_b128 v[194:197], v160 offset:16384
	ds_read_b128 v[198:201], v160 offset:17408
	ds_read_b128 v[202:205], v160 offset:18432
	ds_read_b128 v[206:209], v160 offset:19456
	ds_read_b128 v[210:213], v160 offset:20480
	ds_read_b128 v[214:217], v160 offset:21504
	ds_read_b128 v[218:221], v160 offset:22528
	ds_read_b128 v[226:229], v160 offset:23552
	global_load_lds_dwordx4 v[234:235], off
	v_lshl_add_u64 v[236:237], v[232:233], 0, v[134:135]
	s_add_i32 m0, s62, 0x2000
	v_lshl_add_u64 v[232:233], v[232:233], 0, v[138:139]
	s_add_i32 s62, s63, s2
	global_load_lds_dwordx4 v[236:237], off
	v_lshl_add_u64 v[238:239], v[232:233], 0, v[2:3]
	s_mov_b32 m0, s62
	v_lshl_add_u64 v[232:233], v[232:233], 0, v[134:135]
	global_load_lds_dwordx4 v[238:239], off
	s_add_i32 m0, s62, 0x2000
	v_lshl_add_u64 v[240:241], v[230:231], 0, v[0:1]
	global_load_lds_dwordx4 v[232:233], off
	s_mov_b32 m0, s3
	v_lshl_add_u64 v[242:243], v[230:231], 0, v[132:133]
	global_load_lds_dwordx4 v[240:241], off
	s_mov_b32 m0, s8
	s_nop 0
	global_load_lds_dwordx4 v[242:243], off
	s_waitcnt vmcnt(8)
	s_waitcnt lgkmcnt(0)
	s_barrier
; #define PG8_STAGE(bufoff, gbase, voff) do { _Pragma("unroll") for (int _i = 0; _i < 2; ++_i) \
;         __builtin_amdgcn_global_load_lds((const unsigned*)((const char*)(gbase) + (voff)[_i]), (LAS unsigned*)(lds + (bufoff) + ldsw + _i * 8192), 16, 0, 0); } while (0)
; #define PG8_LDA(dst, b, h) do { _Pragma("unroll") for (int m = 0; m < 4; ++m) _Pragma("unroll") for (int k = 0; k < 2; ++k) dst[m][k] = *(const LAS bf16x8*)(lds + PG8_SA(b, h) + aoff + m * 2048 + k * 1024); } while (0)
; #define PG8_LDB(dst, b, h) do { _Pragma("unroll") for (int n = 0; n < 2; ++n) _Pragma("unroll") for (int k = 0; k < 2; ++k) dst[n][k] = *(const LAS bf16x8*)(lds + PG8_SB(b, h) + boff + n * 2048 + k * 1024); } while (0)
; #define PG8_WAIT_V(n) asm volatile("s_waitcnt vmcnt(" #n ")" ::: "memory")
; #define PG8_WAIT_L(n) asm volatile("s_waitcnt lgkmcnt(" #n ")" ::: "memory")
; #define PG8_BAR __builtin_amdgcn_s_barrier()
; #define PG8_SCHED __builtin_amdgcn_sched_barrier(0)
;     ...
;             PG8_WAIT_V(8); PG8_WAIT_L(0); PG8_BAR; PG8_MMA(1, 0, At, B0); PG8_MMA(1, 1, At, B1); PG8_BAR; PG8_SCHED;
;             PG8_LDB(B0, 1, 0); PG8_LDB(B1, 1, 1); PG8_SCHED; PG8_LDA(At, 1, 0); PG8_STAGE(PG8_SA(0, 1), a2 + hstepA, voffA);
;             PG8_WAIT_V(8); PG8_WAIT_L(0); PG8_BAR; PG8_MMA(0, 0, At, B0); PG8_MMA(0, 1, At, B1); PG8_BAR; PG8_SCHED;
	s_setprio 1
	v_mfma_i32_16x16x64_i8 v[64:67], v[162:165], v[194:197], v[64:67]
	v_mfma_i32_16x16x64_i8 v[60:63], v[170:173], v[194:197], v[60:63]
	v_mfma_i32_16x16x64_i8 v[48:51], v[162:165], v[202:205], v[48:51]
	v_mfma_i32_16x16x64_i8 v[44:47], v[170:173], v[202:205], v[44:47]
	v_mfma_i32_16x16x64_i8 v[32:35], v[162:165], v[210:213], v[32:35]
	v_mfma_i32_16x16x64_i8 v[28:31], v[170:173], v[210:213], v[28:31]
	v_mfma_i32_16x16x64_i8 v[16:19], v[162:165], v[218:221], v[16:19]
	v_mfma_i32_16x16x64_i8 v[12:15], v[170:173], v[218:221], v[12:15]
	v_mfma_i32_16x16x64_i8 v[64:67], v[166:169], v[198:201], v[64:67]
	v_mfma_i32_16x16x64_i8 v[60:63], v[174:177], v[198:201], v[60:63]
	v_mfma_i32_16x16x64_i8 v[48:51], v[166:169], v[206:209], v[48:51]
	v_mfma_i32_16x16x64_i8 v[44:47], v[174:177], v[206:209], v[44:47]
	v_mfma_i32_16x16x64_i8 v[32:35], v[166:169], v[214:217], v[32:35]
	v_mfma_i32_16x16x64_i8 v[28:31], v[174:177], v[214:217], v[28:31]
	v_mfma_i32_16x16x64_i8 v[16:19], v[166:169], v[226:229], v[16:19]
	v_mfma_i32_16x16x64_i8 v[12:15], v[174:177], v[226:229], v[12:15]
	v_mfma_i32_16x16x64_i8 v[56:59], v[178:181], v[194:197], v[56:59]
	v_mfma_i32_16x16x64_i8 v[52:55], v[186:189], v[194:197], v[52:55]
	v_mfma_i32_16x16x64_i8 v[40:43], v[178:181], v[202:205], v[40:43]
	v_mfma_i32_16x16x64_i8 v[36:39], v[186:189], v[202:205], v[36:39]
	v_mfma_i32_16x16x64_i8 v[24:27], v[178:181], v[210:213], v[24:27]
	v_mfma_i32_16x16x64_i8 v[20:23], v[186:189], v[210:213], v[20:23]
	v_mfma_i32_16x16x64_i8 v[8:11], v[178:181], v[218:221], v[8:11]
	v_mfma_i32_16x16x64_i8 v[4:7], v[186:189], v[218:221], v[4:7]
	v_mfma_i32_16x16x64_i8 v[56:59], v[182:185], v[198:201], v[56:59]
	v_mfma_i32_16x16x64_i8 v[52:55], v[190:193], v[198:201], v[52:55]
	v_mfma_i32_16x16x64_i8 v[40:43], v[182:185], v[206:209], v[40:43]
	v_mfma_i32_16x16x64_i8 v[36:39], v[190:193], v[206:209], v[36:39]
	v_mfma_i32_16x16x64_i8 v[24:27], v[182:185], v[214:217], v[24:27]
	v_mfma_i32_16x16x64_i8 v[20:23], v[190:193], v[214:217], v[20:23]
	v_mfma_i32_16x16x64_i8 v[8:11], v[182:185], v[226:229], v[8:11]
	v_mfma_i32_16x16x64_i8 v[4:7], v[190:193], v[226:229], v[4:7]
	s_setprio 0
	s_barrier
	s_add_i32 s62, 0, 0x18000
	s_add_i32 s63, 0, 0x1c000
	ds_read_b128 v[162:165], v248
	ds_read_b128 v[166:169], v248 offset:1024
	ds_read_b128 v[170:173], v248 offset:2048
	ds_read_b128 v[174:177], v248 offset:3072
	ds_read_b128 v[178:181], v249
	ds_read_b128 v[182:185], v249 offset:1024
	ds_read_b128 v[186:189], v249 offset:2048
	ds_read_b128 v[190:193], v249 offset:3072
	ds_read_b128 v[194:197], v160 offset:32768
	ds_read_b128 v[198:201], v160 offset:33792
	ds_read_b128 v[202:205], v160 offset:34816
	ds_read_b128 v[206:209], v160 offset:35840
	ds_read_b128 v[210:213], v160 offset:36864
	ds_read_b128 v[214:217], v160 offset:37888
	ds_read_b128 v[218:221], v160 offset:38912
	ds_read_b128 v[226:229], v160 offset:39936
	v_lshl_add_u64 v[230:231], v[230:231], 0, v[136:137]
	s_mov_b32 m0, s9
	v_lshl_add_u64 v[244:245], v[230:231], 0, v[0:1]
	global_load_lds_dwordx4 v[244:245], off
	v_lshl_add_u64 v[230:231], v[230:231], 0, v[132:133]
	s_mov_b32 m0, s15
	s_nop 0
	global_load_lds_dwordx4 v[230:231], off
	s_waitcnt vmcnt(8)
	s_waitcnt lgkmcnt(0)
	s_barrier
	s_setprio 1
	v_mfma_i32_16x16x64_i8 v[128:131], v[162:165], v[194:197], v[128:131]
	v_mfma_i32_16x16x64_i8 v[124:127], v[170:173], v[194:197], v[124:127]
	v_mfma_i32_16x16x64_i8 v[112:115], v[162:165], v[202:205], v[112:115]
	v_mfma_i32_16x16x64_i8 v[108:111], v[170:173], v[202:205], v[108:111]
	v_mfma_i32_16x16x64_i8 v[96:99], v[162:165], v[210:213], v[96:99]
	v_mfma_i32_16x16x64_i8 v[92:95], v[170:173], v[210:213], v[92:95]
	v_mfma_i32_16x16x64_i8 v[80:83], v[162:165], v[218:221], v[80:83]
	v_mfma_i32_16x16x64_i8 v[76:79], v[170:173], v[218:221], v[76:79]
	v_mfma_i32_16x16x64_i8 v[128:131], v[166:169], v[198:201], v[128:131]
	v_mfma_i32_16x16x64_i8 v[124:127], v[174:177], v[198:201], v[124:127]
	v_mfma_i32_16x16x64_i8 v[112:115], v[166:169], v[206:209], v[112:115]
	v_mfma_i32_16x16x64_i8 v[108:111], v[174:177], v[206:209], v[108:111]
	v_mfma_i32_16x16x64_i8 v[96:99], v[166:169], v[214:217], v[96:99]
	v_mfma_i32_16x16x64_i8 v[92:95], v[174:177], v[214:217], v[92:95]
	v_mfma_i32_16x16x64_i8 v[80:83], v[166:169], v[226:229], v[80:83]
	v_mfma_i32_16x16x64_i8 v[76:79], v[174:177], v[226:229], v[76:79]
	v_mfma_i32_16x16x64_i8 v[120:123], v[178:181], v[194:197], v[120:123]
	v_mfma_i32_16x16x64_i8 v[116:119], v[186:189], v[194:197], v[116:119]
	v_mfma_i32_16x16x64_i8 v[104:107], v[178:181], v[202:205], v[104:107]
	v_mfma_i32_16x16x64_i8 v[100:103], v[186:189], v[202:205], v[100:103]
	v_mfma_i32_16x16x64_i8 v[88:91], v[178:181], v[210:213], v[88:91]
	v_mfma_i32_16x16x64_i8 v[84:87], v[186:189], v[210:213], v[84:87]
	v_mfma_i32_16x16x64_i8 v[72:75], v[178:181], v[218:221], v[72:75]
	v_mfma_i32_16x16x64_i8 v[68:71], v[186:189], v[218:221], v[68:71]
	v_mfma_i32_16x16x64_i8 v[120:123], v[182:185], v[198:201], v[120:123]
	v_mfma_i32_16x16x64_i8 v[116:119], v[190:193], v[198:201], v[116:119]
	v_mfma_i32_16x16x64_i8 v[104:107], v[182:185], v[206:209], v[104:107]
	v_mfma_i32_16x16x64_i8 v[100:103], v[190:193], v[206:209], v[100:103]
	v_mfma_i32_16x16x64_i8 v[88:91], v[182:185], v[214:217], v[88:91]
	v_mfma_i32_16x16x64_i8 v[84:87], v[190:193], v[214:217], v[84:87]
	v_mfma_i32_16x16x64_i8 v[72:75], v[182:185], v[226:229], v[72:75]
	v_mfma_i32_16x16x64_i8 v[68:71], v[190:193], v[226:229], v[68:71]
	s_setprio 0
	s_barrier
; #define PG8_STAGE(bufoff, gbase, voff) do { _Pragma("unroll") for (int _i = 0; _i < 2; ++_i) \
;         __builtin_amdgcn_global_load_lds((const unsigned*)((const char*)(gbase) + (voff)[_i]), (LAS unsigned*)(lds + (bufoff) + ldsw + _i * 8192), 16, 0, 0); } while (0)
; #define PG8_LDA(dst, b, h) do { _Pragma("unroll") for (int m = 0; m < 4; ++m) _Pragma("unroll") for (int k = 0; k < 2; ++k) dst[m][k] = *(const LAS bf16x8*)(lds + PG8_SA(b, h) + aoff + m * 2048 + k * 1024); } while (0)
; #define PG8_WAIT_V(n) asm volatile("s_waitcnt vmcnt(" #n ")" ::: "memory")
; #define PG8_WAIT_L(n) asm volatile("s_waitcnt lgkmcnt(" #n ")" ::: "memory")
; #define PG8_BAR __builtin_amdgcn_s_barrier()
; #define PG8_SCHED __builtin_amdgcn_sched_barrier(0)
;     ...
;             PG8_LDA(At, 1, 1); PG8_STAGE(PG8_SB(1, 0), b3, voffB); PG8_STAGE(PG8_SB(1, 1), b3 + hstepB, voffB); PG8_STAGE(PG8_SA(1, 0), a3, voffA);
;             PG8_WAIT_V(8); PG8_WAIT_L(0); PG8_BAR; PG8_MMA(1, 0, At, B0); PG8_MMA(1, 1, At, B1); PG8_BAR; PG8_SCHED;
	s_add_i32 s62, s62, s2
	v_lshl_add_u64 v[230:231], v[234:235], 0, s[52:53]
	s_mov_b32 m0, s62
	ds_read_b128 v[194:197], v160 offset:49152
	ds_read_b128 v[198:201], v160 offset:50176
	ds_read_b128 v[202:205], v160 offset:51200
	ds_read_b128 v[206:209], v160 offset:52224
	ds_read_b128 v[210:213], v160 offset:53248
	ds_read_b128 v[214:217], v160 offset:54272
	ds_read_b128 v[218:221], v160 offset:55296
	ds_read_b128 v[226:229], v160 offset:56320
	global_load_lds_dwordx4 v[230:231], off
	v_lshl_add_u64 v[230:231], v[236:237], 0, s[52:53]
	s_add_i32 m0, s62, 0x2000
	s_add_i32 s62, s63, s2
	global_load_lds_dwordx4 v[230:231], off
	v_lshl_add_u64 v[230:231], v[238:239], 0, s[52:53]
	s_mov_b32 m0, s62
	s_nop 0
	global_load_lds_dwordx4 v[230:231], off
	v_lshl_add_u64 v[230:231], v[232:233], 0, s[52:53]
	s_add_i32 m0, s62, 0x2000
	s_nop 0
	global_load_lds_dwordx4 v[230:231], off
	v_lshl_add_u64 v[230:231], v[240:241], 0, s[52:53]
	s_mov_b32 m0, s47
	s_nop 0
	global_load_lds_dwordx4 v[230:231], off
	v_lshl_add_u64 v[230:231], v[242:243], 0, s[52:53]
	s_mov_b32 m0, s48
	s_nop 0
	global_load_lds_dwordx4 v[230:231], off
	s_waitcnt vmcnt(8)
	s_waitcnt lgkmcnt(0)
	s_barrier
	s_setprio 1
	v_mfma_i32_16x16x64_i8 v[64:67], v[162:165], v[194:197], v[64:67]
	v_mfma_i32_16x16x64_i8 v[60:63], v[170:173], v[194:197], v[60:63]
	v_mfma_i32_16x16x64_i8 v[48:51], v[162:165], v[202:205], v[48:51]
	v_mfma_i32_16x16x64_i8 v[44:47], v[170:173], v[202:205], v[44:47]
	v_mfma_i32_16x16x64_i8 v[32:35], v[162:165], v[210:213], v[32:35]
	v_mfma_i32_16x16x64_i8 v[28:31], v[170:173], v[210:213], v[28:31]
	v_mfma_i32_16x16x64_i8 v[16:19], v[162:165], v[218:221], v[16:19]
	v_mfma_i32_16x16x64_i8 v[12:15], v[170:173], v[218:221], v[12:15]
	v_mfma_i32_16x16x64_i8 v[64:67], v[166:169], v[198:201], v[64:67]
	v_mfma_i32_16x16x64_i8 v[60:63], v[174:177], v[198:201], v[60:63]
	v_mfma_i32_16x16x64_i8 v[48:51], v[166:169], v[206:209], v[48:51]
	v_mfma_i32_16x16x64_i8 v[44:47], v[174:177], v[206:209], v[44:47]
	v_mfma_i32_16x16x64_i8 v[32:35], v[166:169], v[214:217], v[32:35]
	v_mfma_i32_16x16x64_i8 v[28:31], v[174:177], v[214:217], v[28:31]
	v_mfma_i32_16x16x64_i8 v[16:19], v[166:169], v[226:229], v[16:19]
	v_mfma_i32_16x16x64_i8 v[12:15], v[174:177], v[226:229], v[12:15]
	v_mfma_i32_16x16x64_i8 v[56:59], v[178:181], v[194:197], v[56:59]
	v_mfma_i32_16x16x64_i8 v[52:55], v[186:189], v[194:197], v[52:55]
	v_mfma_i32_16x16x64_i8 v[40:43], v[178:181], v[202:205], v[40:43]
	v_mfma_i32_16x16x64_i8 v[36:39], v[186:189], v[202:205], v[36:39]
	v_mfma_i32_16x16x64_i8 v[24:27], v[178:181], v[210:213], v[24:27]
	v_mfma_i32_16x16x64_i8 v[20:23], v[186:189], v[210:213], v[20:23]
	v_mfma_i32_16x16x64_i8 v[8:11], v[178:181], v[218:221], v[8:11]
	v_mfma_i32_16x16x64_i8 v[4:7], v[186:189], v[218:221], v[4:7]
	v_mfma_i32_16x16x64_i8 v[56:59], v[182:185], v[198:201], v[56:59]
	v_mfma_i32_16x16x64_i8 v[52:55], v[190:193], v[198:201], v[52:55]
	v_mfma_i32_16x16x64_i8 v[40:43], v[182:185], v[206:209], v[40:43]
	v_mfma_i32_16x16x64_i8 v[36:39], v[190:193], v[206:209], v[36:39]
	v_mfma_i32_16x16x64_i8 v[24:27], v[182:185], v[214:217], v[24:27]
	v_mfma_i32_16x16x64_i8 v[20:23], v[190:193], v[214:217], v[20:23]
	v_mfma_i32_16x16x64_i8 v[8:11], v[182:185], v[226:229], v[8:11]
	v_mfma_i32_16x16x64_i8 v[4:7], v[190:193], v[226:229], v[4:7]
	s_setprio 0
	s_barrier
	s_add_i32 s60, s60, 2
	s_add_u32 s38, s38, 0x100
	s_addc_u32 s39, s39, 0
	s_cmp_gt_u32 s60, 29
	s_cbranch_scc0 .LBB0_165
	s_and_b64 vcc, exec, s[42:43]
	s_cbranch_vccz .LBB0_168
	s_barrier

; #define PG8_STAGE(bufoff, gbase, voff) do { _Pragma("unroll") for (int _i = 0; _i < 2; ++_i) \
;         __builtin_amdgcn_global_load_lds((const unsigned*)((const char*)(gbase) + (voff)[_i]), (LAS unsigned*)(lds + (bufoff) + ldsw + _i * 8192), 16, 0, 0); } while (0)
; #define PG8_LDA(dst, b, h) do { _Pragma("unroll") for (int m = 0; m < 4; ++m) _Pragma("unroll") for (int k = 0; k < 2; ++k) dst[m][k] = *(const LAS bf16x8*)(lds + PG8_SA(b, h) + aoff + m * 2048 + k * 1024); } while (0)
; #define PG8_LDB(dst, b, h) do { _Pragma("unroll") for (int n = 0; n < 2; ++n) _Pragma("unroll") for (int k = 0; k < 2; ++k) dst[n][k] = *(const LAS bf16x8*)(lds + PG8_SB(b, h) + boff + n * 2048 + k * 1024); } while (0)
; #define PG8_WAIT_V(n) asm volatile("s_waitcnt vmcnt(" #n ")" ::: "memory")
; #define PG8_WAIT_L(n) asm volatile("s_waitcnt lgkmcnt(" #n ")" ::: "memory")
; #define PG8_BAR __builtin_amdgcn_s_barrier()
; #define PG8_SCHED __builtin_amdgcn_sched_barrier(0)
;     ...
;             const char* a2 = last ? nA : cA + (size_t)(t + 2) * kstep; const char* b2 = last ? nB : cB + (size_t)(t + 2) * kstep;
;             const char* a3 = a2 + kstep; const char* b3 = b2 + kstep;
;             if constexpr (SP2) {
;             PG8_LDB(B0, 0, 0); PG8_LDB(B1, 0, 1); PG8_SCHED; PG8_LDA(At, 0, 0); PG8_STAGE(PG8_SA(1, 1), a1 + hstepA, voffA);
;             PG8_WAIT_V(8); PG8_WAIT_L(0); PG8_BAR; PG8_MMA(0, 0, At, B0); PG8_MMA(0, 1, At, B1); PG8_BAR; PG8_SCHED;
;             PG8_LDA(At, 0, 1); PG8_STAGE(PG8_SB(0, 0), b2, voffB); PG8_STAGE(PG8_SB(0, 1), b2 + hstepB, voffB); PG8_STAGE(PG8_SA(0, 0), a2, voffA);
;             PG8_WAIT_V(8); PG8_WAIT_L(0); PG8_BAR; PG8_MMA(1, 0, At, B0); PG8_MMA(1, 1, At, B1); PG8_BAR; PG8_SCHED;
.LBB0_440:
	s_add_i32 s63, 0, 0x10000
	s_add_i32 s64, 0, 0x14000
	ds_read_b128 v[28:31], v204
	ds_read_b128 v[32:35], v204 offset:1024
	ds_read_b128 v[20:23], v204 offset:2048
	ds_read_b128 v[24:27], v204 offset:3072
	ds_read_b128 v[12:15], v205
	ds_read_b128 v[16:19], v205 offset:1024
	ds_read_b128 v[4:7], v205 offset:2048
	ds_read_b128 v[8:11], v205 offset:3072
	ds_read_b128 v[190:193], v212
	ds_read_b128 v[194:197], v212 offset:1024
	ds_read_b128 v[226:229], v212 offset:2048
	ds_read_b128 v[230:233], v212 offset:3072
	ds_read_b128 v[234:237], v212 offset:4096
	ds_read_b128 v[238:241], v212 offset:5120
	ds_read_b128 v[242:245], v212 offset:6144
	ds_read_b128 v[246:249], v212 offset:7168
	v_lshl_add_u64 v[188:189], v[180:181], 0, s[38:39]
	s_cmpk_eq_i32 s38, 0x300
	v_lshl_add_u64 v[188:189], v[188:189], 0, s[4:5]
	s_cselect_b64 vcc, -1, 0
	v_lshl_add_u64 v[198:199], v[186:187], 0, s[38:39]
	v_cndmask_b32_e32 v188, v188, v176, vcc
	v_cndmask_b32_e32 v189, v189, v177, vcc
	v_cndmask_b32_e32 v199, v199, v179, vcc
	v_cndmask_b32_e32 v198, v198, v178, vcc
	s_add_i32 m0, s15, 0xc000
	v_lshl_add_u64 v[200:201], v[184:185], 0, s[38:39]
	global_load_lds_dwordx4 v[200:201], off
	v_lshl_add_u64 v[200:201], v[182:183], 0, s[38:39]
	s_add_i32 m0, s15, 0xe000
	s_nop 0
	global_load_lds_dwordx4 v[200:201], off
	s_waitcnt vmcnt(8)
	s_waitcnt lgkmcnt(0)
	s_barrier
	s_setprio 1
	v_mfma_f32_16x16x128_f8f6f4 v[160:163], v[28:35], v[190:197], v[160:163]
	v_mfma_f32_16x16x128_f8f6f4 v[156:159], v[20:27], v[190:197], v[156:159]
	v_mfma_f32_16x16x128_f8f6f4 v[148:151], v[28:35], v[226:233], v[148:151]
	v_mfma_f32_16x16x128_f8f6f4 v[140:143], v[20:27], v[226:233], v[140:143]
	v_mfma_f32_16x16x128_f8f6f4 v[132:135], v[28:35], v[234:241], v[132:135]
	v_mfma_f32_16x16x128_f8f6f4 v[124:127], v[20:27], v[234:241], v[124:127]
	v_mfma_f32_16x16x128_f8f6f4 v[116:119], v[28:35], v[242:249], v[116:119]
	v_mfma_f32_16x16x128_f8f6f4 v[108:111], v[20:27], v[242:249], v[108:111]
	v_mfma_f32_16x16x128_f8f6f4 v[152:155], v[12:19], v[190:197], v[152:155]
	v_mfma_f32_16x16x128_f8f6f4 v[144:147], v[4:11], v[190:197], v[144:147]
	v_mfma_f32_16x16x128_f8f6f4 v[136:139], v[12:19], v[226:233], v[136:139]
	v_mfma_f32_16x16x128_f8f6f4 v[128:131], v[4:11], v[226:233], v[128:131]
	v_mfma_f32_16x16x128_f8f6f4 v[120:123], v[12:19], v[234:241], v[120:123]
	v_mfma_f32_16x16x128_f8f6f4 v[112:115], v[4:11], v[234:241], v[112:115]
	v_mfma_f32_16x16x128_f8f6f4 v[104:107], v[12:19], v[242:249], v[104:107]
	v_mfma_f32_16x16x128_f8f6f4 v[100:103], v[4:11], v[242:249], v[100:103]
	s_setprio 0
	s_barrier
	s_add_i32 s63, s63, s8
	v_lshl_add_u64 v[190:191], v[198:199], 0, v[2:3]
	s_mov_b32 m0, s63
	ds_read_b128 v[226:229], v212 offset:16384
	ds_read_b128 v[230:233], v212 offset:17408
	ds_read_b128 v[234:237], v212 offset:18432
	ds_read_b128 v[238:241], v212 offset:19456
	ds_read_b128 v[242:245], v212 offset:20480
	ds_read_b128 v[246:249], v212 offset:21504
	ds_read_b128 v[214:217], v212 offset:22528
	ds_read_b128 v[218:221], v212 offset:23552
	global_load_lds_dwordx4 v[190:191], off
	v_lshl_add_u64 v[192:193], v[198:199], 0, v[166:167]
	s_add_i32 m0, s63, 0x2000
	v_lshl_add_u64 v[196:197], v[198:199], 0, v[164:165]
	s_add_i32 s63, s64, s8
	global_load_lds_dwordx4 v[192:193], off
	v_lshl_add_u64 v[194:195], v[196:197], 0, v[2:3]
	s_mov_b32 m0, s63
	v_lshl_add_u64 v[196:197], v[196:197], 0, v[166:167]
	global_load_lds_dwordx4 v[194:195], off
	s_add_i32 m0, s63, 0x2000
	v_lshl_add_u64 v[198:199], v[188:189], 0, v[170:171]
	global_load_lds_dwordx4 v[196:197], off
	s_mov_b32 m0, s15
	v_lshl_add_u64 v[200:201], v[188:189], 0, v[168:169]
	global_load_lds_dwordx4 v[198:199], off
	s_mov_b32 m0, s33
	s_nop 0
	global_load_lds_dwordx4 v[200:201], off
	s_waitcnt vmcnt(8)
	s_waitcnt lgkmcnt(0)
	s_barrier
	s_setprio 1
	v_mfma_f32_16x16x128_f8f6f4 v[96:99], v[28:35], v[226:233], v[96:99]
	v_mfma_f32_16x16x128_f8f6f4 v[92:95], v[20:27], v[226:233], v[92:95]
	v_mfma_f32_16x16x128_f8f6f4 v[84:87], v[28:35], v[234:241], v[84:87]
	v_mfma_f32_16x16x128_f8f6f4 v[76:79], v[20:27], v[234:241], v[76:79]
	v_mfma_f32_16x16x128_f8f6f4 v[68:71], v[28:35], v[242:249], v[68:71]
	v_mfma_f32_16x16x128_f8f6f4 v[60:63], v[20:27], v[242:249], v[60:63]
	v_mfma_f32_16x16x128_f8f6f4 v[52:55], v[28:35], v[214:221], v[52:55]
	v_mfma_f32_16x16x128_f8f6f4 v[44:47], v[20:27], v[214:221], v[44:47]
	v_mfma_f32_16x16x128_f8f6f4 v[88:91], v[12:19], v[226:233], v[88:91]
	v_mfma_f32_16x16x128_f8f6f4 v[80:83], v[4:11], v[226:233], v[80:83]
	v_mfma_f32_16x16x128_f8f6f4 v[72:75], v[12:19], v[234:241], v[72:75]
	v_mfma_f32_16x16x128_f8f6f4 v[64:67], v[4:11], v[234:241], v[64:67]
	v_mfma_f32_16x16x128_f8f6f4 v[56:59], v[12:19], v[242:249], v[56:59]
	v_mfma_f32_16x16x128_f8f6f4 v[48:51], v[4:11], v[242:249], v[48:51]
	v_mfma_f32_16x16x128_f8f6f4 v[40:43], v[12:19], v[214:221], v[40:43]
	v_mfma_f32_16x16x128_f8f6f4 v[36:39], v[4:11], v[214:221], v[36:39]
	s_setprio 0
	s_barrier
; #define PG8_STAGE(bufoff, gbase, voff) do { _Pragma("unroll") for (int _i = 0; _i < 2; ++_i) \
;         __builtin_amdgcn_global_load_lds((const unsigned*)((const char*)(gbase) + (voff)[_i]), (LAS unsigned*)(lds + (bufoff) + ldsw + _i * 8192), 16, 0, 0); } while (0)
; #define PG8_LDA(dst, b, h) do { _Pragma("unroll") for (int m = 0; m < 4; ++m) _Pragma("unroll") for (int k = 0; k < 2; ++k) dst[m][k] = *(const LAS bf16x8*)(lds + PG8_SA(b, h) + aoff + m * 2048 + k * 1024); } while (0)
; #define PG8_LDB(dst, b, h) do { _Pragma("unroll") for (int n = 0; n < 2; ++n) _Pragma("unroll") for (int k = 0; k < 2; ++k) dst[n][k] = *(const LAS bf16x8*)(lds + PG8_SB(b, h) + boff + n * 2048 + k * 1024); } while (0)
; #define PG8_WAIT_V(n) asm volatile("s_waitcnt vmcnt(" #n ")" ::: "memory")
; #define PG8_WAIT_L(n) asm volatile("s_waitcnt lgkmcnt(" #n ")" ::: "memory")
; #define PG8_BAR __builtin_amdgcn_s_barrier()
; #define PG8_SCHED __builtin_amdgcn_sched_barrier(0)
;     ...
;             PG8_LDB(B0, 1, 0); PG8_LDB(B1, 1, 1); PG8_SCHED; PG8_LDA(At, 1, 0); PG8_STAGE(PG8_SA(0, 1), a2 + hstepA, voffA);
;             PG8_WAIT_V(8); PG8_WAIT_L(0); PG8_BAR; PG8_MMA(0, 0, At, B0); PG8_MMA(0, 1, At, B1); PG8_BAR; PG8_SCHED;
;             PG8_LDA(At, 1, 1); PG8_STAGE(PG8_SB(1, 0), b3, voffB); PG8_STAGE(PG8_SB(1, 1), b3 + hstepB, voffB); PG8_STAGE(PG8_SA(1, 0), a3, voffA);
;             PG8_WAIT_V(8); PG8_WAIT_L(0); PG8_BAR; PG8_MMA(1, 0, At, B0); PG8_MMA(1, 1, At, B1); PG8_BAR; PG8_SCHED;
	s_add_i32 s63, 0, 0x18000
	s_add_i32 s64, 0, 0x1c000
	ds_read_b128 v[4:7], v206
	ds_read_b128 v[8:11], v206 offset:1024
	ds_read_b128 v[12:15], v206 offset:2048
	ds_read_b128 v[16:19], v206 offset:3072
	ds_read_b128 v[20:23], v207
	ds_read_b128 v[24:27], v207 offset:1024
	ds_read_b128 v[28:31], v207 offset:2048
	ds_read_b128 v[32:35], v207 offset:3072
	ds_read_b128 v[214:217], v212 offset:32768
	ds_read_b128 v[218:221], v212 offset:33792
	ds_read_b128 v[226:229], v212 offset:34816
	ds_read_b128 v[230:233], v212 offset:35840
	ds_read_b128 v[234:237], v212 offset:36864
	ds_read_b128 v[238:241], v212 offset:37888
	ds_read_b128 v[242:245], v212 offset:38912
	ds_read_b128 v[246:249], v212 offset:39936
	v_lshl_add_u64 v[188:189], v[188:189], 0, v[0:1]
	s_mov_b32 m0, s44
	v_lshl_add_u64 v[202:203], v[188:189], 0, v[170:171]
	global_load_lds_dwordx4 v[202:203], off
	v_lshl_add_u64 v[188:189], v[188:189], 0, v[168:169]
	s_mov_b32 m0, s45
	s_nop 0
	global_load_lds_dwordx4 v[188:189], off
	s_waitcnt vmcnt(8)
	s_waitcnt lgkmcnt(0)
	s_barrier
	s_setprio 1
	v_mfma_f32_16x16x128_f8f6f4 v[160:163], v[4:11], v[214:221], v[160:163]
	v_mfma_f32_16x16x128_f8f6f4 v[156:159], v[12:19], v[214:221], v[156:159]
	v_mfma_f32_16x16x128_f8f6f4 v[148:151], v[4:11], v[226:233], v[148:151]
	v_mfma_f32_16x16x128_f8f6f4 v[140:143], v[12:19], v[226:233], v[140:143]
	v_mfma_f32_16x16x128_f8f6f4 v[132:135], v[4:11], v[234:241], v[132:135]
	v_mfma_f32_16x16x128_f8f6f4 v[124:127], v[12:19], v[234:241], v[124:127]
	v_mfma_f32_16x16x128_f8f6f4 v[116:119], v[4:11], v[242:249], v[116:119]
	v_mfma_f32_16x16x128_f8f6f4 v[108:111], v[12:19], v[242:249], v[108:111]
	v_mfma_f32_16x16x128_f8f6f4 v[152:155], v[20:27], v[214:221], v[152:155]
	v_mfma_f32_16x16x128_f8f6f4 v[144:147], v[28:35], v[214:221], v[144:147]
	v_mfma_f32_16x16x128_f8f6f4 v[136:139], v[20:27], v[226:233], v[136:139]
	v_mfma_f32_16x16x128_f8f6f4 v[128:131], v[28:35], v[226:233], v[128:131]
	v_mfma_f32_16x16x128_f8f6f4 v[120:123], v[20:27], v[234:241], v[120:123]
	v_mfma_f32_16x16x128_f8f6f4 v[112:115], v[28:35], v[234:241], v[112:115]
	v_mfma_f32_16x16x128_f8f6f4 v[104:107], v[20:27], v[242:249], v[104:107]
	v_mfma_f32_16x16x128_f8f6f4 v[100:103], v[28:35], v[242:249], v[100:103]
	s_setprio 0
	s_barrier
	s_add_i32 s63, s63, s8
	v_lshl_add_u64 v[188:189], v[190:191], 0, s[52:53]
	s_mov_b32 m0, s63
	ds_read_b128 v[214:217], v212 offset:49152
	ds_read_b128 v[218:221], v212 offset:50176
	ds_read_b128 v[226:229], v212 offset:51200
	ds_read_b128 v[230:233], v212 offset:52224
	ds_read_b128 v[234:237], v212 offset:53248
	ds_read_b128 v[238:241], v212 offset:54272
	ds_read_b128 v[242:245], v212 offset:55296
	ds_read_b128 v[246:249], v212 offset:56320
	global_load_lds_dwordx4 v[188:189], off
	v_lshl_add_u64 v[188:189], v[192:193], 0, s[52:53]
	s_add_i32 m0, s63, 0x2000
	s_add_i32 s63, s64, s8
	global_load_lds_dwordx4 v[188:189], off
	v_lshl_add_u64 v[188:189], v[194:195], 0, s[52:53]
	s_mov_b32 m0, s63
	s_nop 0
	global_load_lds_dwordx4 v[188:189], off
	v_lshl_add_u64 v[188:189], v[196:197], 0, s[52:53]
	s_add_i32 m0, s63, 0x2000
	s_nop 0
	global_load_lds_dwordx4 v[188:189], off
	v_lshl_add_u64 v[188:189], v[198:199], 0, s[52:53]
	s_mov_b32 m0, s46
	s_nop 0
	global_load_lds_dwordx4 v[188:189], off
	v_lshl_add_u64 v[188:189], v[200:201], 0, s[52:53]
	s_mov_b32 m0, s47
	s_nop 0
	global_load_lds_dwordx4 v[188:189], off
	s_waitcnt vmcnt(8)
	s_waitcnt lgkmcnt(0)
	s_barrier
	s_setprio 1
	v_mfma_f32_16x16x128_f8f6f4 v[96:99], v[4:11], v[214:221], v[96:99]
	v_mfma_f32_16x16x128_f8f6f4 v[92:95], v[12:19], v[214:221], v[92:95]
	v_mfma_f32_16x16x128_f8f6f4 v[84:87], v[4:11], v[226:233], v[84:87]
	v_mfma_f32_16x16x128_f8f6f4 v[76:79], v[12:19], v[226:233], v[76:79]
	v_mfma_f32_16x16x128_f8f6f4 v[68:71], v[4:11], v[234:241], v[68:71]
	v_mfma_f32_16x16x128_f8f6f4 v[60:63], v[12:19], v[234:241], v[60:63]
	v_mfma_f32_16x16x128_f8f6f4 v[52:55], v[4:11], v[242:249], v[52:55]
	v_mfma_f32_16x16x128_f8f6f4 v[44:47], v[12:19], v[242:249], v[44:47]
	v_mfma_f32_16x16x128_f8f6f4 v[88:91], v[20:27], v[214:221], v[88:91]
	v_mfma_f32_16x16x128_f8f6f4 v[80:83], v[28:35], v[214:221], v[80:83]
	v_mfma_f32_16x16x128_f8f6f4 v[72:75], v[20:27], v[226:233], v[72:75]
	v_mfma_f32_16x16x128_f8f6f4 v[64:67], v[28:35], v[226:233], v[64:67]
	v_mfma_f32_16x16x128_f8f6f4 v[56:59], v[20:27], v[234:241], v[56:59]
	v_mfma_f32_16x16x128_f8f6f4 v[48:51], v[28:35], v[234:241], v[48:51]
	v_mfma_f32_16x16x128_f8f6f4 v[40:43], v[20:27], v[242:249], v[40:43]
	v_mfma_f32_16x16x128_f8f6f4 v[36:39], v[28:35], v[242:249], v[36:39]
	s_setprio 0
	s_barrier
	s_add_i32 s62, s62, 2
	s_add_u32 s38, s38, 0x100
	s_addc_u32 s39, s39, 0
	s_cmp_gt_u32 s62, 5
	s_cbranch_scc0 .LBB0_440
	s_and_b64 vcc, exec, s[42:43]
	s_cbranch_vccz .LBB0_443
	s_barrier

; #define PG8_STAGE(bufoff, gbase, voff) do { _Pragma("unroll") for (int _i = 0; _i < 2; ++_i) \
;         __builtin_amdgcn_global_load_lds((const unsigned*)((const char*)(gbase) + (voff)[_i]), (LAS unsigned*)(lds + (bufoff) + ldsw + _i * 8192), 16, 0, 0); } while (0)
; #define PG8_LDA(dst, b, h) do { _Pragma("unroll") for (int m = 0; m < 4; ++m) _Pragma("unroll") for (int k = 0; k < 2; ++k) dst[m][k] = *(const LAS bf16x8*)(lds + PG8_SA(b, h) + aoff + m * 2048 + k * 1024); } while (0)
; #define PG8_LDB(dst, b, h) do { _Pragma("unroll") for (int n = 0; n < 2; ++n) _Pragma("unroll") for (int k = 0; k < 2; ++k) dst[n][k] = *(const LAS bf16x8*)(lds + PG8_SB(b, h) + boff + n * 2048 + k * 1024); } while (0)
; #define PG8_WAIT_V(n) asm volatile("s_waitcnt vmcnt(" #n ")" ::: "memory")
; #define PG8_WAIT_L(n) asm volatile("s_waitcnt lgkmcnt(" #n ")" ::: "memory")
; #define PG8_BAR __builtin_amdgcn_s_barrier()
; #define PG8_SCHED __builtin_amdgcn_sched_barrier(0)
;     ...
;             const char* a2 = last ? nA : cA + (size_t)(t + 2) * kstep; const char* b2 = last ? nB : cB + (size_t)(t + 2) * kstep;
;             const char* a3 = a2 + kstep; const char* b3 = b2 + kstep;
;             if constexpr (SP2) {
;             PG8_LDB(B0, 0, 0); PG8_LDB(B1, 0, 1); PG8_SCHED; PG8_LDA(At, 0, 0); PG8_STAGE(PG8_SA(1, 1), a1 + hstepA, voffA);
;             PG8_WAIT_V(8); PG8_WAIT_L(0); PG8_BAR; PG8_MMA(0, 0, At, B0); PG8_MMA(0, 1, At, B1); PG8_BAR; PG8_SCHED;
;             PG8_LDA(At, 0, 1); PG8_STAGE(PG8_SB(0, 0), b2, voffB); PG8_STAGE(PG8_SB(0, 1), b2 + hstepB, voffB); PG8_STAGE(PG8_SA(0, 0), a2, voffA);
.LBB0_783:
	s_add_i32 s39, 0, 0x10000
	s_add_i32 s75, 0, 0x14000
	ds_read_b128 v[160:163], v246
	ds_read_b128 v[164:167], v246 offset:1024
	ds_read_b128 v[168:171], v246 offset:2048
	ds_read_b128 v[172:175], v246 offset:3072
	ds_read_b128 v[176:179], v247
	ds_read_b128 v[180:183], v247 offset:1024
	ds_read_b128 v[184:187], v247 offset:2048
	ds_read_b128 v[188:191], v247 offset:3072
	ds_read_b128 v[192:195], v159
	ds_read_b128 v[196:199], v159 offset:1024
	ds_read_b128 v[200:203], v159 offset:2048
	ds_read_b128 v[204:207], v159 offset:3072
	ds_read_b128 v[210:213], v159 offset:4096
	ds_read_b128 v[214:217], v159 offset:5120
	ds_read_b128 v[218:221], v159 offset:6144
	ds_read_b128 v[226:229], v159 offset:7168
	s_cmpk_eq_i32 s28, 0xf00
	v_lshl_add_u64 v[230:231], v[148:149], 0, s[28:29]
	s_cselect_b64 vcc, -1, 0
	v_lshl_add_u64 v[230:231], v[230:231], 0, s[4:5]
	v_lshl_add_u64 v[232:233], v[154:155], 0, s[28:29]
	v_cndmask_b32_e32 v231, v231, v145, vcc
	v_cndmask_b32_e32 v230, v230, v144, vcc
	v_cndmask_b32_e32 v233, v233, v147, vcc
	v_cndmask_b32_e32 v232, v232, v146, vcc
	s_add_i32 m0, s33, 0xc000
	v_lshl_add_u64 v[234:235], v[152:153], 0, s[28:29]
	global_load_lds_dwordx4 v[234:235], off
	v_lshl_add_u64 v[234:235], v[150:151], 0, s[28:29]
	s_add_i32 m0, s33, 0xe000
	s_nop 0
	global_load_lds_dwordx4 v[234:235], off
	s_waitcnt vmcnt(8)
	s_waitcnt lgkmcnt(0)
	s_barrier
	s_setprio 1
	v_mfma_i32_16x16x64_i8 v[128:131], v[160:163], v[192:195], v[128:131]
	v_mfma_i32_16x16x64_i8 v[124:127], v[168:171], v[192:195], v[124:127]
	v_mfma_i32_16x16x64_i8 v[112:115], v[160:163], v[200:203], v[112:115]
	v_mfma_i32_16x16x64_i8 v[108:111], v[168:171], v[200:203], v[108:111]
	v_mfma_i32_16x16x64_i8 v[96:99], v[160:163], v[210:213], v[96:99]
	v_mfma_i32_16x16x64_i8 v[92:95], v[168:171], v[210:213], v[92:95]
	v_mfma_i32_16x16x64_i8 v[80:83], v[160:163], v[218:221], v[80:83]
	v_mfma_i32_16x16x64_i8 v[76:79], v[168:171], v[218:221], v[76:79]
	v_mfma_i32_16x16x64_i8 v[128:131], v[164:167], v[196:199], v[128:131]
	v_mfma_i32_16x16x64_i8 v[124:127], v[172:175], v[196:199], v[124:127]
	v_mfma_i32_16x16x64_i8 v[112:115], v[164:167], v[204:207], v[112:115]
	v_mfma_i32_16x16x64_i8 v[108:111], v[172:175], v[204:207], v[108:111]
	v_mfma_i32_16x16x64_i8 v[96:99], v[164:167], v[214:217], v[96:99]
	v_mfma_i32_16x16x64_i8 v[92:95], v[172:175], v[214:217], v[92:95]
	v_mfma_i32_16x16x64_i8 v[80:83], v[164:167], v[226:229], v[80:83]
	v_mfma_i32_16x16x64_i8 v[76:79], v[172:175], v[226:229], v[76:79]
	v_mfma_i32_16x16x64_i8 v[120:123], v[176:179], v[192:195], v[120:123]
	v_mfma_i32_16x16x64_i8 v[116:119], v[184:187], v[192:195], v[116:119]
	v_mfma_i32_16x16x64_i8 v[104:107], v[176:179], v[200:203], v[104:107]
	v_mfma_i32_16x16x64_i8 v[100:103], v[184:187], v[200:203], v[100:103]
	v_mfma_i32_16x16x64_i8 v[88:91], v[176:179], v[210:213], v[88:91]
	v_mfma_i32_16x16x64_i8 v[84:87], v[184:187], v[210:213], v[84:87]
	v_mfma_i32_16x16x64_i8 v[72:75], v[176:179], v[218:221], v[72:75]
	v_mfma_i32_16x16x64_i8 v[68:71], v[184:187], v[218:221], v[68:71]
	v_mfma_i32_16x16x64_i8 v[120:123], v[180:183], v[196:199], v[120:123]
	v_mfma_i32_16x16x64_i8 v[116:119], v[188:191], v[196:199], v[116:119]
	v_mfma_i32_16x16x64_i8 v[104:107], v[180:183], v[204:207], v[104:107]
	v_mfma_i32_16x16x64_i8 v[100:103], v[188:191], v[204:207], v[100:103]
	v_mfma_i32_16x16x64_i8 v[88:91], v[180:183], v[214:217], v[88:91]
	v_mfma_i32_16x16x64_i8 v[84:87], v[188:191], v[214:217], v[84:87]
	v_mfma_i32_16x16x64_i8 v[72:75], v[180:183], v[226:229], v[72:75]
	v_mfma_i32_16x16x64_i8 v[68:71], v[188:191], v[226:229], v[68:71]
	s_setprio 0
	s_barrier
	s_add_i32 s39, s39, s15
	v_lshl_add_u64 v[234:235], v[232:233], 0, v[2:3]
	s_mov_b32 m0, s39
	ds_read_b128 v[192:195], v159 offset:16384
	ds_read_b128 v[196:199], v159 offset:17408
	ds_read_b128 v[200:203], v159 offset:18432
	ds_read_b128 v[204:207], v159 offset:19456
	ds_read_b128 v[210:213], v159 offset:20480
	ds_read_b128 v[214:217], v159 offset:21504
	ds_read_b128 v[218:221], v159 offset:22528
	ds_read_b128 v[226:229], v159 offset:23552
	global_load_lds_dwordx4 v[234:235], off
	v_lshl_add_u64 v[236:237], v[232:233], 0, v[134:135]
	s_add_i32 m0, s39, 0x2000
	v_lshl_add_u64 v[232:233], v[232:233], 0, v[138:139]
	s_add_i32 s39, s75, s15
	global_load_lds_dwordx4 v[236:237], off
	v_lshl_add_u64 v[238:239], v[232:233], 0, v[2:3]
	s_mov_b32 m0, s39
	v_lshl_add_u64 v[232:233], v[232:233], 0, v[134:135]
	global_load_lds_dwordx4 v[238:239], off
	s_add_i32 m0, s39, 0x2000
	v_lshl_add_u64 v[240:241], v[230:231], 0, v[0:1]
	global_load_lds_dwordx4 v[232:233], off
	s_mov_b32 m0, s33
	v_lshl_add_u64 v[242:243], v[230:231], 0, v[132:133]
	global_load_lds_dwordx4 v[240:241], off
	s_mov_b32 m0, s57
	s_nop 0
	global_load_lds_dwordx4 v[242:243], off
	s_waitcnt vmcnt(8)
	s_waitcnt lgkmcnt(0)
	s_barrier
; #define PG8_STAGE(bufoff, gbase, voff) do { _Pragma("unroll") for (int _i = 0; _i < 2; ++_i) \
;         __builtin_amdgcn_global_load_lds((const unsigned*)((const char*)(gbase) + (voff)[_i]), (LAS unsigned*)(lds + (bufoff) + ldsw + _i * 8192), 16, 0, 0); } while (0)
; #define PG8_LDA(dst, b, h) do { _Pragma("unroll") for (int m = 0; m < 4; ++m) _Pragma("unroll") for (int k = 0; k < 2; ++k) dst[m][k] = *(const LAS bf16x8*)(lds + PG8_SA(b, h) + aoff + m * 2048 + k * 1024); } while (0)
; #define PG8_LDB(dst, b, h) do { _Pragma("unroll") for (int n = 0; n < 2; ++n) _Pragma("unroll") for (int k = 0; k < 2; ++k) dst[n][k] = *(const LAS bf16x8*)(lds + PG8_SB(b, h) + boff + n * 2048 + k * 1024); } while (0)
; #define PG8_WAIT_V(n) asm volatile("s_waitcnt vmcnt(" #n ")" ::: "memory")
; #define PG8_WAIT_L(n) asm volatile("s_waitcnt lgkmcnt(" #n ")" ::: "memory")
; #define PG8_BAR __builtin_amdgcn_s_barrier()
; #define PG8_SCHED __builtin_amdgcn_sched_barrier(0)
;     ...
;             PG8_WAIT_V(8); PG8_WAIT_L(0); PG8_BAR; PG8_MMA(1, 0, At, B0); PG8_MMA(1, 1, At, B1); PG8_BAR; PG8_SCHED;
;             PG8_LDB(B0, 1, 0); PG8_LDB(B1, 1, 1); PG8_SCHED; PG8_LDA(At, 1, 0); PG8_STAGE(PG8_SA(0, 1), a2 + hstepA, voffA);
;             PG8_WAIT_V(8); PG8_WAIT_L(0); PG8_BAR; PG8_MMA(0, 0, At, B0); PG8_MMA(0, 1, At, B1); PG8_BAR; PG8_SCHED;
	s_setprio 1
	v_mfma_i32_16x16x64_i8 v[64:67], v[160:163], v[192:195], v[64:67]
	v_mfma_i32_16x16x64_i8 v[60:63], v[168:171], v[192:195], v[60:63]
	v_mfma_i32_16x16x64_i8 v[48:51], v[160:163], v[200:203], v[48:51]
	v_mfma_i32_16x16x64_i8 v[44:47], v[168:171], v[200:203], v[44:47]
	v_mfma_i32_16x16x64_i8 v[32:35], v[160:163], v[210:213], v[32:35]
	v_mfma_i32_16x16x64_i8 v[28:31], v[168:171], v[210:213], v[28:31]
	v_mfma_i32_16x16x64_i8 v[16:19], v[160:163], v[218:221], v[16:19]
	v_mfma_i32_16x16x64_i8 v[12:15], v[168:171], v[218:221], v[12:15]
	v_mfma_i32_16x16x64_i8 v[64:67], v[164:167], v[196:199], v[64:67]
	v_mfma_i32_16x16x64_i8 v[60:63], v[172:175], v[196:199], v[60:63]
	v_mfma_i32_16x16x64_i8 v[48:51], v[164:167], v[204:207], v[48:51]
	v_mfma_i32_16x16x64_i8 v[44:47], v[172:175], v[204:207], v[44:47]
	v_mfma_i32_16x16x64_i8 v[32:35], v[164:167], v[214:217], v[32:35]
	v_mfma_i32_16x16x64_i8 v[28:31], v[172:175], v[214:217], v[28:31]
	v_mfma_i32_16x16x64_i8 v[16:19], v[164:167], v[226:229], v[16:19]
	v_mfma_i32_16x16x64_i8 v[12:15], v[172:175], v[226:229], v[12:15]
	v_mfma_i32_16x16x64_i8 v[56:59], v[176:179], v[192:195], v[56:59]
	v_mfma_i32_16x16x64_i8 v[52:55], v[184:187], v[192:195], v[52:55]
	v_mfma_i32_16x16x64_i8 v[40:43], v[176:179], v[200:203], v[40:43]
	v_mfma_i32_16x16x64_i8 v[36:39], v[184:187], v[200:203], v[36:39]
	v_mfma_i32_16x16x64_i8 v[24:27], v[176:179], v[210:213], v[24:27]
	v_mfma_i32_16x16x64_i8 v[20:23], v[184:187], v[210:213], v[20:23]
	v_mfma_i32_16x16x64_i8 v[8:11], v[176:179], v[218:221], v[8:11]
	v_mfma_i32_16x16x64_i8 v[4:7], v[184:187], v[218:221], v[4:7]
	v_mfma_i32_16x16x64_i8 v[56:59], v[180:183], v[196:199], v[56:59]
	v_mfma_i32_16x16x64_i8 v[52:55], v[188:191], v[196:199], v[52:55]
	v_mfma_i32_16x16x64_i8 v[40:43], v[180:183], v[204:207], v[40:43]
	v_mfma_i32_16x16x64_i8 v[36:39], v[188:191], v[204:207], v[36:39]
	v_mfma_i32_16x16x64_i8 v[24:27], v[180:183], v[214:217], v[24:27]
	v_mfma_i32_16x16x64_i8 v[20:23], v[188:191], v[214:217], v[20:23]
	v_mfma_i32_16x16x64_i8 v[8:11], v[180:183], v[226:229], v[8:11]
	v_mfma_i32_16x16x64_i8 v[4:7], v[188:191], v[226:229], v[4:7]
	s_setprio 0
	s_barrier
	s_add_i32 s39, 0, 0x18000
	s_add_i32 s75, 0, 0x1c000
	ds_read_b128 v[160:163], v248
	ds_read_b128 v[164:167], v248 offset:1024
	ds_read_b128 v[168:171], v248 offset:2048
	ds_read_b128 v[172:175], v248 offset:3072
	ds_read_b128 v[176:179], v249
	ds_read_b128 v[180:183], v249 offset:1024
	ds_read_b128 v[184:187], v249 offset:2048
	ds_read_b128 v[188:191], v249 offset:3072
	ds_read_b128 v[192:195], v159 offset:32768
	ds_read_b128 v[196:199], v159 offset:33792
	ds_read_b128 v[200:203], v159 offset:34816
	ds_read_b128 v[204:207], v159 offset:35840
	ds_read_b128 v[210:213], v159 offset:36864
	ds_read_b128 v[214:217], v159 offset:37888
	ds_read_b128 v[218:221], v159 offset:38912
	ds_read_b128 v[226:229], v159 offset:39936
	v_lshl_add_u64 v[230:231], v[230:231], 0, v[136:137]
	s_mov_b32 m0, s62
	v_lshl_add_u64 v[244:245], v[230:231], 0, v[0:1]
	global_load_lds_dwordx4 v[244:245], off
	v_lshl_add_u64 v[230:231], v[230:231], 0, v[132:133]
	s_mov_b32 m0, s63
	s_nop 0
	global_load_lds_dwordx4 v[230:231], off
	s_waitcnt vmcnt(8)
	s_waitcnt lgkmcnt(0)
	s_barrier
	s_setprio 1
	v_mfma_i32_16x16x64_i8 v[128:131], v[160:163], v[192:195], v[128:131]
	v_mfma_i32_16x16x64_i8 v[124:127], v[168:171], v[192:195], v[124:127]
	v_mfma_i32_16x16x64_i8 v[112:115], v[160:163], v[200:203], v[112:115]
	v_mfma_i32_16x16x64_i8 v[108:111], v[168:171], v[200:203], v[108:111]
	v_mfma_i32_16x16x64_i8 v[96:99], v[160:163], v[210:213], v[96:99]
	v_mfma_i32_16x16x64_i8 v[92:95], v[168:171], v[210:213], v[92:95]
	v_mfma_i32_16x16x64_i8 v[80:83], v[160:163], v[218:221], v[80:83]
	v_mfma_i32_16x16x64_i8 v[76:79], v[168:171], v[218:221], v[76:79]
	v_mfma_i32_16x16x64_i8 v[128:131], v[164:167], v[196:199], v[128:131]
	v_mfma_i32_16x16x64_i8 v[124:127], v[172:175], v[196:199], v[124:127]
	v_mfma_i32_16x16x64_i8 v[112:115], v[164:167], v[204:207], v[112:115]
	v_mfma_i32_16x16x64_i8 v[108:111], v[172:175], v[204:207], v[108:111]
	v_mfma_i32_16x16x64_i8 v[96:99], v[164:167], v[214:217], v[96:99]
	v_mfma_i32_16x16x64_i8 v[92:95], v[172:175], v[214:217], v[92:95]
	v_mfma_i32_16x16x64_i8 v[80:83], v[164:167], v[226:229], v[80:83]
	v_mfma_i32_16x16x64_i8 v[76:79], v[172:175], v[226:229], v[76:79]
	v_mfma_i32_16x16x64_i8 v[120:123], v[176:179], v[192:195], v[120:123]
	v_mfma_i32_16x16x64_i8 v[116:119], v[184:187], v[192:195], v[116:119]
	v_mfma_i32_16x16x64_i8 v[104:107], v[176:179], v[200:203], v[104:107]
	v_mfma_i32_16x16x64_i8 v[100:103], v[184:187], v[200:203], v[100:103]
	v_mfma_i32_16x16x64_i8 v[88:91], v[176:179], v[210:213], v[88:91]
	v_mfma_i32_16x16x64_i8 v[84:87], v[184:187], v[210:213], v[84:87]
	v_mfma_i32_16x16x64_i8 v[72:75], v[176:179], v[218:221], v[72:75]
	v_mfma_i32_16x16x64_i8 v[68:71], v[184:187], v[218:221], v[68:71]
	v_mfma_i32_16x16x64_i8 v[120:123], v[180:183], v[196:199], v[120:123]
	v_mfma_i32_16x16x64_i8 v[116:119], v[188:191], v[196:199], v[116:119]
	v_mfma_i32_16x16x64_i8 v[104:107], v[180:183], v[204:207], v[104:107]
	v_mfma_i32_16x16x64_i8 v[100:103], v[188:191], v[204:207], v[100:103]
	v_mfma_i32_16x16x64_i8 v[88:91], v[180:183], v[214:217], v[88:91]
	v_mfma_i32_16x16x64_i8 v[84:87], v[188:191], v[214:217], v[84:87]
	v_mfma_i32_16x16x64_i8 v[72:75], v[180:183], v[226:229], v[72:75]
	v_mfma_i32_16x16x64_i8 v[68:71], v[188:191], v[226:229], v[68:71]
	s_setprio 0
	s_barrier
; #define PG8_STAGE(bufoff, gbase, voff) do { _Pragma("unroll") for (int _i = 0; _i < 2; ++_i) \
;         __builtin_amdgcn_global_load_lds((const unsigned*)((const char*)(gbase) + (voff)[_i]), (LAS unsigned*)(lds + (bufoff) + ldsw + _i * 8192), 16, 0, 0); } while (0)
; #define PG8_LDA(dst, b, h) do { _Pragma("unroll") for (int m = 0; m < 4; ++m) _Pragma("unroll") for (int k = 0; k < 2; ++k) dst[m][k] = *(const LAS bf16x8*)(lds + PG8_SA(b, h) + aoff + m * 2048 + k * 1024); } while (0)
; #define PG8_WAIT_V(n) asm volatile("s_waitcnt vmcnt(" #n ")" ::: "memory")
; #define PG8_WAIT_L(n) asm volatile("s_waitcnt lgkmcnt(" #n ")" ::: "memory")
; #define PG8_BAR __builtin_amdgcn_s_barrier()
; #define PG8_SCHED __builtin_amdgcn_sched_barrier(0)
;     ...
;             PG8_LDA(At, 1, 1); PG8_STAGE(PG8_SB(1, 0), b3, voffB); PG8_STAGE(PG8_SB(1, 1), b3 + hstepB, voffB); PG8_STAGE(PG8_SA(1, 0), a3, voffA);
;             PG8_WAIT_V(8); PG8_WAIT_L(0); PG8_BAR; PG8_MMA(1, 0, At, B0); PG8_MMA(1, 1, At, B1); PG8_BAR; PG8_SCHED;
	s_add_i32 s39, s39, s15
	v_lshl_add_u64 v[230:231], v[234:235], 0, s[52:53]
	s_mov_b32 m0, s39
	ds_read_b128 v[192:195], v159 offset:49152
	ds_read_b128 v[196:199], v159 offset:50176
	ds_read_b128 v[200:203], v159 offset:51200
	ds_read_b128 v[204:207], v159 offset:52224
	ds_read_b128 v[210:213], v159 offset:53248
	ds_read_b128 v[214:217], v159 offset:54272
	ds_read_b128 v[218:221], v159 offset:55296
	ds_read_b128 v[226:229], v159 offset:56320
	global_load_lds_dwordx4 v[230:231], off
	v_lshl_add_u64 v[230:231], v[236:237], 0, s[52:53]
	s_add_i32 m0, s39, 0x2000
	s_add_i32 s39, s75, s15
	global_load_lds_dwordx4 v[230:231], off
	v_lshl_add_u64 v[230:231], v[238:239], 0, s[52:53]
	s_mov_b32 m0, s39
	s_nop 0
	global_load_lds_dwordx4 v[230:231], off
	v_lshl_add_u64 v[230:231], v[232:233], 0, s[52:53]
	s_add_i32 m0, s39, 0x2000
	s_nop 0
	global_load_lds_dwordx4 v[230:231], off
	v_lshl_add_u64 v[230:231], v[240:241], 0, s[52:53]
	s_mov_b32 m0, s64
	s_nop 0
	global_load_lds_dwordx4 v[230:231], off
	v_lshl_add_u64 v[230:231], v[242:243], 0, s[52:53]
	s_mov_b32 m0, s65
	s_nop 0
	global_load_lds_dwordx4 v[230:231], off
	s_waitcnt vmcnt(8)
	s_waitcnt lgkmcnt(0)
	s_barrier
	s_setprio 1
	v_mfma_i32_16x16x64_i8 v[64:67], v[160:163], v[192:195], v[64:67]
	v_mfma_i32_16x16x64_i8 v[60:63], v[168:171], v[192:195], v[60:63]
	v_mfma_i32_16x16x64_i8 v[48:51], v[160:163], v[200:203], v[48:51]
	v_mfma_i32_16x16x64_i8 v[44:47], v[168:171], v[200:203], v[44:47]
	v_mfma_i32_16x16x64_i8 v[32:35], v[160:163], v[210:213], v[32:35]
	v_mfma_i32_16x16x64_i8 v[28:31], v[168:171], v[210:213], v[28:31]
	v_mfma_i32_16x16x64_i8 v[16:19], v[160:163], v[218:221], v[16:19]
	v_mfma_i32_16x16x64_i8 v[12:15], v[168:171], v[218:221], v[12:15]
	v_mfma_i32_16x16x64_i8 v[64:67], v[164:167], v[196:199], v[64:67]
	v_mfma_i32_16x16x64_i8 v[60:63], v[172:175], v[196:199], v[60:63]
	v_mfma_i32_16x16x64_i8 v[48:51], v[164:167], v[204:207], v[48:51]
	v_mfma_i32_16x16x64_i8 v[44:47], v[172:175], v[204:207], v[44:47]
	v_mfma_i32_16x16x64_i8 v[32:35], v[164:167], v[214:217], v[32:35]
	v_mfma_i32_16x16x64_i8 v[28:31], v[172:175], v[214:217], v[28:31]
	v_mfma_i32_16x16x64_i8 v[16:19], v[164:167], v[226:229], v[16:19]
	v_mfma_i32_16x16x64_i8 v[12:15], v[172:175], v[226:229], v[12:15]
	v_mfma_i32_16x16x64_i8 v[56:59], v[176:179], v[192:195], v[56:59]
	v_mfma_i32_16x16x64_i8 v[52:55], v[184:187], v[192:195], v[52:55]
	v_mfma_i32_16x16x64_i8 v[40:43], v[176:179], v[200:203], v[40:43]
	v_mfma_i32_16x16x64_i8 v[36:39], v[184:187], v[200:203], v[36:39]
	v_mfma_i32_16x16x64_i8 v[24:27], v[176:179], v[210:213], v[24:27]
	v_mfma_i32_16x16x64_i8 v[20:23], v[184:187], v[210:213], v[20:23]
	v_mfma_i32_16x16x64_i8 v[8:11], v[176:179], v[218:221], v[8:11]
	v_mfma_i32_16x16x64_i8 v[4:7], v[184:187], v[218:221], v[4:7]
	v_mfma_i32_16x16x64_i8 v[56:59], v[180:183], v[196:199], v[56:59]
	v_mfma_i32_16x16x64_i8 v[52:55], v[188:191], v[196:199], v[52:55]
	v_mfma_i32_16x16x64_i8 v[40:43], v[180:183], v[204:207], v[40:43]
	v_mfma_i32_16x16x64_i8 v[36:39], v[188:191], v[204:207], v[36:39]
	v_mfma_i32_16x16x64_i8 v[24:27], v[180:183], v[214:217], v[24:27]
	v_mfma_i32_16x16x64_i8 v[20:23], v[188:191], v[214:217], v[20:23]
	v_mfma_i32_16x16x64_i8 v[8:11], v[180:183], v[226:229], v[8:11]
	v_mfma_i32_16x16x64_i8 v[4:7], v[188:191], v[226:229], v[4:7]
	s_setprio 0
	s_barrier
	s_add_i32 s38, s38, 2
	s_add_u32 s28, s28, 0x100
	s_addc_u32 s29, s29, 0
	s_cmp_gt_u32 s38, 29
	s_cbranch_scc0 .LBB0_783
	s_and_b64 vcc, exec, s[60:61]
	s_cbranch_vccz .LBB0_786
	s_barrier

; #define PG8_STAGE(bufoff, gbase, voff) do { _Pragma("unroll") for (int _i = 0; _i < 2; ++_i) \
;         __builtin_amdgcn_global_load_lds((const unsigned*)((const char*)(gbase) + (voff)[_i]), (LAS unsigned*)(lds + (bufoff) + ldsw + _i * 8192), 16, 0, 0); } while (0)
; #define PG8_LDA(dst, b, h) do { _Pragma("unroll") for (int m = 0; m < 4; ++m) _Pragma("unroll") for (int k = 0; k < 2; ++k) dst[m][k] = *(const LAS bf16x8*)(lds + PG8_SA(b, h) + aoff + m * 2048 + k * 1024); } while (0)
; #define PG8_LDB(dst, b, h) do { _Pragma("unroll") for (int n = 0; n < 2; ++n) _Pragma("unroll") for (int k = 0; k < 2; ++k) dst[n][k] = *(const LAS bf16x8*)(lds + PG8_SB(b, h) + boff + n * 2048 + k * 1024); } while (0)
; #define PG8_WAIT_V(n) asm volatile("s_waitcnt vmcnt(" #n ")" ::: "memory")
; #define PG8_WAIT_L(n) asm volatile("s_waitcnt lgkmcnt(" #n ")" ::: "memory")
; #define PG8_BAR __builtin_amdgcn_s_barrier()
; #define PG8_SCHED __builtin_amdgcn_sched_barrier(0)
;     ...
;             const char* a2 = last ? nA : cA + (size_t)(t + 2) * kstep; const char* b2 = last ? nB : cB + (size_t)(t + 2) * kstep;
;             const char* a3 = a2 + kstep; const char* b3 = b2 + kstep;
;             if constexpr (SP2) {
;             PG8_LDB(B0, 0, 0); PG8_LDB(B1, 0, 1); PG8_SCHED; PG8_LDA(At, 0, 0); PG8_STAGE(PG8_SA(1, 1), a1 + hstepA, voffA);
;             PG8_WAIT_V(8); PG8_WAIT_L(0); PG8_BAR; PG8_MMA(0, 0, At, B0); PG8_MMA(0, 1, At, B1); PG8_BAR; PG8_SCHED;
;             PG8_LDA(At, 0, 1); PG8_STAGE(PG8_SB(0, 0), b2, voffB); PG8_STAGE(PG8_SB(0, 1), b2 + hstepB, voffB); PG8_STAGE(PG8_SA(0, 0), a2, voffA);
;             PG8_WAIT_V(8); PG8_WAIT_L(0); PG8_BAR; PG8_MMA(1, 0, At, B0); PG8_MMA(1, 1, At, B1); PG8_BAR; PG8_SCHED;
.LBB0_818:
	s_add_i32 s43, 0, 0x10000
	s_add_i32 s75, 0, 0x14000
	ds_read_b128 v[28:31], v213
	ds_read_b128 v[32:35], v213 offset:1024
	ds_read_b128 v[20:23], v213 offset:2048
	ds_read_b128 v[24:27], v213 offset:3072
	ds_read_b128 v[12:15], v250
	ds_read_b128 v[16:19], v250 offset:1024
	ds_read_b128 v[4:7], v250 offset:2048
	ds_read_b128 v[8:11], v250 offset:3072
	ds_read_b128 v[190:193], v212
	ds_read_b128 v[194:197], v212 offset:1024
	ds_read_b128 v[198:201], v212 offset:2048
	ds_read_b128 v[202:205], v212 offset:3072
	ds_read_b128 v[214:217], v212 offset:4096
	ds_read_b128 v[218:221], v212 offset:5120
	ds_read_b128 v[226:229], v212 offset:6144
	ds_read_b128 v[230:233], v212 offset:7168
	v_lshl_add_u64 v[188:189], v[180:181], 0, s[28:29]
	s_cmpk_eq_i32 s28, 0xf00
	v_lshl_add_u64 v[188:189], v[188:189], 0, s[4:5]
	s_cselect_b64 vcc, -1, 0
	v_lshl_add_u64 v[206:207], v[186:187], 0, s[28:29]
	v_cndmask_b32_e32 v188, v188, v176, vcc
	v_cndmask_b32_e32 v189, v189, v177, vcc
	v_cndmask_b32_e32 v207, v207, v179, vcc
	v_cndmask_b32_e32 v206, v206, v178, vcc
	s_add_i32 m0, s57, 0xc000
	v_lshl_add_u64 v[234:235], v[184:185], 0, s[28:29]
	global_load_lds_dwordx4 v[234:235], off
	v_lshl_add_u64 v[234:235], v[182:183], 0, s[28:29]
	s_add_i32 m0, s57, 0xe000
	s_nop 0
	global_load_lds_dwordx4 v[234:235], off
	s_waitcnt vmcnt(8)
	s_waitcnt lgkmcnt(0)
	s_barrier
	s_setprio 1
	v_mfma_f32_16x16x128_f8f6f4 v[160:163], v[28:35], v[190:197], v[160:163]
	v_mfma_f32_16x16x128_f8f6f4 v[156:159], v[20:27], v[190:197], v[156:159]
	v_mfma_f32_16x16x128_f8f6f4 v[144:147], v[28:35], v[198:205], v[144:147]
	v_mfma_f32_16x16x128_f8f6f4 v[140:143], v[20:27], v[198:205], v[140:143]
	v_mfma_f32_16x16x128_f8f6f4 v[128:131], v[28:35], v[214:221], v[128:131]
	v_mfma_f32_16x16x128_f8f6f4 v[124:127], v[20:27], v[214:221], v[124:127]
	v_mfma_f32_16x16x128_f8f6f4 v[112:115], v[28:35], v[226:233], v[112:115]
	v_mfma_f32_16x16x128_f8f6f4 v[108:111], v[20:27], v[226:233], v[108:111]
	v_mfma_f32_16x16x128_f8f6f4 v[152:155], v[12:19], v[190:197], v[152:155]
	v_mfma_f32_16x16x128_f8f6f4 v[148:151], v[4:11], v[190:197], v[148:151]
	v_mfma_f32_16x16x128_f8f6f4 v[136:139], v[12:19], v[198:205], v[136:139]
	v_mfma_f32_16x16x128_f8f6f4 v[132:135], v[4:11], v[198:205], v[132:135]
	v_mfma_f32_16x16x128_f8f6f4 v[120:123], v[12:19], v[214:221], v[120:123]
	v_mfma_f32_16x16x128_f8f6f4 v[116:119], v[4:11], v[214:221], v[116:119]
	v_mfma_f32_16x16x128_f8f6f4 v[104:107], v[12:19], v[226:233], v[104:107]
	v_mfma_f32_16x16x128_f8f6f4 v[100:103], v[4:11], v[226:233], v[100:103]
	s_setprio 0
	s_barrier
	s_add_i32 s43, s43, s33
	v_lshl_add_u64 v[190:191], v[206:207], 0, v[2:3]
	s_mov_b32 m0, s43
	ds_read_b128 v[214:217], v212 offset:16384
	ds_read_b128 v[218:221], v212 offset:17408
	ds_read_b128 v[226:229], v212 offset:18432
	ds_read_b128 v[230:233], v212 offset:19456
	ds_read_b128 v[234:237], v212 offset:20480
	ds_read_b128 v[238:241], v212 offset:21504
	ds_read_b128 v[242:245], v212 offset:22528
	ds_read_b128 v[246:249], v212 offset:23552
	global_load_lds_dwordx4 v[190:191], off
	v_lshl_add_u64 v[192:193], v[206:207], 0, v[166:167]
	s_add_i32 m0, s43, 0x2000
	v_lshl_add_u64 v[196:197], v[206:207], 0, v[170:171]
	s_add_i32 s43, s75, s33
	global_load_lds_dwordx4 v[192:193], off
	v_lshl_add_u64 v[194:195], v[196:197], 0, v[2:3]
	s_mov_b32 m0, s43
	v_lshl_add_u64 v[196:197], v[196:197], 0, v[166:167]
	global_load_lds_dwordx4 v[194:195], off
	s_add_i32 m0, s43, 0x2000
	v_lshl_add_u64 v[198:199], v[188:189], 0, v[0:1]
	global_load_lds_dwordx4 v[196:197], off
	s_mov_b32 m0, s57
	v_lshl_add_u64 v[200:201], v[188:189], 0, v[164:165]
	global_load_lds_dwordx4 v[198:199], off
	s_mov_b32 m0, s62
	s_nop 0
	global_load_lds_dwordx4 v[200:201], off
	s_waitcnt vmcnt(8)
	s_waitcnt lgkmcnt(0)
	s_barrier
	s_setprio 1
	v_mfma_f32_16x16x128_f8f6f4 v[96:99], v[28:35], v[214:221], v[96:99]
	v_mfma_f32_16x16x128_f8f6f4 v[92:95], v[20:27], v[214:221], v[92:95]
	v_mfma_f32_16x16x128_f8f6f4 v[80:83], v[28:35], v[226:233], v[80:83]
	v_mfma_f32_16x16x128_f8f6f4 v[76:79], v[20:27], v[226:233], v[76:79]
	v_mfma_f32_16x16x128_f8f6f4 v[64:67], v[28:35], v[234:241], v[64:67]
	v_mfma_f32_16x16x128_f8f6f4 v[60:63], v[20:27], v[234:241], v[60:63]
	v_mfma_f32_16x16x128_f8f6f4 v[48:51], v[28:35], v[242:249], v[48:51]
	v_mfma_f32_16x16x128_f8f6f4 v[44:47], v[20:27], v[242:249], v[44:47]
	v_mfma_f32_16x16x128_f8f6f4 v[88:91], v[12:19], v[214:221], v[88:91]
	v_mfma_f32_16x16x128_f8f6f4 v[84:87], v[4:11], v[214:221], v[84:87]
	v_mfma_f32_16x16x128_f8f6f4 v[72:75], v[12:19], v[226:233], v[72:75]
	v_mfma_f32_16x16x128_f8f6f4 v[68:71], v[4:11], v[226:233], v[68:71]
	v_mfma_f32_16x16x128_f8f6f4 v[56:59], v[12:19], v[234:241], v[56:59]
	v_mfma_f32_16x16x128_f8f6f4 v[52:55], v[4:11], v[234:241], v[52:55]
	v_mfma_f32_16x16x128_f8f6f4 v[40:43], v[12:19], v[242:249], v[40:43]
	v_mfma_f32_16x16x128_f8f6f4 v[36:39], v[4:11], v[242:249], v[36:39]
	s_setprio 0
	s_barrier
; #define PG8_STAGE(bufoff, gbase, voff) do { _Pragma("unroll") for (int _i = 0; _i < 2; ++_i) \
;         __builtin_amdgcn_global_load_lds((const unsigned*)((const char*)(gbase) + (voff)[_i]), (LAS unsigned*)(lds + (bufoff) + ldsw + _i * 8192), 16, 0, 0); } while (0)
; #define PG8_LDA(dst, b, h) do { _Pragma("unroll") for (int m = 0; m < 4; ++m) _Pragma("unroll") for (int k = 0; k < 2; ++k) dst[m][k] = *(const LAS bf16x8*)(lds + PG8_SA(b, h) + aoff + m * 2048 + k * 1024); } while (0)
; #define PG8_LDB(dst, b, h) do { _Pragma("unroll") for (int n = 0; n < 2; ++n) _Pragma("unroll") for (int k = 0; k < 2; ++k) dst[n][k] = *(const LAS bf16x8*)(lds + PG8_SB(b, h) + boff + n * 2048 + k * 1024); } while (0)
; #define PG8_WAIT_V(n) asm volatile("s_waitcnt vmcnt(" #n ")" ::: "memory")
; #define PG8_WAIT_L(n) asm volatile("s_waitcnt lgkmcnt(" #n ")" ::: "memory")
; #define PG8_BAR __builtin_amdgcn_s_barrier()
; #define PG8_SCHED __builtin_amdgcn_sched_barrier(0)
;     ...
;             PG8_LDB(B0, 1, 0); PG8_LDB(B1, 1, 1); PG8_SCHED; PG8_LDA(At, 1, 0); PG8_STAGE(PG8_SA(0, 1), a2 + hstepA, voffA);
;             PG8_WAIT_V(8); PG8_WAIT_L(0); PG8_BAR; PG8_MMA(0, 0, At, B0); PG8_MMA(0, 1, At, B1); PG8_BAR; PG8_SCHED;
;             PG8_LDA(At, 1, 1); PG8_STAGE(PG8_SB(1, 0), b3, voffB); PG8_STAGE(PG8_SB(1, 1), b3 + hstepB, voffB); PG8_STAGE(PG8_SA(1, 0), a3, voffA);
;             PG8_WAIT_V(8); PG8_WAIT_L(0); PG8_BAR; PG8_MMA(1, 0, At, B0); PG8_MMA(1, 1, At, B1); PG8_BAR; PG8_SCHED;
	s_add_i32 s43, 0, 0x18000
	s_add_i32 s75, 0, 0x1c000
	v_add_u32_e32 v32, s75, v210
	ds_read_b128 v[4:7], v251
	ds_read_b128 v[8:11], v251 offset:1024
	ds_read_b128 v[12:15], v251 offset:2048
	ds_read_b128 v[16:19], v251 offset:3072
	ds_read_b128 v[20:23], v32
	ds_read_b128 v[24:27], v32 offset:1024
	ds_read_b128 v[28:31], v32 offset:2048
	ds_read_b128 v[32:35], v32 offset:3072
	v_lshl_add_u64 v[188:189], v[188:189], 0, v[168:169]
	s_mov_b32 m0, s63
	v_lshl_add_u64 v[202:203], v[188:189], 0, v[0:1]
	ds_read_b128 v[214:217], v212 offset:32768
	ds_read_b128 v[218:221], v212 offset:33792
	ds_read_b128 v[226:229], v212 offset:34816
	ds_read_b128 v[230:233], v212 offset:35840
	ds_read_b128 v[234:237], v212 offset:36864
	ds_read_b128 v[238:241], v212 offset:37888
	ds_read_b128 v[242:245], v212 offset:38912
	ds_read_b128 v[246:249], v212 offset:39936
	global_load_lds_dwordx4 v[202:203], off
	v_lshl_add_u64 v[188:189], v[188:189], 0, v[164:165]
	s_mov_b32 m0, s64
	s_nop 0
	global_load_lds_dwordx4 v[188:189], off
	s_waitcnt vmcnt(8)
	s_waitcnt lgkmcnt(0)
	s_barrier
	s_setprio 1
	v_mfma_f32_16x16x128_f8f6f4 v[160:163], v[4:11], v[214:221], v[160:163]
	v_mfma_f32_16x16x128_f8f6f4 v[156:159], v[12:19], v[214:221], v[156:159]
	v_mfma_f32_16x16x128_f8f6f4 v[144:147], v[4:11], v[226:233], v[144:147]
	v_mfma_f32_16x16x128_f8f6f4 v[140:143], v[12:19], v[226:233], v[140:143]
	v_mfma_f32_16x16x128_f8f6f4 v[128:131], v[4:11], v[234:241], v[128:131]
	v_mfma_f32_16x16x128_f8f6f4 v[124:127], v[12:19], v[234:241], v[124:127]
	v_mfma_f32_16x16x128_f8f6f4 v[112:115], v[4:11], v[242:249], v[112:115]
	v_mfma_f32_16x16x128_f8f6f4 v[108:111], v[12:19], v[242:249], v[108:111]
	v_mfma_f32_16x16x128_f8f6f4 v[152:155], v[20:27], v[214:221], v[152:155]
	v_mfma_f32_16x16x128_f8f6f4 v[148:151], v[28:35], v[214:221], v[148:151]
	v_mfma_f32_16x16x128_f8f6f4 v[136:139], v[20:27], v[226:233], v[136:139]
	v_mfma_f32_16x16x128_f8f6f4 v[132:135], v[28:35], v[226:233], v[132:135]
	v_mfma_f32_16x16x128_f8f6f4 v[120:123], v[20:27], v[234:241], v[120:123]
	v_mfma_f32_16x16x128_f8f6f4 v[116:119], v[28:35], v[234:241], v[116:119]
	v_mfma_f32_16x16x128_f8f6f4 v[104:107], v[20:27], v[242:249], v[104:107]
	v_mfma_f32_16x16x128_f8f6f4 v[100:103], v[28:35], v[242:249], v[100:103]
	s_setprio 0
	s_barrier
	s_add_i32 s43, s43, s33
	v_lshl_add_u64 v[188:189], v[190:191], 0, s[52:53]
	s_mov_b32 m0, s43
	ds_read_b128 v[214:217], v212 offset:49152
	ds_read_b128 v[218:221], v212 offset:50176
	ds_read_b128 v[226:229], v212 offset:51200
	ds_read_b128 v[230:233], v212 offset:52224
	ds_read_b128 v[234:237], v212 offset:53248
	ds_read_b128 v[238:241], v212 offset:54272
	ds_read_b128 v[242:245], v212 offset:55296
	ds_read_b128 v[246:249], v212 offset:56320
	global_load_lds_dwordx4 v[188:189], off
	v_lshl_add_u64 v[188:189], v[192:193], 0, s[52:53]
	s_add_i32 m0, s43, 0x2000
	s_add_i32 s43, s75, s33
	global_load_lds_dwordx4 v[188:189], off
	v_lshl_add_u64 v[188:189], v[194:195], 0, s[52:53]
	s_mov_b32 m0, s43
	s_nop 0
	global_load_lds_dwordx4 v[188:189], off
	v_lshl_add_u64 v[188:189], v[196:197], 0, s[52:53]
	s_add_i32 m0, s43, 0x2000
	s_nop 0
	global_load_lds_dwordx4 v[188:189], off
	v_lshl_add_u64 v[188:189], v[198:199], 0, s[52:53]
	s_mov_b32 m0, s65
	s_nop 0
	global_load_lds_dwordx4 v[188:189], off
	v_lshl_add_u64 v[188:189], v[200:201], 0, s[52:53]
	s_mov_b32 m0, s66
	s_nop 0
	global_load_lds_dwordx4 v[188:189], off
	s_waitcnt vmcnt(8)
	s_waitcnt lgkmcnt(0)
	s_barrier
	s_setprio 1
	v_mfma_f32_16x16x128_f8f6f4 v[96:99], v[4:11], v[214:221], v[96:99]
	v_mfma_f32_16x16x128_f8f6f4 v[92:95], v[12:19], v[214:221], v[92:95]
	v_mfma_f32_16x16x128_f8f6f4 v[80:83], v[4:11], v[226:233], v[80:83]
	v_mfma_f32_16x16x128_f8f6f4 v[76:79], v[12:19], v[226:233], v[76:79]
	v_mfma_f32_16x16x128_f8f6f4 v[64:67], v[4:11], v[234:241], v[64:67]
	v_mfma_f32_16x16x128_f8f6f4 v[60:63], v[12:19], v[234:241], v[60:63]
	v_mfma_f32_16x16x128_f8f6f4 v[48:51], v[4:11], v[242:249], v[48:51]
	v_mfma_f32_16x16x128_f8f6f4 v[44:47], v[12:19], v[242:249], v[44:47]
	v_mfma_f32_16x16x128_f8f6f4 v[88:91], v[20:27], v[214:221], v[88:91]
	v_mfma_f32_16x16x128_f8f6f4 v[84:87], v[28:35], v[214:221], v[84:87]
	v_mfma_f32_16x16x128_f8f6f4 v[72:75], v[20:27], v[226:233], v[72:75]
	v_mfma_f32_16x16x128_f8f6f4 v[68:71], v[28:35], v[226:233], v[68:71]
	v_mfma_f32_16x16x128_f8f6f4 v[56:59], v[20:27], v[234:241], v[56:59]
	v_mfma_f32_16x16x128_f8f6f4 v[52:55], v[28:35], v[234:241], v[52:55]
	v_mfma_f32_16x16x128_f8f6f4 v[40:43], v[20:27], v[242:249], v[40:43]
	v_mfma_f32_16x16x128_f8f6f4 v[36:39], v[28:35], v[242:249], v[36:39]
	s_setprio 0
	s_barrier
	s_add_i32 s42, s42, 2
	s_add_u32 s28, s28, 0x100
	s_addc_u32 s29, s29, 0
	s_cmp_gt_u32 s42, 29
	s_cbranch_scc0 .LBB0_818
	s_and_b64 vcc, exec, s[60:61]
	s_cbranch_vccz .LBB0_821
	s_barrier

; #define PG8_STAGE(bufoff, gbase, voff) do { _Pragma("unroll") for (int _i = 0; _i < 2; ++_i) \
;         __builtin_amdgcn_global_load_lds((const unsigned*)((const char*)(gbase) + (voff)[_i]), (LAS unsigned*)(lds + (bufoff) + ldsw + _i * 8192), 16, 0, 0); } while (0)
; #define PG8_LDA(dst, b, h) do { _Pragma("unroll") for (int m = 0; m < 4; ++m) _Pragma("unroll") for (int k = 0; k < 2; ++k) dst[m][k] = *(const LAS bf16x8*)(lds + PG8_SA(b, h) + aoff + m * 2048 + k * 1024); } while (0)
; #define PG8_LDB(dst, b, h) do { _Pragma("unroll") for (int n = 0; n < 2; ++n) _Pragma("unroll") for (int k = 0; k < 2; ++k) dst[n][k] = *(const LAS bf16x8*)(lds + PG8_SB(b, h) + boff + n * 2048 + k * 1024); } while (0)
; #define PG8_WAIT_V(n) asm volatile("s_waitcnt vmcnt(" #n ")" ::: "memory")
; #define PG8_WAIT_L(n) asm volatile("s_waitcnt lgkmcnt(" #n ")" ::: "memory")
; #define PG8_BAR __builtin_amdgcn_s_barrier()
; #define PG8_SCHED __builtin_amdgcn_sched_barrier(0)
;     ...
;             const char* a2 = last ? nA : cA + (size_t)(t + 2) * kstep; const char* b2 = last ? nB : cB + (size_t)(t + 2) * kstep;
;             const char* a3 = a2 + kstep; const char* b3 = b2 + kstep;
;             if constexpr (SP2) {
;             PG8_LDB(B0, 0, 0); PG8_LDB(B1, 0, 1); PG8_SCHED; PG8_LDA(At, 0, 0); PG8_STAGE(PG8_SA(1, 1), a1 + hstepA, voffA);
;             PG8_WAIT_V(8); PG8_WAIT_L(0); PG8_BAR; PG8_MMA(0, 0, At, B0); PG8_MMA(0, 1, At, B1); PG8_BAR; PG8_SCHED;
;             PG8_LDA(At, 0, 1); PG8_STAGE(PG8_SB(0, 0), b2, voffB); PG8_STAGE(PG8_SB(0, 1), b2 + hstepB, voffB); PG8_STAGE(PG8_SA(0, 0), a2, voffA);
.LBB0_912:
	s_add_i32 s59, 0, 0x10000
	s_add_i32 s75, 0, 0x14000
	ds_read_b128 v[162:165], v246
	ds_read_b128 v[166:169], v246 offset:1024
	ds_read_b128 v[170:173], v246 offset:2048
	ds_read_b128 v[174:177], v246 offset:3072
	ds_read_b128 v[178:181], v247
	ds_read_b128 v[182:185], v247 offset:1024
	ds_read_b128 v[186:189], v247 offset:2048
	ds_read_b128 v[190:193], v247 offset:3072
	ds_read_b128 v[194:197], v160
	ds_read_b128 v[198:201], v160 offset:1024
	ds_read_b128 v[202:205], v160 offset:2048
	ds_read_b128 v[206:209], v160 offset:3072
	ds_read_b128 v[210:213], v160 offset:4096
	ds_read_b128 v[214:217], v160 offset:5120
	ds_read_b128 v[218:221], v160 offset:6144
	ds_read_b128 v[226:229], v160 offset:7168
	v_lshl_add_u64 v[230:231], v[148:149], 0, s[38:39]
	s_cmpk_eq_i32 s38, 0xf00
	v_lshl_add_u64 v[230:231], v[230:231], 0, s[4:5]
	s_cselect_b64 vcc, -1, 0
	v_lshl_add_u64 v[232:233], v[154:155], 0, s[38:39]
	v_cndmask_b32_e32 v231, v231, v145, vcc
	v_cndmask_b32_e32 v230, v230, v144, vcc
	v_cndmask_b32_e32 v233, v233, v147, vcc
	v_cndmask_b32_e32 v232, v232, v146, vcc
	s_add_i32 m0, s60, 0xc000
	v_lshl_add_u64 v[234:235], v[152:153], 0, s[38:39]
	global_load_lds_dwordx4 v[234:235], off
	v_lshl_add_u64 v[234:235], v[150:151], 0, s[38:39]
	s_add_i32 m0, s60, 0xe000
	s_nop 0
	global_load_lds_dwordx4 v[234:235], off
	s_waitcnt vmcnt(8)
	s_waitcnt lgkmcnt(0)
	s_barrier
	s_setprio 1
	v_mfma_i32_16x16x64_i8 v[128:131], v[162:165], v[194:197], v[128:131]
	v_mfma_i32_16x16x64_i8 v[124:127], v[170:173], v[194:197], v[124:127]
	v_mfma_i32_16x16x64_i8 v[120:123], v[162:165], v[202:205], v[120:123]
	v_mfma_i32_16x16x64_i8 v[116:119], v[170:173], v[202:205], v[116:119]
	v_mfma_i32_16x16x64_i8 v[112:115], v[162:165], v[210:213], v[112:115]
	v_mfma_i32_16x16x64_i8 v[108:111], v[170:173], v[210:213], v[108:111]
	v_mfma_i32_16x16x64_i8 v[104:107], v[162:165], v[218:221], v[104:107]
	v_mfma_i32_16x16x64_i8 v[100:103], v[170:173], v[218:221], v[100:103]
	v_mfma_i32_16x16x64_i8 v[128:131], v[166:169], v[198:201], v[128:131]
	v_mfma_i32_16x16x64_i8 v[124:127], v[174:177], v[198:201], v[124:127]
	v_mfma_i32_16x16x64_i8 v[120:123], v[166:169], v[206:209], v[120:123]
	v_mfma_i32_16x16x64_i8 v[116:119], v[174:177], v[206:209], v[116:119]
	v_mfma_i32_16x16x64_i8 v[112:115], v[166:169], v[214:217], v[112:115]
	v_mfma_i32_16x16x64_i8 v[108:111], v[174:177], v[214:217], v[108:111]
	v_mfma_i32_16x16x64_i8 v[104:107], v[166:169], v[226:229], v[104:107]
	v_mfma_i32_16x16x64_i8 v[100:103], v[174:177], v[226:229], v[100:103]
	v_mfma_i32_16x16x64_i8 v[96:99], v[178:181], v[194:197], v[96:99]
	v_mfma_i32_16x16x64_i8 v[92:95], v[186:189], v[194:197], v[92:95]
	v_mfma_i32_16x16x64_i8 v[88:91], v[178:181], v[202:205], v[88:91]
	v_mfma_i32_16x16x64_i8 v[84:87], v[186:189], v[202:205], v[84:87]
	v_mfma_i32_16x16x64_i8 v[80:83], v[178:181], v[210:213], v[80:83]
	v_mfma_i32_16x16x64_i8 v[76:79], v[186:189], v[210:213], v[76:79]
	v_mfma_i32_16x16x64_i8 v[72:75], v[178:181], v[218:221], v[72:75]
	v_mfma_i32_16x16x64_i8 v[68:71], v[186:189], v[218:221], v[68:71]
	v_mfma_i32_16x16x64_i8 v[96:99], v[182:185], v[198:201], v[96:99]
	v_mfma_i32_16x16x64_i8 v[92:95], v[190:193], v[198:201], v[92:95]
	v_mfma_i32_16x16x64_i8 v[88:91], v[182:185], v[206:209], v[88:91]
	v_mfma_i32_16x16x64_i8 v[84:87], v[190:193], v[206:209], v[84:87]
	v_mfma_i32_16x16x64_i8 v[80:83], v[182:185], v[214:217], v[80:83]
	v_mfma_i32_16x16x64_i8 v[76:79], v[190:193], v[214:217], v[76:79]
	v_mfma_i32_16x16x64_i8 v[72:75], v[182:185], v[226:229], v[72:75]
	v_mfma_i32_16x16x64_i8 v[68:71], v[190:193], v[226:229], v[68:71]
	s_setprio 0
	s_barrier
	s_add_i32 s59, s59, s57
	v_lshl_add_u64 v[234:235], v[232:233], 0, v[2:3]
	s_mov_b32 m0, s59
	ds_read_b128 v[194:197], v160 offset:16384
	ds_read_b128 v[198:201], v160 offset:17408
	ds_read_b128 v[202:205], v160 offset:18432
	ds_read_b128 v[206:209], v160 offset:19456
	ds_read_b128 v[210:213], v160 offset:20480
	ds_read_b128 v[214:217], v160 offset:21504
	ds_read_b128 v[218:221], v160 offset:22528
	ds_read_b128 v[226:229], v160 offset:23552
	global_load_lds_dwordx4 v[234:235], off
	v_lshl_add_u64 v[236:237], v[232:233], 0, v[134:135]
	s_add_i32 m0, s59, 0x2000
	v_lshl_add_u64 v[232:233], v[232:233], 0, v[138:139]
	s_add_i32 s59, s75, s57
	global_load_lds_dwordx4 v[236:237], off
	v_lshl_add_u64 v[238:239], v[232:233], 0, v[2:3]
	s_mov_b32 m0, s59
	v_lshl_add_u64 v[232:233], v[232:233], 0, v[134:135]
	global_load_lds_dwordx4 v[238:239], off
	s_add_i32 m0, s59, 0x2000
	v_lshl_add_u64 v[240:241], v[230:231], 0, v[0:1]
	global_load_lds_dwordx4 v[232:233], off
	s_mov_b32 m0, s60
	v_lshl_add_u64 v[242:243], v[230:231], 0, v[132:133]
	global_load_lds_dwordx4 v[240:241], off
	s_mov_b32 m0, s61
	s_nop 0
	global_load_lds_dwordx4 v[242:243], off
	s_waitcnt vmcnt(8)
	s_waitcnt lgkmcnt(0)
	s_barrier
; #define PG8_STAGE(bufoff, gbase, voff) do { _Pragma("unroll") for (int _i = 0; _i < 2; ++_i) \
;         __builtin_amdgcn_global_load_lds((const unsigned*)((const char*)(gbase) + (voff)[_i]), (LAS unsigned*)(lds + (bufoff) + ldsw + _i * 8192), 16, 0, 0); } while (0)
; #define PG8_LDA(dst, b, h) do { _Pragma("unroll") for (int m = 0; m < 4; ++m) _Pragma("unroll") for (int k = 0; k < 2; ++k) dst[m][k] = *(const LAS bf16x8*)(lds + PG8_SA(b, h) + aoff + m * 2048 + k * 1024); } while (0)
; #define PG8_LDB(dst, b, h) do { _Pragma("unroll") for (int n = 0; n < 2; ++n) _Pragma("unroll") for (int k = 0; k < 2; ++k) dst[n][k] = *(const LAS bf16x8*)(lds + PG8_SB(b, h) + boff + n * 2048 + k * 1024); } while (0)
; #define PG8_WAIT_V(n) asm volatile("s_waitcnt vmcnt(" #n ")" ::: "memory")
; #define PG8_WAIT_L(n) asm volatile("s_waitcnt lgkmcnt(" #n ")" ::: "memory")
; #define PG8_BAR __builtin_amdgcn_s_barrier()
; #define PG8_SCHED __builtin_amdgcn_sched_barrier(0)
;     ...
;             PG8_WAIT_V(8); PG8_WAIT_L(0); PG8_BAR; PG8_MMA(1, 0, At, B0); PG8_MMA(1, 1, At, B1); PG8_BAR; PG8_SCHED;
;             PG8_LDB(B0, 1, 0); PG8_LDB(B1, 1, 1); PG8_SCHED; PG8_LDA(At, 1, 0); PG8_STAGE(PG8_SA(0, 1), a2 + hstepA, voffA);
;             PG8_WAIT_V(8); PG8_WAIT_L(0); PG8_BAR; PG8_MMA(0, 0, At, B0); PG8_MMA(0, 1, At, B1); PG8_BAR; PG8_SCHED;
	s_setprio 1
	v_mfma_i32_16x16x64_i8 v[64:67], v[162:165], v[194:197], v[64:67]
	v_mfma_i32_16x16x64_i8 v[60:63], v[170:173], v[194:197], v[60:63]
	v_mfma_i32_16x16x64_i8 v[56:59], v[162:165], v[202:205], v[56:59]
	v_mfma_i32_16x16x64_i8 v[52:55], v[170:173], v[202:205], v[52:55]
	v_mfma_i32_16x16x64_i8 v[48:51], v[162:165], v[210:213], v[48:51]
	v_mfma_i32_16x16x64_i8 v[44:47], v[170:173], v[210:213], v[44:47]
	v_mfma_i32_16x16x64_i8 v[40:43], v[162:165], v[218:221], v[40:43]
	v_mfma_i32_16x16x64_i8 v[36:39], v[170:173], v[218:221], v[36:39]
	v_mfma_i32_16x16x64_i8 v[64:67], v[166:169], v[198:201], v[64:67]
	v_mfma_i32_16x16x64_i8 v[60:63], v[174:177], v[198:201], v[60:63]
	v_mfma_i32_16x16x64_i8 v[56:59], v[166:169], v[206:209], v[56:59]
	v_mfma_i32_16x16x64_i8 v[52:55], v[174:177], v[206:209], v[52:55]
	v_mfma_i32_16x16x64_i8 v[48:51], v[166:169], v[214:217], v[48:51]
	v_mfma_i32_16x16x64_i8 v[44:47], v[174:177], v[214:217], v[44:47]
	v_mfma_i32_16x16x64_i8 v[40:43], v[166:169], v[226:229], v[40:43]
	v_mfma_i32_16x16x64_i8 v[36:39], v[174:177], v[226:229], v[36:39]
	v_mfma_i32_16x16x64_i8 v[32:35], v[178:181], v[194:197], v[32:35]
	v_mfma_i32_16x16x64_i8 v[28:31], v[186:189], v[194:197], v[28:31]
	v_mfma_i32_16x16x64_i8 v[24:27], v[178:181], v[202:205], v[24:27]
	v_mfma_i32_16x16x64_i8 v[20:23], v[186:189], v[202:205], v[20:23]
	v_mfma_i32_16x16x64_i8 v[16:19], v[178:181], v[210:213], v[16:19]
	v_mfma_i32_16x16x64_i8 v[12:15], v[186:189], v[210:213], v[12:15]
	v_mfma_i32_16x16x64_i8 v[8:11], v[178:181], v[218:221], v[8:11]
	v_mfma_i32_16x16x64_i8 v[4:7], v[186:189], v[218:221], v[4:7]
	v_mfma_i32_16x16x64_i8 v[32:35], v[182:185], v[198:201], v[32:35]
	v_mfma_i32_16x16x64_i8 v[28:31], v[190:193], v[198:201], v[28:31]
	v_mfma_i32_16x16x64_i8 v[24:27], v[182:185], v[206:209], v[24:27]
	v_mfma_i32_16x16x64_i8 v[20:23], v[190:193], v[206:209], v[20:23]
	v_mfma_i32_16x16x64_i8 v[16:19], v[182:185], v[214:217], v[16:19]
	v_mfma_i32_16x16x64_i8 v[12:15], v[190:193], v[214:217], v[12:15]
	v_mfma_i32_16x16x64_i8 v[8:11], v[182:185], v[226:229], v[8:11]
	v_mfma_i32_16x16x64_i8 v[4:7], v[190:193], v[226:229], v[4:7]
	s_setprio 0
	s_barrier
	s_add_i32 s59, 0, 0x18000
	s_add_i32 s75, 0, 0x1c000
	ds_read_b128 v[162:165], v248
	ds_read_b128 v[166:169], v248 offset:1024
	ds_read_b128 v[170:173], v248 offset:2048
	ds_read_b128 v[174:177], v248 offset:3072
	ds_read_b128 v[178:181], v249
	ds_read_b128 v[182:185], v249 offset:1024
	ds_read_b128 v[186:189], v249 offset:2048
	ds_read_b128 v[190:193], v249 offset:3072
	ds_read_b128 v[194:197], v160 offset:32768
	ds_read_b128 v[198:201], v160 offset:33792
	ds_read_b128 v[202:205], v160 offset:34816
	ds_read_b128 v[206:209], v160 offset:35840
	ds_read_b128 v[210:213], v160 offset:36864
	ds_read_b128 v[214:217], v160 offset:37888
	ds_read_b128 v[218:221], v160 offset:38912
	ds_read_b128 v[226:229], v160 offset:39936
	v_lshl_add_u64 v[230:231], v[230:231], 0, v[136:137]
	s_mov_b32 m0, s62
	v_lshl_add_u64 v[244:245], v[230:231], 0, v[0:1]
	global_load_lds_dwordx4 v[244:245], off
	v_lshl_add_u64 v[230:231], v[230:231], 0, v[132:133]
	s_mov_b32 m0, s63
	s_nop 0
	global_load_lds_dwordx4 v[230:231], off
	s_waitcnt vmcnt(8)
	s_waitcnt lgkmcnt(0)
	s_barrier
	s_setprio 1
	v_mfma_i32_16x16x64_i8 v[128:131], v[162:165], v[194:197], v[128:131]
	v_mfma_i32_16x16x64_i8 v[124:127], v[170:173], v[194:197], v[124:127]
	v_mfma_i32_16x16x64_i8 v[120:123], v[162:165], v[202:205], v[120:123]
	v_mfma_i32_16x16x64_i8 v[116:119], v[170:173], v[202:205], v[116:119]
	v_mfma_i32_16x16x64_i8 v[112:115], v[162:165], v[210:213], v[112:115]
	v_mfma_i32_16x16x64_i8 v[108:111], v[170:173], v[210:213], v[108:111]
	v_mfma_i32_16x16x64_i8 v[104:107], v[162:165], v[218:221], v[104:107]
	v_mfma_i32_16x16x64_i8 v[100:103], v[170:173], v[218:221], v[100:103]
	v_mfma_i32_16x16x64_i8 v[128:131], v[166:169], v[198:201], v[128:131]
	v_mfma_i32_16x16x64_i8 v[124:127], v[174:177], v[198:201], v[124:127]
	v_mfma_i32_16x16x64_i8 v[120:123], v[166:169], v[206:209], v[120:123]
	v_mfma_i32_16x16x64_i8 v[116:119], v[174:177], v[206:209], v[116:119]
	v_mfma_i32_16x16x64_i8 v[112:115], v[166:169], v[214:217], v[112:115]
	v_mfma_i32_16x16x64_i8 v[108:111], v[174:177], v[214:217], v[108:111]
	v_mfma_i32_16x16x64_i8 v[104:107], v[166:169], v[226:229], v[104:107]
	v_mfma_i32_16x16x64_i8 v[100:103], v[174:177], v[226:229], v[100:103]
	v_mfma_i32_16x16x64_i8 v[96:99], v[178:181], v[194:197], v[96:99]
	v_mfma_i32_16x16x64_i8 v[92:95], v[186:189], v[194:197], v[92:95]
	v_mfma_i32_16x16x64_i8 v[88:91], v[178:181], v[202:205], v[88:91]
	v_mfma_i32_16x16x64_i8 v[84:87], v[186:189], v[202:205], v[84:87]
	v_mfma_i32_16x16x64_i8 v[80:83], v[178:181], v[210:213], v[80:83]
	v_mfma_i32_16x16x64_i8 v[76:79], v[186:189], v[210:213], v[76:79]
	v_mfma_i32_16x16x64_i8 v[72:75], v[178:181], v[218:221], v[72:75]
	v_mfma_i32_16x16x64_i8 v[68:71], v[186:189], v[218:221], v[68:71]
	v_mfma_i32_16x16x64_i8 v[96:99], v[182:185], v[198:201], v[96:99]
	v_mfma_i32_16x16x64_i8 v[92:95], v[190:193], v[198:201], v[92:95]
	v_mfma_i32_16x16x64_i8 v[88:91], v[182:185], v[206:209], v[88:91]
	v_mfma_i32_16x16x64_i8 v[84:87], v[190:193], v[206:209], v[84:87]
	v_mfma_i32_16x16x64_i8 v[80:83], v[182:185], v[214:217], v[80:83]
	v_mfma_i32_16x16x64_i8 v[76:79], v[190:193], v[214:217], v[76:79]
	v_mfma_i32_16x16x64_i8 v[72:75], v[182:185], v[226:229], v[72:75]
	v_mfma_i32_16x16x64_i8 v[68:71], v[190:193], v[226:229], v[68:71]
	s_setprio 0
	s_barrier
; #define PG8_STAGE(bufoff, gbase, voff) do { _Pragma("unroll") for (int _i = 0; _i < 2; ++_i) \
;         __builtin_amdgcn_global_load_lds((const unsigned*)((const char*)(gbase) + (voff)[_i]), (LAS unsigned*)(lds + (bufoff) + ldsw + _i * 8192), 16, 0, 0); } while (0)
; #define PG8_LDA(dst, b, h) do { _Pragma("unroll") for (int m = 0; m < 4; ++m) _Pragma("unroll") for (int k = 0; k < 2; ++k) dst[m][k] = *(const LAS bf16x8*)(lds + PG8_SA(b, h) + aoff + m * 2048 + k * 1024); } while (0)
; #define PG8_WAIT_V(n) asm volatile("s_waitcnt vmcnt(" #n ")" ::: "memory")
; #define PG8_WAIT_L(n) asm volatile("s_waitcnt lgkmcnt(" #n ")" ::: "memory")
; #define PG8_BAR __builtin_amdgcn_s_barrier()
; #define PG8_SCHED __builtin_amdgcn_sched_barrier(0)
;     ...
;             PG8_LDA(At, 1, 1); PG8_STAGE(PG8_SB(1, 0), b3, voffB); PG8_STAGE(PG8_SB(1, 1), b3 + hstepB, voffB); PG8_STAGE(PG8_SA(1, 0), a3, voffA);
;             PG8_WAIT_V(8); PG8_WAIT_L(0); PG8_BAR; PG8_MMA(1, 0, At, B0); PG8_MMA(1, 1, At, B1); PG8_BAR; PG8_SCHED;
	s_add_i32 s59, s59, s57
	v_lshl_add_u64 v[230:231], v[234:235], 0, s[52:53]
	s_mov_b32 m0, s59
	ds_read_b128 v[194:197], v160 offset:49152
	ds_read_b128 v[198:201], v160 offset:50176
	ds_read_b128 v[202:205], v160 offset:51200
	ds_read_b128 v[206:209], v160 offset:52224
	ds_read_b128 v[210:213], v160 offset:53248
	ds_read_b128 v[214:217], v160 offset:54272
	ds_read_b128 v[218:221], v160 offset:55296
	ds_read_b128 v[226:229], v160 offset:56320
	global_load_lds_dwordx4 v[230:231], off
	v_lshl_add_u64 v[230:231], v[236:237], 0, s[52:53]
	s_add_i32 m0, s59, 0x2000
	s_add_i32 s59, s75, s57
	global_load_lds_dwordx4 v[230:231], off
	v_lshl_add_u64 v[230:231], v[238:239], 0, s[52:53]
	s_mov_b32 m0, s59
	s_nop 0
	global_load_lds_dwordx4 v[230:231], off
	v_lshl_add_u64 v[230:231], v[232:233], 0, s[52:53]
	s_add_i32 m0, s59, 0x2000
	s_nop 0
	global_load_lds_dwordx4 v[230:231], off
	v_lshl_add_u64 v[230:231], v[240:241], 0, s[52:53]
	s_mov_b32 m0, s64
	s_nop 0
	global_load_lds_dwordx4 v[230:231], off
	v_lshl_add_u64 v[230:231], v[242:243], 0, s[52:53]
	s_mov_b32 m0, s65
	s_nop 0
	global_load_lds_dwordx4 v[230:231], off
	s_waitcnt vmcnt(8)
	s_waitcnt lgkmcnt(0)
	s_barrier
	s_setprio 1
	v_mfma_i32_16x16x64_i8 v[64:67], v[162:165], v[194:197], v[64:67]
	v_mfma_i32_16x16x64_i8 v[60:63], v[170:173], v[194:197], v[60:63]
	v_mfma_i32_16x16x64_i8 v[56:59], v[162:165], v[202:205], v[56:59]
	v_mfma_i32_16x16x64_i8 v[52:55], v[170:173], v[202:205], v[52:55]
	v_mfma_i32_16x16x64_i8 v[48:51], v[162:165], v[210:213], v[48:51]
	v_mfma_i32_16x16x64_i8 v[44:47], v[170:173], v[210:213], v[44:47]
	v_mfma_i32_16x16x64_i8 v[40:43], v[162:165], v[218:221], v[40:43]
	v_mfma_i32_16x16x64_i8 v[36:39], v[170:173], v[218:221], v[36:39]
	v_mfma_i32_16x16x64_i8 v[64:67], v[166:169], v[198:201], v[64:67]
	v_mfma_i32_16x16x64_i8 v[60:63], v[174:177], v[198:201], v[60:63]
	v_mfma_i32_16x16x64_i8 v[56:59], v[166:169], v[206:209], v[56:59]
	v_mfma_i32_16x16x64_i8 v[52:55], v[174:177], v[206:209], v[52:55]
	v_mfma_i32_16x16x64_i8 v[48:51], v[166:169], v[214:217], v[48:51]
	v_mfma_i32_16x16x64_i8 v[44:47], v[174:177], v[214:217], v[44:47]
	v_mfma_i32_16x16x64_i8 v[40:43], v[166:169], v[226:229], v[40:43]
	v_mfma_i32_16x16x64_i8 v[36:39], v[174:177], v[226:229], v[36:39]
	v_mfma_i32_16x16x64_i8 v[32:35], v[178:181], v[194:197], v[32:35]
	v_mfma_i32_16x16x64_i8 v[28:31], v[186:189], v[194:197], v[28:31]
	v_mfma_i32_16x16x64_i8 v[24:27], v[178:181], v[202:205], v[24:27]
	v_mfma_i32_16x16x64_i8 v[20:23], v[186:189], v[202:205], v[20:23]
	v_mfma_i32_16x16x64_i8 v[16:19], v[178:181], v[210:213], v[16:19]
	v_mfma_i32_16x16x64_i8 v[12:15], v[186:189], v[210:213], v[12:15]
	v_mfma_i32_16x16x64_i8 v[8:11], v[178:181], v[218:221], v[8:11]
	v_mfma_i32_16x16x64_i8 v[4:7], v[186:189], v[218:221], v[4:7]
	v_mfma_i32_16x16x64_i8 v[32:35], v[182:185], v[198:201], v[32:35]
	v_mfma_i32_16x16x64_i8 v[28:31], v[190:193], v[198:201], v[28:31]
	v_mfma_i32_16x16x64_i8 v[24:27], v[182:185], v[206:209], v[24:27]
	v_mfma_i32_16x16x64_i8 v[20:23], v[190:193], v[206:209], v[20:23]
	v_mfma_i32_16x16x64_i8 v[16:19], v[182:185], v[214:217], v[16:19]
	v_mfma_i32_16x16x64_i8 v[12:15], v[190:193], v[214:217], v[12:15]
	v_mfma_i32_16x16x64_i8 v[8:11], v[182:185], v[226:229], v[8:11]
	v_mfma_i32_16x16x64_i8 v[4:7], v[190:193], v[226:229], v[4:7]
	s_setprio 0
	s_barrier
	s_add_i32 s58, s58, 2
	s_add_u32 s38, s38, 0x100
	s_addc_u32 s39, s39, 0
	s_cmp_gt_u32 s58, 29
	s_cbranch_scc0 .LBB0_912
	s_and_b64 vcc, exec, s[50:51]
	s_cbranch_vccz .LBB0_915
	s_barrier

; #define PG8_STAGE(bufoff, gbase, voff) do { _Pragma("unroll") for (int _i = 0; _i < 2; ++_i) \
;         __builtin_amdgcn_global_load_lds((const unsigned*)((const char*)(gbase) + (voff)[_i]), (LAS unsigned*)(lds + (bufoff) + ldsw + _i * 8192), 16, 0, 0); } while (0)
; #define PG8_LDA(dst, b, h) do { _Pragma("unroll") for (int m = 0; m < 4; ++m) _Pragma("unroll") for (int k = 0; k < 2; ++k) dst[m][k] = *(const LAS bf16x8*)(lds + PG8_SA(b, h) + aoff + m * 2048 + k * 1024); } while (0)
; #define PG8_LDB(dst, b, h) do { _Pragma("unroll") for (int n = 0; n < 2; ++n) _Pragma("unroll") for (int k = 0; k < 2; ++k) dst[n][k] = *(const LAS bf16x8*)(lds + PG8_SB(b, h) + boff + n * 2048 + k * 1024); } while (0)
; #define PG8_WAIT_V(n) asm volatile("s_waitcnt vmcnt(" #n ")" ::: "memory")
; #define PG8_WAIT_L(n) asm volatile("s_waitcnt lgkmcnt(" #n ")" ::: "memory")
; #define PG8_BAR __builtin_amdgcn_s_barrier()
; #define PG8_SCHED __builtin_amdgcn_sched_barrier(0)
;     ...
;             const char* a2 = last ? nA : cA + (size_t)(t + 2) * kstep; const char* b2 = last ? nB : cB + (size_t)(t + 2) * kstep;
;             const char* a3 = a2 + kstep; const char* b3 = b2 + kstep;
;             if constexpr (SP2) {
;             PG8_LDB(B0, 0, 0); PG8_LDB(B1, 0, 1); PG8_SCHED; PG8_LDA(At, 0, 0); PG8_STAGE(PG8_SA(1, 1), a1 + hstepA, voffA);
;             PG8_WAIT_V(8); PG8_WAIT_L(0); PG8_BAR; PG8_MMA(0, 0, At, B0); PG8_MMA(0, 1, At, B1); PG8_BAR; PG8_SCHED;
;             PG8_LDA(At, 0, 1); PG8_STAGE(PG8_SB(0, 0), b2, voffB); PG8_STAGE(PG8_SB(0, 1), b2 + hstepB, voffB); PG8_STAGE(PG8_SA(0, 0), a2, voffA);
.LBB0_1046:
	ds_read_b128 v[168:171], v164
	ds_read_b128 v[172:175], v164 offset:1024
	ds_read_b128 v[176:179], v164 offset:2048
	ds_read_b128 v[180:183], v164 offset:3072
	ds_read_b128 v[184:187], v165
	ds_read_b128 v[188:191], v165 offset:1024
	ds_read_b128 v[192:195], v165 offset:2048
	ds_read_b128 v[196:199], v165 offset:3072
	ds_read_b128 v[200:203], v166
	ds_read_b128 v[204:207], v166 offset:1024
	ds_read_b128 v[208:211], v166 offset:2048
	ds_read_b128 v[212:215], v166 offset:3072
	ds_read_b128 v[216:219], v166 offset:4096
	ds_read_b128 v[220:223], v166 offset:5120
	ds_read_b128 v[224:227], v166 offset:6144
	ds_read_b128 v[228:231], v166 offset:7168
	v_lshl_add_u64 v[232:233], v[152:153], 0, s[24:25]
	s_cmpk_eq_i32 s24, 0xf00
	v_lshl_add_u64 v[232:233], v[232:233], 0, s[20:21]
	v_lshl_add_u64 v[234:235], v[158:159], 0, s[24:25]
	s_cselect_b64 vcc, -1, 0
	v_cndmask_b32_e32 v233, v233, v149, vcc
	v_cndmask_b32_e32 v232, v232, v148, vcc
	v_cndmask_b32_e32 v235, v235, v151, vcc
	v_cndmask_b32_e32 v234, v234, v150, vcc
	s_mov_b32 m0, s44
	v_lshl_add_u64 v[236:237], v[156:157], 0, s[24:25]
	global_load_lds_dwordx4 v[236:237], off
	v_lshl_add_u64 v[236:237], v[154:155], 0, s[24:25]
	s_mov_b32 m0, s45
	s_nop 0
	global_load_lds_dwordx4 v[236:237], off
	s_waitcnt vmcnt(8)
	s_waitcnt lgkmcnt(0)
	s_barrier
	s_setprio 1
	v_mfma_i32_16x16x64_i8 v[124:127], v[168:171], v[200:203], v[124:127]
	v_mfma_i32_16x16x64_i8 v[120:123], v[176:179], v[200:203], v[120:123]
	v_mfma_i32_16x16x64_i8 v[116:119], v[168:171], v[208:211], v[116:119]
	v_mfma_i32_16x16x64_i8 v[112:115], v[176:179], v[208:211], v[112:115]
	v_mfma_i32_16x16x64_i8 v[108:111], v[168:171], v[216:219], v[108:111]
	v_mfma_i32_16x16x64_i8 v[104:107], v[176:179], v[216:219], v[104:107]
	v_mfma_i32_16x16x64_i8 v[100:103], v[168:171], v[224:227], v[100:103]
	v_mfma_i32_16x16x64_i8 v[96:99], v[176:179], v[224:227], v[96:99]
	v_mfma_i32_16x16x64_i8 v[124:127], v[172:175], v[204:207], v[124:127]
	v_mfma_i32_16x16x64_i8 v[120:123], v[180:183], v[204:207], v[120:123]
	v_mfma_i32_16x16x64_i8 v[116:119], v[172:175], v[212:215], v[116:119]
	v_mfma_i32_16x16x64_i8 v[112:115], v[180:183], v[212:215], v[112:115]
	v_mfma_i32_16x16x64_i8 v[108:111], v[172:175], v[220:223], v[108:111]
	v_mfma_i32_16x16x64_i8 v[104:107], v[180:183], v[220:223], v[104:107]
	v_mfma_i32_16x16x64_i8 v[100:103], v[172:175], v[228:231], v[100:103]
	v_mfma_i32_16x16x64_i8 v[96:99], v[180:183], v[228:231], v[96:99]
	v_mfma_i32_16x16x64_i8 v[92:95], v[184:187], v[200:203], v[92:95]
	v_mfma_i32_16x16x64_i8 v[88:91], v[192:195], v[200:203], v[88:91]
	v_mfma_i32_16x16x64_i8 v[84:87], v[184:187], v[208:211], v[84:87]
	v_mfma_i32_16x16x64_i8 v[80:83], v[192:195], v[208:211], v[80:83]
	v_mfma_i32_16x16x64_i8 v[76:79], v[184:187], v[216:219], v[76:79]
	v_mfma_i32_16x16x64_i8 v[72:75], v[192:195], v[216:219], v[72:75]
	v_mfma_i32_16x16x64_i8 v[68:71], v[184:187], v[224:227], v[68:71]
	v_mfma_i32_16x16x64_i8 v[64:67], v[192:195], v[224:227], v[64:67]
	v_mfma_i32_16x16x64_i8 v[92:95], v[188:191], v[204:207], v[92:95]
	v_mfma_i32_16x16x64_i8 v[88:91], v[196:199], v[204:207], v[88:91]
	v_mfma_i32_16x16x64_i8 v[84:87], v[188:191], v[212:215], v[84:87]
	v_mfma_i32_16x16x64_i8 v[80:83], v[196:199], v[212:215], v[80:83]
	v_mfma_i32_16x16x64_i8 v[76:79], v[188:191], v[220:223], v[76:79]
	v_mfma_i32_16x16x64_i8 v[72:75], v[196:199], v[220:223], v[72:75]
	v_mfma_i32_16x16x64_i8 v[68:71], v[188:191], v[228:231], v[68:71]
	v_mfma_i32_16x16x64_i8 v[64:67], v[196:199], v[228:231], v[64:67]
	s_setprio 0
	s_barrier
	s_mov_b32 m0, s46
	v_lshl_add_u64 v[236:237], v[234:235], 0, v[136:137]
	ds_read_b128 v[200:203], v166 offset:16384
	ds_read_b128 v[204:207], v166 offset:17408
	ds_read_b128 v[208:211], v166 offset:18432
	ds_read_b128 v[212:215], v166 offset:19456
	ds_read_b128 v[216:219], v166 offset:20480
	ds_read_b128 v[220:223], v166 offset:21504
	ds_read_b128 v[224:227], v166 offset:22528
	ds_read_b128 v[228:231], v166 offset:23552
	global_load_lds_dwordx4 v[236:237], off
	v_lshl_add_u64 v[238:239], v[234:235], 0, v[132:133]
	s_add_i32 m0, s46, 0x2000
	v_lshl_add_u64 v[234:235], v[234:235], 0, v[130:131]
	s_add_i32 s39, s43, s2
	global_load_lds_dwordx4 v[238:239], off
	v_lshl_add_u64 v[240:241], v[234:235], 0, v[136:137]
	s_mov_b32 m0, s39
	v_lshl_add_u64 v[234:235], v[234:235], 0, v[132:133]
	global_load_lds_dwordx4 v[240:241], off
	s_add_i32 m0, s39, 0x2000
	v_lshl_add_u64 v[242:243], v[232:233], 0, v[138:139]
	global_load_lds_dwordx4 v[234:235], off
	s_mov_b32 m0, s26
	v_lshl_add_u64 v[244:245], v[232:233], 0, v[134:135]
	global_load_lds_dwordx4 v[242:243], off
	s_mov_b32 m0, s27
	s_nop 0
	global_load_lds_dwordx4 v[244:245], off
	s_waitcnt vmcnt(8)
	s_waitcnt lgkmcnt(0)
	s_barrier
; #define PG8_STAGE(bufoff, gbase, voff) do { _Pragma("unroll") for (int _i = 0; _i < 2; ++_i) \
;         __builtin_amdgcn_global_load_lds((const unsigned*)((const char*)(gbase) + (voff)[_i]), (LAS unsigned*)(lds + (bufoff) + ldsw + _i * 8192), 16, 0, 0); } while (0)
; #define PG8_LDA(dst, b, h) do { _Pragma("unroll") for (int m = 0; m < 4; ++m) _Pragma("unroll") for (int k = 0; k < 2; ++k) dst[m][k] = *(const LAS bf16x8*)(lds + PG8_SA(b, h) + aoff + m * 2048 + k * 1024); } while (0)
; #define PG8_LDB(dst, b, h) do { _Pragma("unroll") for (int n = 0; n < 2; ++n) _Pragma("unroll") for (int k = 0; k < 2; ++k) dst[n][k] = *(const LAS bf16x8*)(lds + PG8_SB(b, h) + boff + n * 2048 + k * 1024); } while (0)
; #define PG8_WAIT_V(n) asm volatile("s_waitcnt vmcnt(" #n ")" ::: "memory")
; #define PG8_WAIT_L(n) asm volatile("s_waitcnt lgkmcnt(" #n ")" ::: "memory")
; #define PG8_BAR __builtin_amdgcn_s_barrier()
; #define PG8_SCHED __builtin_amdgcn_sched_barrier(0)
;     ...
;             PG8_WAIT_V(8); PG8_WAIT_L(0); PG8_BAR; PG8_MMA(1, 0, At, B0); PG8_MMA(1, 1, At, B1); PG8_BAR; PG8_SCHED;
;             PG8_LDB(B0, 1, 0); PG8_LDB(B1, 1, 1); PG8_SCHED; PG8_LDA(At, 1, 0); PG8_STAGE(PG8_SA(0, 1), a2 + hstepA, voffA);
;             PG8_WAIT_V(8); PG8_WAIT_L(0); PG8_BAR; PG8_MMA(0, 0, At, B0); PG8_MMA(0, 1, At, B1); PG8_BAR; PG8_SCHED;
	s_setprio 1
	v_mfma_i32_16x16x64_i8 v[60:63], v[168:171], v[200:203], v[60:63]
	v_mfma_i32_16x16x64_i8 v[56:59], v[176:179], v[200:203], v[56:59]
	v_mfma_i32_16x16x64_i8 v[52:55], v[168:171], v[208:211], v[52:55]
	v_mfma_i32_16x16x64_i8 v[48:51], v[176:179], v[208:211], v[48:51]
	v_mfma_i32_16x16x64_i8 v[44:47], v[168:171], v[216:219], v[44:47]
	v_mfma_i32_16x16x64_i8 v[40:43], v[176:179], v[216:219], v[40:43]
	v_mfma_i32_16x16x64_i8 v[36:39], v[168:171], v[224:227], v[36:39]
	v_mfma_i32_16x16x64_i8 v[32:35], v[176:179], v[224:227], v[32:35]
	v_mfma_i32_16x16x64_i8 v[60:63], v[172:175], v[204:207], v[60:63]
	v_mfma_i32_16x16x64_i8 v[56:59], v[180:183], v[204:207], v[56:59]
	v_mfma_i32_16x16x64_i8 v[52:55], v[172:175], v[212:215], v[52:55]
	v_mfma_i32_16x16x64_i8 v[48:51], v[180:183], v[212:215], v[48:51]
	v_mfma_i32_16x16x64_i8 v[44:47], v[172:175], v[220:223], v[44:47]
	v_mfma_i32_16x16x64_i8 v[40:43], v[180:183], v[220:223], v[40:43]
	v_mfma_i32_16x16x64_i8 v[36:39], v[172:175], v[228:231], v[36:39]
	v_mfma_i32_16x16x64_i8 v[32:35], v[180:183], v[228:231], v[32:35]
	v_mfma_i32_16x16x64_i8 v[28:31], v[184:187], v[200:203], v[28:31]
	v_mfma_i32_16x16x64_i8 v[24:27], v[192:195], v[200:203], v[24:27]
	v_mfma_i32_16x16x64_i8 v[20:23], v[184:187], v[208:211], v[20:23]
	v_mfma_i32_16x16x64_i8 v[16:19], v[192:195], v[208:211], v[16:19]
	v_mfma_i32_16x16x64_i8 v[12:15], v[184:187], v[216:219], v[12:15]
	v_mfma_i32_16x16x64_i8 v[8:11], v[192:195], v[216:219], v[8:11]
	v_mfma_i32_16x16x64_i8 v[4:7], v[184:187], v[224:227], v[4:7]
	v_mfma_i32_16x16x64_i8 v[0:3], v[192:195], v[224:227], v[0:3]
	v_mfma_i32_16x16x64_i8 v[28:31], v[188:191], v[204:207], v[28:31]
	v_mfma_i32_16x16x64_i8 v[24:27], v[196:199], v[204:207], v[24:27]
	v_mfma_i32_16x16x64_i8 v[20:23], v[188:191], v[212:215], v[20:23]
	v_mfma_i32_16x16x64_i8 v[16:19], v[196:199], v[212:215], v[16:19]
	v_mfma_i32_16x16x64_i8 v[12:15], v[188:191], v[220:223], v[12:15]
	v_mfma_i32_16x16x64_i8 v[8:11], v[196:199], v[220:223], v[8:11]
	v_mfma_i32_16x16x64_i8 v[4:7], v[188:191], v[228:231], v[4:7]
	v_mfma_i32_16x16x64_i8 v[0:3], v[196:199], v[228:231], v[0:3]
	s_setprio 0
	s_barrier
	s_add_i32 s39, 0, 0x18000
	s_add_i32 s51, 0, 0x1c000
	ds_read_b128 v[168:171], v248
	ds_read_b128 v[172:175], v248 offset:1024
	ds_read_b128 v[176:179], v248 offset:2048
	ds_read_b128 v[180:183], v248 offset:3072
	ds_read_b128 v[184:187], v249
	ds_read_b128 v[188:191], v249 offset:1024
	ds_read_b128 v[192:195], v249 offset:2048
	ds_read_b128 v[196:199], v249 offset:3072
	ds_read_b128 v[200:203], v166 offset:32768
	ds_read_b128 v[204:207], v166 offset:33792
	ds_read_b128 v[208:211], v166 offset:34816
	ds_read_b128 v[212:215], v166 offset:35840
	ds_read_b128 v[216:219], v166 offset:36864
	ds_read_b128 v[220:223], v166 offset:37888
	ds_read_b128 v[224:227], v166 offset:38912
	ds_read_b128 v[228:231], v166 offset:39936
	v_lshl_add_u64 v[232:233], v[232:233], 0, v[128:129]
	s_mov_b32 m0, s28
	v_lshl_add_u64 v[246:247], v[232:233], 0, v[138:139]
	global_load_lds_dwordx4 v[246:247], off
	v_lshl_add_u64 v[232:233], v[232:233], 0, v[134:135]
	s_mov_b32 m0, s29
	s_nop 0
	global_load_lds_dwordx4 v[232:233], off
	s_waitcnt vmcnt(8)
	s_waitcnt lgkmcnt(0)
	s_barrier
	s_setprio 1
	v_mfma_i32_16x16x64_i8 v[124:127], v[168:171], v[200:203], v[124:127]
	v_mfma_i32_16x16x64_i8 v[120:123], v[176:179], v[200:203], v[120:123]
	v_mfma_i32_16x16x64_i8 v[116:119], v[168:171], v[208:211], v[116:119]
	v_mfma_i32_16x16x64_i8 v[112:115], v[176:179], v[208:211], v[112:115]
	v_mfma_i32_16x16x64_i8 v[108:111], v[168:171], v[216:219], v[108:111]
	v_mfma_i32_16x16x64_i8 v[104:107], v[176:179], v[216:219], v[104:107]
	v_mfma_i32_16x16x64_i8 v[100:103], v[168:171], v[224:227], v[100:103]
	v_mfma_i32_16x16x64_i8 v[96:99], v[176:179], v[224:227], v[96:99]
	v_mfma_i32_16x16x64_i8 v[124:127], v[172:175], v[204:207], v[124:127]
	v_mfma_i32_16x16x64_i8 v[120:123], v[180:183], v[204:207], v[120:123]
	v_mfma_i32_16x16x64_i8 v[116:119], v[172:175], v[212:215], v[116:119]
	v_mfma_i32_16x16x64_i8 v[112:115], v[180:183], v[212:215], v[112:115]
	v_mfma_i32_16x16x64_i8 v[108:111], v[172:175], v[220:223], v[108:111]
	v_mfma_i32_16x16x64_i8 v[104:107], v[180:183], v[220:223], v[104:107]
	v_mfma_i32_16x16x64_i8 v[100:103], v[172:175], v[228:231], v[100:103]
	v_mfma_i32_16x16x64_i8 v[96:99], v[180:183], v[228:231], v[96:99]
	v_mfma_i32_16x16x64_i8 v[92:95], v[184:187], v[200:203], v[92:95]
	v_mfma_i32_16x16x64_i8 v[88:91], v[192:195], v[200:203], v[88:91]
	v_mfma_i32_16x16x64_i8 v[84:87], v[184:187], v[208:211], v[84:87]
	v_mfma_i32_16x16x64_i8 v[80:83], v[192:195], v[208:211], v[80:83]
	v_mfma_i32_16x16x64_i8 v[76:79], v[184:187], v[216:219], v[76:79]
	v_mfma_i32_16x16x64_i8 v[72:75], v[192:195], v[216:219], v[72:75]
	v_mfma_i32_16x16x64_i8 v[68:71], v[184:187], v[224:227], v[68:71]
	v_mfma_i32_16x16x64_i8 v[64:67], v[192:195], v[224:227], v[64:67]
	v_mfma_i32_16x16x64_i8 v[92:95], v[188:191], v[204:207], v[92:95]
	v_mfma_i32_16x16x64_i8 v[88:91], v[196:199], v[204:207], v[88:91]
	v_mfma_i32_16x16x64_i8 v[84:87], v[188:191], v[212:215], v[84:87]
	v_mfma_i32_16x16x64_i8 v[80:83], v[196:199], v[212:215], v[80:83]
	v_mfma_i32_16x16x64_i8 v[76:79], v[188:191], v[220:223], v[76:79]
	v_mfma_i32_16x16x64_i8 v[72:75], v[196:199], v[220:223], v[72:75]
	v_mfma_i32_16x16x64_i8 v[68:71], v[188:191], v[228:231], v[68:71]
	v_mfma_i32_16x16x64_i8 v[64:67], v[196:199], v[228:231], v[64:67]
	s_setprio 0
	s_barrier
; #define PG8_STAGE(bufoff, gbase, voff) do { _Pragma("unroll") for (int _i = 0; _i < 2; ++_i) \
;         __builtin_amdgcn_global_load_lds((const unsigned*)((const char*)(gbase) + (voff)[_i]), (LAS unsigned*)(lds + (bufoff) + ldsw + _i * 8192), 16, 0, 0); } while (0)
; #define PG8_LDA(dst, b, h) do { _Pragma("unroll") for (int m = 0; m < 4; ++m) _Pragma("unroll") for (int k = 0; k < 2; ++k) dst[m][k] = *(const LAS bf16x8*)(lds + PG8_SA(b, h) + aoff + m * 2048 + k * 1024); } while (0)
; #define PG8_WAIT_V(n) asm volatile("s_waitcnt vmcnt(" #n ")" ::: "memory")
; #define PG8_WAIT_L(n) asm volatile("s_waitcnt lgkmcnt(" #n ")" ::: "memory")
; #define PG8_BAR __builtin_amdgcn_s_barrier()
; #define PG8_SCHED __builtin_amdgcn_sched_barrier(0)
;     ...
;             PG8_LDA(At, 1, 1); PG8_STAGE(PG8_SB(1, 0), b3, voffB); PG8_STAGE(PG8_SB(1, 1), b3 + hstepB, voffB); PG8_STAGE(PG8_SA(1, 0), a3, voffA);
;             PG8_WAIT_V(8); PG8_WAIT_L(0); PG8_BAR; PG8_MMA(1, 0, At, B0); PG8_MMA(1, 1, At, B1); PG8_BAR; PG8_SCHED;
	s_add_i32 s39, s39, s2
	v_lshl_add_u64 v[232:233], v[236:237], 0, s[16:17]
	s_mov_b32 m0, s39
	ds_read_b128 v[200:203], v166 offset:49152
	ds_read_b128 v[204:207], v166 offset:50176
	ds_read_b128 v[208:211], v166 offset:51200
	ds_read_b128 v[212:215], v166 offset:52224
	ds_read_b128 v[216:219], v166 offset:53248
	ds_read_b128 v[220:223], v166 offset:54272
	ds_read_b128 v[224:227], v166 offset:55296
	ds_read_b128 v[228:231], v166 offset:56320
	global_load_lds_dwordx4 v[232:233], off
	v_lshl_add_u64 v[232:233], v[238:239], 0, s[16:17]
	s_add_i32 m0, s39, 0x2000
	s_add_i32 s39, s51, s2
	global_load_lds_dwordx4 v[232:233], off
	v_lshl_add_u64 v[232:233], v[240:241], 0, s[16:17]
	s_mov_b32 m0, s39
	s_nop 0
	global_load_lds_dwordx4 v[232:233], off
	v_lshl_add_u64 v[232:233], v[234:235], 0, s[16:17]
	s_add_i32 m0, s39, 0x2000
	s_nop 0
	global_load_lds_dwordx4 v[232:233], off
	v_lshl_add_u64 v[232:233], v[242:243], 0, s[16:17]
	s_mov_b32 m0, s40
	s_nop 0
	global_load_lds_dwordx4 v[232:233], off
	v_lshl_add_u64 v[232:233], v[244:245], 0, s[16:17]
	s_mov_b32 m0, s41
	s_nop 0
	global_load_lds_dwordx4 v[232:233], off
	s_waitcnt vmcnt(8)
	s_waitcnt lgkmcnt(0)
	s_barrier
	s_setprio 1
	v_mfma_i32_16x16x64_i8 v[60:63], v[168:171], v[200:203], v[60:63]
	v_mfma_i32_16x16x64_i8 v[56:59], v[176:179], v[200:203], v[56:59]
	v_mfma_i32_16x16x64_i8 v[52:55], v[168:171], v[208:211], v[52:55]
	v_mfma_i32_16x16x64_i8 v[48:51], v[176:179], v[208:211], v[48:51]
	v_mfma_i32_16x16x64_i8 v[44:47], v[168:171], v[216:219], v[44:47]
	v_mfma_i32_16x16x64_i8 v[40:43], v[176:179], v[216:219], v[40:43]
	v_mfma_i32_16x16x64_i8 v[36:39], v[168:171], v[224:227], v[36:39]
	v_mfma_i32_16x16x64_i8 v[32:35], v[176:179], v[224:227], v[32:35]
	v_mfma_i32_16x16x64_i8 v[60:63], v[172:175], v[204:207], v[60:63]
	v_mfma_i32_16x16x64_i8 v[56:59], v[180:183], v[204:207], v[56:59]
	v_mfma_i32_16x16x64_i8 v[52:55], v[172:175], v[212:215], v[52:55]
	v_mfma_i32_16x16x64_i8 v[48:51], v[180:183], v[212:215], v[48:51]
	v_mfma_i32_16x16x64_i8 v[44:47], v[172:175], v[220:223], v[44:47]
	v_mfma_i32_16x16x64_i8 v[40:43], v[180:183], v[220:223], v[40:43]
	v_mfma_i32_16x16x64_i8 v[36:39], v[172:175], v[228:231], v[36:39]
	v_mfma_i32_16x16x64_i8 v[32:35], v[180:183], v[228:231], v[32:35]
	v_mfma_i32_16x16x64_i8 v[28:31], v[184:187], v[200:203], v[28:31]
	v_mfma_i32_16x16x64_i8 v[24:27], v[192:195], v[200:203], v[24:27]
	v_mfma_i32_16x16x64_i8 v[20:23], v[184:187], v[208:211], v[20:23]
	v_mfma_i32_16x16x64_i8 v[16:19], v[192:195], v[208:211], v[16:19]
	v_mfma_i32_16x16x64_i8 v[12:15], v[184:187], v[216:219], v[12:15]
	v_mfma_i32_16x16x64_i8 v[8:11], v[192:195], v[216:219], v[8:11]
	v_mfma_i32_16x16x64_i8 v[4:7], v[184:187], v[224:227], v[4:7]
	v_mfma_i32_16x16x64_i8 v[0:3], v[192:195], v[224:227], v[0:3]
	v_mfma_i32_16x16x64_i8 v[28:31], v[188:191], v[204:207], v[28:31]
	v_mfma_i32_16x16x64_i8 v[24:27], v[196:199], v[204:207], v[24:27]
	v_mfma_i32_16x16x64_i8 v[20:23], v[188:191], v[212:215], v[20:23]
	v_mfma_i32_16x16x64_i8 v[16:19], v[196:199], v[212:215], v[16:19]
	v_mfma_i32_16x16x64_i8 v[12:15], v[188:191], v[220:223], v[12:15]
	v_mfma_i32_16x16x64_i8 v[8:11], v[196:199], v[220:223], v[8:11]
	v_mfma_i32_16x16x64_i8 v[4:7], v[188:191], v[228:231], v[4:7]
	v_mfma_i32_16x16x64_i8 v[0:3], v[196:199], v[228:231], v[0:3]
	s_setprio 0
	s_barrier
	s_add_i32 s38, s38, 2
	s_add_u32 s24, s24, 0x100
	s_addc_u32 s25, s25, 0
	s_cmp_gt_u32 s38, 29
	s_cbranch_scc0 .LBB0_1046
	s_and_b64 vcc, exec, s[18:19]
	s_cbranch_vccz .LBB0_1049
	s_barrier

; #define PG8_STAGE(bufoff, gbase, voff) do { _Pragma("unroll") for (int _i = 0; _i < 2; ++_i) \
;         __builtin_amdgcn_global_load_lds((const unsigned*)((const char*)(gbase) + (voff)[_i]), (LAS unsigned*)(lds + (bufoff) + ldsw + _i * 8192), 16, 0, 0); } while (0)
; #define PG8_LDA(dst, b, h) do { _Pragma("unroll") for (int m = 0; m < 4; ++m) _Pragma("unroll") for (int k = 0; k < 2; ++k) dst[m][k] = *(const LAS bf16x8*)(lds + PG8_SA(b, h) + aoff + m * 2048 + k * 1024); } while (0)
; #define PG8_LDB(dst, b, h) do { _Pragma("unroll") for (int n = 0; n < 2; ++n) _Pragma("unroll") for (int k = 0; k < 2; ++k) dst[n][k] = *(const LAS bf16x8*)(lds + PG8_SB(b, h) + boff + n * 2048 + k * 1024); } while (0)
; #define PG8_WAIT_V(n) asm volatile("s_waitcnt vmcnt(" #n ")" ::: "memory")
; #define PG8_WAIT_L(n) asm volatile("s_waitcnt lgkmcnt(" #n ")" ::: "memory")
; #define PG8_BAR __builtin_amdgcn_s_barrier()
; #define PG8_SCHED __builtin_amdgcn_sched_barrier(0)
;     ...
;             const char* a2 = last ? nA : cA + (size_t)(t + 2) * kstep; const char* b2 = last ? nB : cB + (size_t)(t + 2) * kstep;
;             const char* a3 = a2 + kstep; const char* b3 = b2 + kstep;
;             if constexpr (SP2) {
;             PG8_LDB(B0, 0, 0); PG8_LDB(B1, 0, 1); PG8_SCHED; PG8_LDA(At, 0, 0); PG8_STAGE(PG8_SA(1, 1), a1 + hstepA, voffA);
;             PG8_WAIT_V(8); PG8_WAIT_L(0); PG8_BAR; PG8_MMA(0, 0, At, B0); PG8_MMA(0, 1, At, B1); PG8_BAR; PG8_SCHED;
;             PG8_LDA(At, 0, 1); PG8_STAGE(PG8_SB(0, 0), b2, voffB); PG8_STAGE(PG8_SB(0, 1), b2 + hstepB, voffB); PG8_STAGE(PG8_SA(0, 0), a2, voffA);
.LBB0_1066:
	ds_read_b128 v[168:171], v164
	ds_read_b128 v[172:175], v164 offset:1024
	ds_read_b128 v[176:179], v164 offset:2048
	ds_read_b128 v[180:183], v164 offset:3072
	ds_read_b128 v[184:187], v165
	ds_read_b128 v[188:191], v165 offset:1024
	ds_read_b128 v[192:195], v165 offset:2048
	ds_read_b128 v[196:199], v165 offset:3072
	ds_read_b128 v[200:203], v166
	ds_read_b128 v[204:207], v166 offset:1024
	ds_read_b128 v[208:211], v166 offset:2048
	ds_read_b128 v[212:215], v166 offset:3072
	ds_read_b128 v[216:219], v166 offset:4096
	ds_read_b128 v[220:223], v166 offset:5120
	ds_read_b128 v[224:227], v166 offset:6144
	ds_read_b128 v[228:231], v166 offset:7168
	v_lshl_add_u64 v[232:233], v[152:153], 0, s[18:19]
	s_cmpk_eq_i32 s18, 0x1f00
	v_lshl_add_u64 v[232:233], v[232:233], 0, s[16:17]
	v_lshl_add_u64 v[234:235], v[158:159], 0, s[18:19]
	s_cselect_b64 vcc, -1, 0
	v_cndmask_b32_e32 v233, v233, v149, vcc
	v_cndmask_b32_e32 v232, v232, v148, vcc
	v_cndmask_b32_e32 v235, v235, v151, vcc
	v_cndmask_b32_e32 v234, v234, v150, vcc
	s_mov_b32 m0, s35
	v_lshl_add_u64 v[236:237], v[156:157], 0, s[18:19]
	global_load_lds_dwordx4 v[236:237], off
	v_lshl_add_u64 v[236:237], v[154:155], 0, s[18:19]
	s_mov_b32 m0, s40
	s_nop 0
	global_load_lds_dwordx4 v[236:237], off
	s_waitcnt vmcnt(8)
	s_waitcnt lgkmcnt(0)
	s_barrier
	s_setprio 1
	v_mfma_f32_16x16x32_bf16 v[124:127], v[168:171], v[200:203], v[124:127]
	v_mfma_f32_16x16x32_bf16 v[120:123], v[176:179], v[200:203], v[120:123]
	v_mfma_f32_16x16x32_bf16 v[108:111], v[168:171], v[208:211], v[108:111]
	v_mfma_f32_16x16x32_bf16 v[104:107], v[176:179], v[208:211], v[104:107]
	v_mfma_f32_16x16x32_bf16 v[92:95], v[168:171], v[216:219], v[92:95]
	v_mfma_f32_16x16x32_bf16 v[88:91], v[176:179], v[216:219], v[88:91]
	v_mfma_f32_16x16x32_bf16 v[76:79], v[168:171], v[224:227], v[76:79]
	v_mfma_f32_16x16x32_bf16 v[72:75], v[176:179], v[224:227], v[72:75]
	v_mfma_f32_16x16x32_bf16 v[124:127], v[172:175], v[204:207], v[124:127]
	v_mfma_f32_16x16x32_bf16 v[120:123], v[180:183], v[204:207], v[120:123]
	v_mfma_f32_16x16x32_bf16 v[108:111], v[172:175], v[212:215], v[108:111]
	v_mfma_f32_16x16x32_bf16 v[104:107], v[180:183], v[212:215], v[104:107]
	v_mfma_f32_16x16x32_bf16 v[92:95], v[172:175], v[220:223], v[92:95]
	v_mfma_f32_16x16x32_bf16 v[88:91], v[180:183], v[220:223], v[88:91]
	v_mfma_f32_16x16x32_bf16 v[76:79], v[172:175], v[228:231], v[76:79]
	v_mfma_f32_16x16x32_bf16 v[72:75], v[180:183], v[228:231], v[72:75]
	v_mfma_f32_16x16x32_bf16 v[116:119], v[184:187], v[200:203], v[116:119]
	v_mfma_f32_16x16x32_bf16 v[112:115], v[192:195], v[200:203], v[112:115]
	v_mfma_f32_16x16x32_bf16 v[100:103], v[184:187], v[208:211], v[100:103]
	v_mfma_f32_16x16x32_bf16 v[96:99], v[192:195], v[208:211], v[96:99]
	v_mfma_f32_16x16x32_bf16 v[84:87], v[184:187], v[216:219], v[84:87]
	v_mfma_f32_16x16x32_bf16 v[80:83], v[192:195], v[216:219], v[80:83]
	v_mfma_f32_16x16x32_bf16 v[68:71], v[184:187], v[224:227], v[68:71]
	v_mfma_f32_16x16x32_bf16 v[64:67], v[192:195], v[224:227], v[64:67]
	v_mfma_f32_16x16x32_bf16 v[116:119], v[188:191], v[204:207], v[116:119]
	v_mfma_f32_16x16x32_bf16 v[112:115], v[196:199], v[204:207], v[112:115]
	v_mfma_f32_16x16x32_bf16 v[100:103], v[188:191], v[212:215], v[100:103]
	v_mfma_f32_16x16x32_bf16 v[96:99], v[196:199], v[212:215], v[96:99]
	v_mfma_f32_16x16x32_bf16 v[84:87], v[188:191], v[220:223], v[84:87]
	v_mfma_f32_16x16x32_bf16 v[80:83], v[196:199], v[220:223], v[80:83]
	v_mfma_f32_16x16x32_bf16 v[68:71], v[188:191], v[228:231], v[68:71]
	v_mfma_f32_16x16x32_bf16 v[64:67], v[196:199], v[228:231], v[64:67]
	s_setprio 0
	s_barrier
	s_mov_b32 m0, s41
	v_lshl_add_u64 v[236:237], v[234:235], 0, v[136:137]
	ds_read_b128 v[200:203], v166 offset:16384
	ds_read_b128 v[204:207], v166 offset:17408
	ds_read_b128 v[208:211], v166 offset:18432
	ds_read_b128 v[212:215], v166 offset:19456
	ds_read_b128 v[216:219], v166 offset:20480
	ds_read_b128 v[220:223], v166 offset:21504
	ds_read_b128 v[224:227], v166 offset:22528
	ds_read_b128 v[228:231], v166 offset:23552
	global_load_lds_dwordx4 v[236:237], off
	v_lshl_add_u64 v[238:239], v[234:235], 0, v[132:133]
	s_add_i32 m0, s41, 0x2000
	v_lshl_add_u64 v[234:235], v[234:235], 0, v[130:131]
	s_add_i32 s39, s34, s2
	global_load_lds_dwordx4 v[238:239], off
	v_lshl_add_u64 v[240:241], v[234:235], 0, v[136:137]
	s_mov_b32 m0, s39
	v_lshl_add_u64 v[234:235], v[234:235], 0, v[132:133]
	global_load_lds_dwordx4 v[240:241], off
	s_add_i32 m0, s39, 0x2000
	v_lshl_add_u64 v[242:243], v[232:233], 0, v[138:139]
	global_load_lds_dwordx4 v[234:235], off
	s_mov_b32 m0, s21
	v_lshl_add_u64 v[244:245], v[232:233], 0, v[134:135]
	global_load_lds_dwordx4 v[242:243], off
	s_mov_b32 m0, s22
	s_nop 0
	global_load_lds_dwordx4 v[244:245], off
	s_waitcnt vmcnt(8)
	s_waitcnt lgkmcnt(0)
	s_barrier
; #define PG8_STAGE(bufoff, gbase, voff) do { _Pragma("unroll") for (int _i = 0; _i < 2; ++_i) \
;         __builtin_amdgcn_global_load_lds((const unsigned*)((const char*)(gbase) + (voff)[_i]), (LAS unsigned*)(lds + (bufoff) + ldsw + _i * 8192), 16, 0, 0); } while (0)
; #define PG8_LDA(dst, b, h) do { _Pragma("unroll") for (int m = 0; m < 4; ++m) _Pragma("unroll") for (int k = 0; k < 2; ++k) dst[m][k] = *(const LAS bf16x8*)(lds + PG8_SA(b, h) + aoff + m * 2048 + k * 1024); } while (0)
; #define PG8_LDB(dst, b, h) do { _Pragma("unroll") for (int n = 0; n < 2; ++n) _Pragma("unroll") for (int k = 0; k < 2; ++k) dst[n][k] = *(const LAS bf16x8*)(lds + PG8_SB(b, h) + boff + n * 2048 + k * 1024); } while (0)
; #define PG8_WAIT_V(n) asm volatile("s_waitcnt vmcnt(" #n ")" ::: "memory")
; #define PG8_WAIT_L(n) asm volatile("s_waitcnt lgkmcnt(" #n ")" ::: "memory")
; #define PG8_BAR __builtin_amdgcn_s_barrier()
; #define PG8_SCHED __builtin_amdgcn_sched_barrier(0)
;     ...
;             PG8_WAIT_V(8); PG8_WAIT_L(0); PG8_BAR; PG8_MMA(1, 0, At, B0); PG8_MMA(1, 1, At, B1); PG8_BAR; PG8_SCHED;
;             PG8_LDB(B0, 1, 0); PG8_LDB(B1, 1, 1); PG8_SCHED; PG8_LDA(At, 1, 0); PG8_STAGE(PG8_SA(0, 1), a2 + hstepA, voffA);
;             PG8_WAIT_V(8); PG8_WAIT_L(0); PG8_BAR; PG8_MMA(0, 0, At, B0); PG8_MMA(0, 1, At, B1); PG8_BAR; PG8_SCHED;
	s_setprio 1
	v_mfma_f32_16x16x32_bf16 v[60:63], v[168:171], v[200:203], v[60:63]
	v_mfma_f32_16x16x32_bf16 v[56:59], v[176:179], v[200:203], v[56:59]
	v_mfma_f32_16x16x32_bf16 v[44:47], v[168:171], v[208:211], v[44:47]
	v_mfma_f32_16x16x32_bf16 v[40:43], v[176:179], v[208:211], v[40:43]
	v_mfma_f32_16x16x32_bf16 v[28:31], v[168:171], v[216:219], v[28:31]
	v_mfma_f32_16x16x32_bf16 v[24:27], v[176:179], v[216:219], v[24:27]
	v_mfma_f32_16x16x32_bf16 v[12:15], v[168:171], v[224:227], v[12:15]
	v_mfma_f32_16x16x32_bf16 v[8:11], v[176:179], v[224:227], v[8:11]
	v_mfma_f32_16x16x32_bf16 v[60:63], v[172:175], v[204:207], v[60:63]
	v_mfma_f32_16x16x32_bf16 v[56:59], v[180:183], v[204:207], v[56:59]
	v_mfma_f32_16x16x32_bf16 v[44:47], v[172:175], v[212:215], v[44:47]
	v_mfma_f32_16x16x32_bf16 v[40:43], v[180:183], v[212:215], v[40:43]
	v_mfma_f32_16x16x32_bf16 v[28:31], v[172:175], v[220:223], v[28:31]
	v_mfma_f32_16x16x32_bf16 v[24:27], v[180:183], v[220:223], v[24:27]
	v_mfma_f32_16x16x32_bf16 v[12:15], v[172:175], v[228:231], v[12:15]
	v_mfma_f32_16x16x32_bf16 v[8:11], v[180:183], v[228:231], v[8:11]
	v_mfma_f32_16x16x32_bf16 v[52:55], v[184:187], v[200:203], v[52:55]
	v_mfma_f32_16x16x32_bf16 v[48:51], v[192:195], v[200:203], v[48:51]
	v_mfma_f32_16x16x32_bf16 v[36:39], v[184:187], v[208:211], v[36:39]
	v_mfma_f32_16x16x32_bf16 v[32:35], v[192:195], v[208:211], v[32:35]
	v_mfma_f32_16x16x32_bf16 v[20:23], v[184:187], v[216:219], v[20:23]
	v_mfma_f32_16x16x32_bf16 v[16:19], v[192:195], v[216:219], v[16:19]
	v_mfma_f32_16x16x32_bf16 v[4:7], v[184:187], v[224:227], v[4:7]
	v_mfma_f32_16x16x32_bf16 v[0:3], v[192:195], v[224:227], v[0:3]
	v_mfma_f32_16x16x32_bf16 v[52:55], v[188:191], v[204:207], v[52:55]
	v_mfma_f32_16x16x32_bf16 v[48:51], v[196:199], v[204:207], v[48:51]
	v_mfma_f32_16x16x32_bf16 v[36:39], v[188:191], v[212:215], v[36:39]
	v_mfma_f32_16x16x32_bf16 v[32:35], v[196:199], v[212:215], v[32:35]
	v_mfma_f32_16x16x32_bf16 v[20:23], v[188:191], v[220:223], v[20:23]
	v_mfma_f32_16x16x32_bf16 v[16:19], v[196:199], v[220:223], v[16:19]
	v_mfma_f32_16x16x32_bf16 v[4:7], v[188:191], v[228:231], v[4:7]
	v_mfma_f32_16x16x32_bf16 v[0:3], v[196:199], v[228:231], v[0:3]
	s_setprio 0
	s_barrier
	s_add_i32 s39, 0, 0x18000
	s_add_i32 s46, 0, 0x1c000
	ds_read_b128 v[168:171], v248
	ds_read_b128 v[172:175], v248 offset:1024
	ds_read_b128 v[176:179], v248 offset:2048
	ds_read_b128 v[180:183], v248 offset:3072
	ds_read_b128 v[184:187], v249
	ds_read_b128 v[188:191], v249 offset:1024
	ds_read_b128 v[192:195], v249 offset:2048
	ds_read_b128 v[196:199], v249 offset:3072
	ds_read_b128 v[200:203], v166 offset:32768
	ds_read_b128 v[204:207], v166 offset:33792
	ds_read_b128 v[208:211], v166 offset:34816
	ds_read_b128 v[212:215], v166 offset:35840
	ds_read_b128 v[216:219], v166 offset:36864
	ds_read_b128 v[220:223], v166 offset:37888
	ds_read_b128 v[224:227], v166 offset:38912
	ds_read_b128 v[228:231], v166 offset:39936
	v_lshl_add_u64 v[232:233], v[232:233], 0, v[128:129]
	s_mov_b32 m0, s23
	v_lshl_add_u64 v[246:247], v[232:233], 0, v[138:139]
	global_load_lds_dwordx4 v[246:247], off
	v_lshl_add_u64 v[232:233], v[232:233], 0, v[134:135]
	s_mov_b32 m0, s24
	s_nop 0
	global_load_lds_dwordx4 v[232:233], off
	s_waitcnt vmcnt(8)
	s_waitcnt lgkmcnt(0)
	s_barrier
	s_setprio 1
	v_mfma_f32_16x16x32_bf16 v[124:127], v[168:171], v[200:203], v[124:127]
	v_mfma_f32_16x16x32_bf16 v[120:123], v[176:179], v[200:203], v[120:123]
	v_mfma_f32_16x16x32_bf16 v[108:111], v[168:171], v[208:211], v[108:111]
	v_mfma_f32_16x16x32_bf16 v[104:107], v[176:179], v[208:211], v[104:107]
	v_mfma_f32_16x16x32_bf16 v[92:95], v[168:171], v[216:219], v[92:95]
	v_mfma_f32_16x16x32_bf16 v[88:91], v[176:179], v[216:219], v[88:91]
	v_mfma_f32_16x16x32_bf16 v[76:79], v[168:171], v[224:227], v[76:79]
	v_mfma_f32_16x16x32_bf16 v[72:75], v[176:179], v[224:227], v[72:75]
	v_mfma_f32_16x16x32_bf16 v[124:127], v[172:175], v[204:207], v[124:127]
	v_mfma_f32_16x16x32_bf16 v[120:123], v[180:183], v[204:207], v[120:123]
	v_mfma_f32_16x16x32_bf16 v[108:111], v[172:175], v[212:215], v[108:111]
	v_mfma_f32_16x16x32_bf16 v[104:107], v[180:183], v[212:215], v[104:107]
	v_mfma_f32_16x16x32_bf16 v[92:95], v[172:175], v[220:223], v[92:95]
	v_mfma_f32_16x16x32_bf16 v[88:91], v[180:183], v[220:223], v[88:91]
	v_mfma_f32_16x16x32_bf16 v[76:79], v[172:175], v[228:231], v[76:79]
	v_mfma_f32_16x16x32_bf16 v[72:75], v[180:183], v[228:231], v[72:75]
	v_mfma_f32_16x16x32_bf16 v[116:119], v[184:187], v[200:203], v[116:119]
	v_mfma_f32_16x16x32_bf16 v[112:115], v[192:195], v[200:203], v[112:115]
	v_mfma_f32_16x16x32_bf16 v[100:103], v[184:187], v[208:211], v[100:103]
	v_mfma_f32_16x16x32_bf16 v[96:99], v[192:195], v[208:211], v[96:99]
	v_mfma_f32_16x16x32_bf16 v[84:87], v[184:187], v[216:219], v[84:87]
	v_mfma_f32_16x16x32_bf16 v[80:83], v[192:195], v[216:219], v[80:83]
	v_mfma_f32_16x16x32_bf16 v[68:71], v[184:187], v[224:227], v[68:71]
	v_mfma_f32_16x16x32_bf16 v[64:67], v[192:195], v[224:227], v[64:67]
	v_mfma_f32_16x16x32_bf16 v[116:119], v[188:191], v[204:207], v[116:119]
	v_mfma_f32_16x16x32_bf16 v[112:115], v[196:199], v[204:207], v[112:115]
	v_mfma_f32_16x16x32_bf16 v[100:103], v[188:191], v[212:215], v[100:103]
	v_mfma_f32_16x16x32_bf16 v[96:99], v[196:199], v[212:215], v[96:99]
	v_mfma_f32_16x16x32_bf16 v[84:87], v[188:191], v[220:223], v[84:87]
	v_mfma_f32_16x16x32_bf16 v[80:83], v[196:199], v[220:223], v[80:83]
	v_mfma_f32_16x16x32_bf16 v[68:71], v[188:191], v[228:231], v[68:71]
	v_mfma_f32_16x16x32_bf16 v[64:67], v[196:199], v[228:231], v[64:67]
	s_setprio 0
	s_barrier
; #define PG8_STAGE(bufoff, gbase, voff) do { _Pragma("unroll") for (int _i = 0; _i < 2; ++_i) \
;         __builtin_amdgcn_global_load_lds((const unsigned*)((const char*)(gbase) + (voff)[_i]), (LAS unsigned*)(lds + (bufoff) + ldsw + _i * 8192), 16, 0, 0); } while (0)
; #define PG8_LDA(dst, b, h) do { _Pragma("unroll") for (int m = 0; m < 4; ++m) _Pragma("unroll") for (int k = 0; k < 2; ++k) dst[m][k] = *(const LAS bf16x8*)(lds + PG8_SA(b, h) + aoff + m * 2048 + k * 1024); } while (0)
; #define PG8_WAIT_V(n) asm volatile("s_waitcnt vmcnt(" #n ")" ::: "memory")
; #define PG8_WAIT_L(n) asm volatile("s_waitcnt lgkmcnt(" #n ")" ::: "memory")
; #define PG8_BAR __builtin_amdgcn_s_barrier()
; #define PG8_SCHED __builtin_amdgcn_sched_barrier(0)
;     ...
;             PG8_LDA(At, 1, 1); PG8_STAGE(PG8_SB(1, 0), b3, voffB); PG8_STAGE(PG8_SB(1, 1), b3 + hstepB, voffB); PG8_STAGE(PG8_SA(1, 0), a3, voffA);
;             PG8_WAIT_V(8); PG8_WAIT_L(0); PG8_BAR; PG8_MMA(1, 0, At, B0); PG8_MMA(1, 1, At, B1); PG8_BAR; PG8_SCHED;
	s_add_i32 s39, s39, s2
	v_lshl_add_u64 v[232:233], v[236:237], 0, s[12:13]
	s_mov_b32 m0, s39
	ds_read_b128 v[200:203], v166 offset:49152
	ds_read_b128 v[204:207], v166 offset:50176
	ds_read_b128 v[208:211], v166 offset:51200
	ds_read_b128 v[212:215], v166 offset:52224
	ds_read_b128 v[216:219], v166 offset:53248
	ds_read_b128 v[220:223], v166 offset:54272
	ds_read_b128 v[224:227], v166 offset:55296
	ds_read_b128 v[228:231], v166 offset:56320
	global_load_lds_dwordx4 v[232:233], off
	v_lshl_add_u64 v[232:233], v[238:239], 0, s[12:13]
	s_add_i32 m0, s39, 0x2000
	s_add_i32 s39, s46, s2
	global_load_lds_dwordx4 v[232:233], off
	v_lshl_add_u64 v[232:233], v[240:241], 0, s[12:13]
	s_mov_b32 m0, s39
	s_nop 0
	global_load_lds_dwordx4 v[232:233], off
	v_lshl_add_u64 v[232:233], v[234:235], 0, s[12:13]
	s_add_i32 m0, s39, 0x2000
	s_nop 0
	global_load_lds_dwordx4 v[232:233], off
	v_lshl_add_u64 v[232:233], v[242:243], 0, s[12:13]
	s_mov_b32 m0, s30
	s_nop 0
	global_load_lds_dwordx4 v[232:233], off
	v_lshl_add_u64 v[232:233], v[244:245], 0, s[12:13]
	s_mov_b32 m0, s31
	s_nop 0
	global_load_lds_dwordx4 v[232:233], off
	s_waitcnt vmcnt(8)
	s_waitcnt lgkmcnt(0)
	s_barrier
	s_setprio 1
	v_mfma_f32_16x16x32_bf16 v[60:63], v[168:171], v[200:203], v[60:63]
	v_mfma_f32_16x16x32_bf16 v[56:59], v[176:179], v[200:203], v[56:59]
	v_mfma_f32_16x16x32_bf16 v[44:47], v[168:171], v[208:211], v[44:47]
	v_mfma_f32_16x16x32_bf16 v[40:43], v[176:179], v[208:211], v[40:43]
	v_mfma_f32_16x16x32_bf16 v[28:31], v[168:171], v[216:219], v[28:31]
	v_mfma_f32_16x16x32_bf16 v[24:27], v[176:179], v[216:219], v[24:27]
	v_mfma_f32_16x16x32_bf16 v[12:15], v[168:171], v[224:227], v[12:15]
	v_mfma_f32_16x16x32_bf16 v[8:11], v[176:179], v[224:227], v[8:11]
	v_mfma_f32_16x16x32_bf16 v[60:63], v[172:175], v[204:207], v[60:63]
	v_mfma_f32_16x16x32_bf16 v[56:59], v[180:183], v[204:207], v[56:59]
	v_mfma_f32_16x16x32_bf16 v[44:47], v[172:175], v[212:215], v[44:47]
	v_mfma_f32_16x16x32_bf16 v[40:43], v[180:183], v[212:215], v[40:43]
	v_mfma_f32_16x16x32_bf16 v[28:31], v[172:175], v[220:223], v[28:31]
	v_mfma_f32_16x16x32_bf16 v[24:27], v[180:183], v[220:223], v[24:27]
	v_mfma_f32_16x16x32_bf16 v[12:15], v[172:175], v[228:231], v[12:15]
	v_mfma_f32_16x16x32_bf16 v[8:11], v[180:183], v[228:231], v[8:11]
	v_mfma_f32_16x16x32_bf16 v[52:55], v[184:187], v[200:203], v[52:55]
	v_mfma_f32_16x16x32_bf16 v[48:51], v[192:195], v[200:203], v[48:51]
	v_mfma_f32_16x16x32_bf16 v[36:39], v[184:187], v[208:211], v[36:39]
	v_mfma_f32_16x16x32_bf16 v[32:35], v[192:195], v[208:211], v[32:35]
	v_mfma_f32_16x16x32_bf16 v[20:23], v[184:187], v[216:219], v[20:23]
	v_mfma_f32_16x16x32_bf16 v[16:19], v[192:195], v[216:219], v[16:19]
	v_mfma_f32_16x16x32_bf16 v[4:7], v[184:187], v[224:227], v[4:7]
	v_mfma_f32_16x16x32_bf16 v[0:3], v[192:195], v[224:227], v[0:3]
	v_mfma_f32_16x16x32_bf16 v[52:55], v[188:191], v[204:207], v[52:55]
	v_mfma_f32_16x16x32_bf16 v[48:51], v[196:199], v[204:207], v[48:51]
	v_mfma_f32_16x16x32_bf16 v[36:39], v[188:191], v[212:215], v[36:39]
	v_mfma_f32_16x16x32_bf16 v[32:35], v[196:199], v[212:215], v[32:35]
	v_mfma_f32_16x16x32_bf16 v[20:23], v[188:191], v[220:223], v[20:23]
	v_mfma_f32_16x16x32_bf16 v[16:19], v[196:199], v[220:223], v[16:19]
	v_mfma_f32_16x16x32_bf16 v[4:7], v[188:191], v[228:231], v[4:7]
	v_mfma_f32_16x16x32_bf16 v[0:3], v[196:199], v[228:231], v[0:3]
	s_setprio 0
	s_barrier
	s_add_i32 s38, s38, 2
	s_add_u32 s18, s18, 0x100
	s_addc_u32 s19, s19, 0
	s_cmp_gt_u32 s38, 61
	s_cbranch_scc0 .LBB0_1066
	s_and_b64 vcc, exec, s[14:15]
	s_cbranch_vccz .LBB0_1069
	s_barrier

; #define PG8_STAGE(bufoff, gbase, voff) do { _Pragma("unroll") for (int _i = 0; _i < 2; ++_i) \
;         __builtin_amdgcn_global_load_lds((const unsigned*)((const char*)(gbase) + (voff)[_i]), (LAS unsigned*)(lds + (bufoff) + ldsw + _i * 8192), 16, 0, 0); } while (0)
; #define PG8_LDA(dst, b, h) do { _Pragma("unroll") for (int m = 0; m < 4; ++m) _Pragma("unroll") for (int k = 0; k < 2; ++k) dst[m][k] = *(const LAS bf16x8*)(lds + PG8_SA(b, h) + aoff + m * 2048 + k * 1024); } while (0)
; #define PG8_LDB(dst, b, h) do { _Pragma("unroll") for (int n = 0; n < 2; ++n) _Pragma("unroll") for (int k = 0; k < 2; ++k) dst[n][k] = *(const LAS bf16x8*)(lds + PG8_SB(b, h) + boff + n * 2048 + k * 1024); } while (0)
; #define PG8_WAIT_V(n) asm volatile("s_waitcnt vmcnt(" #n ")" ::: "memory")
; #define PG8_WAIT_L(n) asm volatile("s_waitcnt lgkmcnt(" #n ")" ::: "memory")
; #define PG8_BAR __builtin_amdgcn_s_barrier()
; #define PG8_SCHED __builtin_amdgcn_sched_barrier(0)
;     ...
;             const char* a2 = last ? nA : cA + (size_t)(t + 2) * kstep; const char* b2 = last ? nB : cB + (size_t)(t + 2) * kstep;
;             const char* a3 = a2 + kstep; const char* b3 = b2 + kstep;
;             if constexpr (SP2) {
;             PG8_LDB(B0, 0, 0); PG8_LDB(B1, 0, 1); PG8_SCHED; PG8_LDA(At, 0, 0); PG8_STAGE(PG8_SA(1, 1), a1 + hstepA, voffA);
;             PG8_WAIT_V(8); PG8_WAIT_L(0); PG8_BAR; PG8_MMA(0, 0, At, B0); PG8_MMA(0, 1, At, B1); PG8_BAR; PG8_SCHED;
;             PG8_LDA(At, 0, 1); PG8_STAGE(PG8_SB(0, 0), b2, voffB); PG8_STAGE(PG8_SB(0, 1), b2 + hstepB, voffB); PG8_STAGE(PG8_SA(0, 0), a2, voffA);
.LBB0_1148:
	ds_read_b128 v[168:171], v164
	ds_read_b128 v[172:175], v164 offset:1024
	ds_read_b128 v[176:179], v164 offset:2048
	ds_read_b128 v[180:183], v164 offset:3072
	ds_read_b128 v[184:187], v165
	ds_read_b128 v[188:191], v165 offset:1024
	ds_read_b128 v[192:195], v165 offset:2048
	ds_read_b128 v[196:199], v165 offset:3072
	ds_read_b128 v[200:203], v166
	ds_read_b128 v[204:207], v166 offset:1024
	ds_read_b128 v[208:211], v166 offset:2048
	ds_read_b128 v[212:215], v166 offset:3072
	ds_read_b128 v[216:219], v166 offset:4096
	ds_read_b128 v[220:223], v166 offset:5120
	ds_read_b128 v[224:227], v166 offset:6144
	ds_read_b128 v[228:231], v166 offset:7168
	v_lshl_add_u64 v[232:233], v[152:153], 0, s[18:19]
	s_cmpk_eq_i32 s18, 0x7f00
	v_lshl_add_u64 v[232:233], v[232:233], 0, s[16:17]
	v_lshl_add_u64 v[234:235], v[158:159], 0, s[18:19]
	s_cselect_b64 vcc, -1, 0
	v_cndmask_b32_e32 v233, v233, v149, vcc
	v_cndmask_b32_e32 v232, v232, v148, vcc
	v_cndmask_b32_e32 v235, v235, v151, vcc
	v_cndmask_b32_e32 v234, v234, v150, vcc
	s_add_i32 m0, s3, 0xc000
	v_lshl_add_u64 v[236:237], v[156:157], 0, s[18:19]
	global_load_lds_dwordx4 v[236:237], off
	v_lshl_add_u64 v[236:237], v[154:155], 0, s[18:19]
	s_add_i32 m0, s3, 0xe000
	s_nop 0
	global_load_lds_dwordx4 v[236:237], off
	s_waitcnt vmcnt(8)
	s_waitcnt lgkmcnt(0)
	s_barrier
	s_setprio 1
	v_mfma_f32_16x16x32_bf16 v[124:127], v[168:171], v[200:203], v[124:127]
	v_mfma_f32_16x16x32_bf16 v[120:123], v[176:179], v[200:203], v[120:123]
	v_mfma_f32_16x16x32_bf16 v[108:111], v[168:171], v[208:211], v[108:111]
	v_mfma_f32_16x16x32_bf16 v[104:107], v[176:179], v[208:211], v[104:107]
	v_mfma_f32_16x16x32_bf16 v[92:95], v[168:171], v[216:219], v[92:95]
	v_mfma_f32_16x16x32_bf16 v[88:91], v[176:179], v[216:219], v[88:91]
	v_mfma_f32_16x16x32_bf16 v[76:79], v[168:171], v[224:227], v[76:79]
	v_mfma_f32_16x16x32_bf16 v[72:75], v[176:179], v[224:227], v[72:75]
	v_mfma_f32_16x16x32_bf16 v[124:127], v[172:175], v[204:207], v[124:127]
	v_mfma_f32_16x16x32_bf16 v[120:123], v[180:183], v[204:207], v[120:123]
	v_mfma_f32_16x16x32_bf16 v[108:111], v[172:175], v[212:215], v[108:111]
	v_mfma_f32_16x16x32_bf16 v[104:107], v[180:183], v[212:215], v[104:107]
	v_mfma_f32_16x16x32_bf16 v[92:95], v[172:175], v[220:223], v[92:95]
	v_mfma_f32_16x16x32_bf16 v[88:91], v[180:183], v[220:223], v[88:91]
	v_mfma_f32_16x16x32_bf16 v[76:79], v[172:175], v[228:231], v[76:79]
	v_mfma_f32_16x16x32_bf16 v[72:75], v[180:183], v[228:231], v[72:75]
	v_mfma_f32_16x16x32_bf16 v[116:119], v[184:187], v[200:203], v[116:119]
	v_mfma_f32_16x16x32_bf16 v[112:115], v[192:195], v[200:203], v[112:115]
	v_mfma_f32_16x16x32_bf16 v[100:103], v[184:187], v[208:211], v[100:103]
	v_mfma_f32_16x16x32_bf16 v[96:99], v[192:195], v[208:211], v[96:99]
	v_mfma_f32_16x16x32_bf16 v[84:87], v[184:187], v[216:219], v[84:87]
	v_mfma_f32_16x16x32_bf16 v[80:83], v[192:195], v[216:219], v[80:83]
	v_mfma_f32_16x16x32_bf16 v[68:71], v[184:187], v[224:227], v[68:71]
	v_mfma_f32_16x16x32_bf16 v[64:67], v[192:195], v[224:227], v[64:67]
	v_mfma_f32_16x16x32_bf16 v[116:119], v[188:191], v[204:207], v[116:119]
	v_mfma_f32_16x16x32_bf16 v[112:115], v[196:199], v[204:207], v[112:115]
	v_mfma_f32_16x16x32_bf16 v[100:103], v[188:191], v[212:215], v[100:103]
	v_mfma_f32_16x16x32_bf16 v[96:99], v[196:199], v[212:215], v[96:99]
	v_mfma_f32_16x16x32_bf16 v[84:87], v[188:191], v[220:223], v[84:87]
	v_mfma_f32_16x16x32_bf16 v[80:83], v[196:199], v[220:223], v[80:83]
	v_mfma_f32_16x16x32_bf16 v[68:71], v[188:191], v[228:231], v[68:71]
	v_mfma_f32_16x16x32_bf16 v[64:67], v[196:199], v[228:231], v[64:67]
	s_setprio 0
	s_barrier
	s_add_i32 s21, s43, s2
	v_lshl_add_u64 v[236:237], v[234:235], 0, v[130:131]
	s_mov_b32 m0, s21
	ds_read_b128 v[200:203], v166 offset:16384
	ds_read_b128 v[204:207], v166 offset:17408
	ds_read_b128 v[208:211], v166 offset:18432
	ds_read_b128 v[212:215], v166 offset:19456
	ds_read_b128 v[216:219], v166 offset:20480
	ds_read_b128 v[220:223], v166 offset:21504
	ds_read_b128 v[224:227], v166 offset:22528
	ds_read_b128 v[228:231], v166 offset:23552
	global_load_lds_dwordx4 v[236:237], off
	v_lshl_add_u64 v[238:239], v[234:235], 0, v[134:135]
	s_add_i32 m0, s21, 0x2000
	v_lshl_add_u64 v[234:235], v[234:235], 0, v[138:139]
	s_add_i32 s21, s46, s2
	global_load_lds_dwordx4 v[238:239], off
	v_lshl_add_u64 v[240:241], v[234:235], 0, v[130:131]
	s_mov_b32 m0, s21
	v_lshl_add_u64 v[234:235], v[234:235], 0, v[134:135]
	global_load_lds_dwordx4 v[240:241], off
	s_add_i32 m0, s21, 0x2000
	v_lshl_add_u64 v[242:243], v[232:233], 0, v[128:129]
	global_load_lds_dwordx4 v[234:235], off
	s_mov_b32 m0, s3
	v_lshl_add_u64 v[244:245], v[232:233], 0, v[132:133]
	global_load_lds_dwordx4 v[242:243], off
	s_mov_b32 m0, s22
	s_nop 0
	global_load_lds_dwordx4 v[244:245], off
	s_waitcnt vmcnt(8)
	s_waitcnt lgkmcnt(0)
	s_barrier
; #define PG8_STAGE(bufoff, gbase, voff) do { _Pragma("unroll") for (int _i = 0; _i < 2; ++_i) \
;         __builtin_amdgcn_global_load_lds((const unsigned*)((const char*)(gbase) + (voff)[_i]), (LAS unsigned*)(lds + (bufoff) + ldsw + _i * 8192), 16, 0, 0); } while (0)
; #define PG8_LDA(dst, b, h) do { _Pragma("unroll") for (int m = 0; m < 4; ++m) _Pragma("unroll") for (int k = 0; k < 2; ++k) dst[m][k] = *(const LAS bf16x8*)(lds + PG8_SA(b, h) + aoff + m * 2048 + k * 1024); } while (0)
; #define PG8_LDB(dst, b, h) do { _Pragma("unroll") for (int n = 0; n < 2; ++n) _Pragma("unroll") for (int k = 0; k < 2; ++k) dst[n][k] = *(const LAS bf16x8*)(lds + PG8_SB(b, h) + boff + n * 2048 + k * 1024); } while (0)
; #define PG8_WAIT_V(n) asm volatile("s_waitcnt vmcnt(" #n ")" ::: "memory")
; #define PG8_WAIT_L(n) asm volatile("s_waitcnt lgkmcnt(" #n ")" ::: "memory")
; #define PG8_BAR __builtin_amdgcn_s_barrier()
; #define PG8_SCHED __builtin_amdgcn_sched_barrier(0)
;     ...
;             PG8_WAIT_V(8); PG8_WAIT_L(0); PG8_BAR; PG8_MMA(1, 0, At, B0); PG8_MMA(1, 1, At, B1); PG8_BAR; PG8_SCHED;
;             PG8_LDB(B0, 1, 0); PG8_LDB(B1, 1, 1); PG8_SCHED; PG8_LDA(At, 1, 0); PG8_STAGE(PG8_SA(0, 1), a2 + hstepA, voffA);
;             PG8_WAIT_V(8); PG8_WAIT_L(0); PG8_BAR; PG8_MMA(0, 0, At, B0); PG8_MMA(0, 1, At, B1); PG8_BAR; PG8_SCHED;
	s_setprio 1
	v_mfma_f32_16x16x32_bf16 v[60:63], v[168:171], v[200:203], v[60:63]
	v_mfma_f32_16x16x32_bf16 v[56:59], v[176:179], v[200:203], v[56:59]
	v_mfma_f32_16x16x32_bf16 v[44:47], v[168:171], v[208:211], v[44:47]
	v_mfma_f32_16x16x32_bf16 v[40:43], v[176:179], v[208:211], v[40:43]
	v_mfma_f32_16x16x32_bf16 v[28:31], v[168:171], v[216:219], v[28:31]
	v_mfma_f32_16x16x32_bf16 v[24:27], v[176:179], v[216:219], v[24:27]
	v_mfma_f32_16x16x32_bf16 v[12:15], v[168:171], v[224:227], v[12:15]
	v_mfma_f32_16x16x32_bf16 v[8:11], v[176:179], v[224:227], v[8:11]
	v_mfma_f32_16x16x32_bf16 v[60:63], v[172:175], v[204:207], v[60:63]
	v_mfma_f32_16x16x32_bf16 v[56:59], v[180:183], v[204:207], v[56:59]
	v_mfma_f32_16x16x32_bf16 v[44:47], v[172:175], v[212:215], v[44:47]
	v_mfma_f32_16x16x32_bf16 v[40:43], v[180:183], v[212:215], v[40:43]
	v_mfma_f32_16x16x32_bf16 v[28:31], v[172:175], v[220:223], v[28:31]
	v_mfma_f32_16x16x32_bf16 v[24:27], v[180:183], v[220:223], v[24:27]
	v_mfma_f32_16x16x32_bf16 v[12:15], v[172:175], v[228:231], v[12:15]
	v_mfma_f32_16x16x32_bf16 v[8:11], v[180:183], v[228:231], v[8:11]
	v_mfma_f32_16x16x32_bf16 v[52:55], v[184:187], v[200:203], v[52:55]
	v_mfma_f32_16x16x32_bf16 v[48:51], v[192:195], v[200:203], v[48:51]
	v_mfma_f32_16x16x32_bf16 v[36:39], v[184:187], v[208:211], v[36:39]
	v_mfma_f32_16x16x32_bf16 v[32:35], v[192:195], v[208:211], v[32:35]
	v_mfma_f32_16x16x32_bf16 v[20:23], v[184:187], v[216:219], v[20:23]
	v_mfma_f32_16x16x32_bf16 v[16:19], v[192:195], v[216:219], v[16:19]
	v_mfma_f32_16x16x32_bf16 v[4:7], v[184:187], v[224:227], v[4:7]
	v_mfma_f32_16x16x32_bf16 v[0:3], v[192:195], v[224:227], v[0:3]
	v_mfma_f32_16x16x32_bf16 v[52:55], v[188:191], v[204:207], v[52:55]
	v_mfma_f32_16x16x32_bf16 v[48:51], v[196:199], v[204:207], v[48:51]
	v_mfma_f32_16x16x32_bf16 v[36:39], v[188:191], v[212:215], v[36:39]
	v_mfma_f32_16x16x32_bf16 v[32:35], v[196:199], v[212:215], v[32:35]
	v_mfma_f32_16x16x32_bf16 v[20:23], v[188:191], v[220:223], v[20:23]
	v_mfma_f32_16x16x32_bf16 v[16:19], v[196:199], v[220:223], v[16:19]
	v_mfma_f32_16x16x32_bf16 v[4:7], v[188:191], v[228:231], v[4:7]
	v_mfma_f32_16x16x32_bf16 v[0:3], v[196:199], v[228:231], v[0:3]
	s_setprio 0
	s_barrier
	s_add_i32 s21, 0, 0x18000
	s_add_i32 s40, 0, 0x1c000
	ds_read_b128 v[168:171], v248
	ds_read_b128 v[172:175], v248 offset:1024
	ds_read_b128 v[176:179], v248 offset:2048
	ds_read_b128 v[180:183], v248 offset:3072
	ds_read_b128 v[184:187], v249
	ds_read_b128 v[188:191], v249 offset:1024
	ds_read_b128 v[192:195], v249 offset:2048
	ds_read_b128 v[196:199], v249 offset:3072
	ds_read_b128 v[200:203], v166 offset:32768
	ds_read_b128 v[204:207], v166 offset:33792
	ds_read_b128 v[208:211], v166 offset:34816
	ds_read_b128 v[212:215], v166 offset:35840
	ds_read_b128 v[216:219], v166 offset:36864
	ds_read_b128 v[220:223], v166 offset:37888
	ds_read_b128 v[224:227], v166 offset:38912
	ds_read_b128 v[228:231], v166 offset:39936
	v_lshl_add_u64 v[232:233], v[232:233], 0, v[136:137]
	s_mov_b32 m0, s23
	v_lshl_add_u64 v[246:247], v[232:233], 0, v[128:129]
	global_load_lds_dwordx4 v[246:247], off
	v_lshl_add_u64 v[232:233], v[232:233], 0, v[132:133]
	s_mov_b32 m0, s24
	s_nop 0
	global_load_lds_dwordx4 v[232:233], off
	s_waitcnt vmcnt(8)
	s_waitcnt lgkmcnt(0)
	s_barrier
	s_setprio 1
	v_mfma_f32_16x16x32_bf16 v[124:127], v[168:171], v[200:203], v[124:127]
	v_mfma_f32_16x16x32_bf16 v[120:123], v[176:179], v[200:203], v[120:123]
	v_mfma_f32_16x16x32_bf16 v[108:111], v[168:171], v[208:211], v[108:111]
	v_mfma_f32_16x16x32_bf16 v[104:107], v[176:179], v[208:211], v[104:107]
	v_mfma_f32_16x16x32_bf16 v[92:95], v[168:171], v[216:219], v[92:95]
	v_mfma_f32_16x16x32_bf16 v[88:91], v[176:179], v[216:219], v[88:91]
	v_mfma_f32_16x16x32_bf16 v[76:79], v[168:171], v[224:227], v[76:79]
	v_mfma_f32_16x16x32_bf16 v[72:75], v[176:179], v[224:227], v[72:75]
	v_mfma_f32_16x16x32_bf16 v[124:127], v[172:175], v[204:207], v[124:127]
	v_mfma_f32_16x16x32_bf16 v[120:123], v[180:183], v[204:207], v[120:123]
	v_mfma_f32_16x16x32_bf16 v[108:111], v[172:175], v[212:215], v[108:111]
	v_mfma_f32_16x16x32_bf16 v[104:107], v[180:183], v[212:215], v[104:107]
	v_mfma_f32_16x16x32_bf16 v[92:95], v[172:175], v[220:223], v[92:95]
	v_mfma_f32_16x16x32_bf16 v[88:91], v[180:183], v[220:223], v[88:91]
	v_mfma_f32_16x16x32_bf16 v[76:79], v[172:175], v[228:231], v[76:79]
	v_mfma_f32_16x16x32_bf16 v[72:75], v[180:183], v[228:231], v[72:75]
	v_mfma_f32_16x16x32_bf16 v[116:119], v[184:187], v[200:203], v[116:119]
	v_mfma_f32_16x16x32_bf16 v[112:115], v[192:195], v[200:203], v[112:115]
	v_mfma_f32_16x16x32_bf16 v[100:103], v[184:187], v[208:211], v[100:103]
	v_mfma_f32_16x16x32_bf16 v[96:99], v[192:195], v[208:211], v[96:99]
	v_mfma_f32_16x16x32_bf16 v[84:87], v[184:187], v[216:219], v[84:87]
	v_mfma_f32_16x16x32_bf16 v[80:83], v[192:195], v[216:219], v[80:83]
	v_mfma_f32_16x16x32_bf16 v[68:71], v[184:187], v[224:227], v[68:71]
	v_mfma_f32_16x16x32_bf16 v[64:67], v[192:195], v[224:227], v[64:67]
	v_mfma_f32_16x16x32_bf16 v[116:119], v[188:191], v[204:207], v[116:119]
	v_mfma_f32_16x16x32_bf16 v[112:115], v[196:199], v[204:207], v[112:115]
	v_mfma_f32_16x16x32_bf16 v[100:103], v[188:191], v[212:215], v[100:103]
	v_mfma_f32_16x16x32_bf16 v[96:99], v[196:199], v[212:215], v[96:99]
	v_mfma_f32_16x16x32_bf16 v[84:87], v[188:191], v[220:223], v[84:87]
	v_mfma_f32_16x16x32_bf16 v[80:83], v[196:199], v[220:223], v[80:83]
	v_mfma_f32_16x16x32_bf16 v[68:71], v[188:191], v[228:231], v[68:71]
	v_mfma_f32_16x16x32_bf16 v[64:67], v[196:199], v[228:231], v[64:67]
	s_setprio 0
	s_barrier
; #define PG8_STAGE(bufoff, gbase, voff) do { _Pragma("unroll") for (int _i = 0; _i < 2; ++_i) \
;         __builtin_amdgcn_global_load_lds((const unsigned*)((const char*)(gbase) + (voff)[_i]), (LAS unsigned*)(lds + (bufoff) + ldsw + _i * 8192), 16, 0, 0); } while (0)
; #define PG8_LDA(dst, b, h) do { _Pragma("unroll") for (int m = 0; m < 4; ++m) _Pragma("unroll") for (int k = 0; k < 2; ++k) dst[m][k] = *(const LAS bf16x8*)(lds + PG8_SA(b, h) + aoff + m * 2048 + k * 1024); } while (0)
; #define PG8_WAIT_V(n) asm volatile("s_waitcnt vmcnt(" #n ")" ::: "memory")
; #define PG8_WAIT_L(n) asm volatile("s_waitcnt lgkmcnt(" #n ")" ::: "memory")
; #define PG8_BAR __builtin_amdgcn_s_barrier()
; #define PG8_SCHED __builtin_amdgcn_sched_barrier(0)
;     ...
;             PG8_LDA(At, 1, 1); PG8_STAGE(PG8_SB(1, 0), b3, voffB); PG8_STAGE(PG8_SB(1, 1), b3 + hstepB, voffB); PG8_STAGE(PG8_SA(1, 0), a3, voffA);
;             PG8_WAIT_V(8); PG8_WAIT_L(0); PG8_BAR; PG8_MMA(1, 0, At, B0); PG8_MMA(1, 1, At, B1); PG8_BAR; PG8_SCHED;
	s_add_i32 s21, s21, s2
	v_lshl_add_u64 v[232:233], v[236:237], 0, s[12:13]
	s_mov_b32 m0, s21
	ds_read_b128 v[200:203], v166 offset:49152
	ds_read_b128 v[204:207], v166 offset:50176
	ds_read_b128 v[208:211], v166 offset:51200
	ds_read_b128 v[212:215], v166 offset:52224
	ds_read_b128 v[216:219], v166 offset:53248
	ds_read_b128 v[220:223], v166 offset:54272
	ds_read_b128 v[224:227], v166 offset:55296
	ds_read_b128 v[228:231], v166 offset:56320
	global_load_lds_dwordx4 v[232:233], off
	v_lshl_add_u64 v[232:233], v[238:239], 0, s[12:13]
	s_add_i32 m0, s21, 0x2000
	s_add_i32 s21, s40, s2
	global_load_lds_dwordx4 v[232:233], off
	v_lshl_add_u64 v[232:233], v[240:241], 0, s[12:13]
	s_mov_b32 m0, s21
	s_nop 0
	global_load_lds_dwordx4 v[232:233], off
	v_lshl_add_u64 v[232:233], v[234:235], 0, s[12:13]
	s_add_i32 m0, s21, 0x2000
	s_nop 0
	global_load_lds_dwordx4 v[232:233], off
	v_lshl_add_u64 v[232:233], v[242:243], 0, s[12:13]
	s_mov_b32 m0, s30
	s_nop 0
	global_load_lds_dwordx4 v[232:233], off
	v_lshl_add_u64 v[232:233], v[244:245], 0, s[12:13]
	s_mov_b32 m0, s31
	s_nop 0
	global_load_lds_dwordx4 v[232:233], off
	s_waitcnt vmcnt(8)
	s_waitcnt lgkmcnt(0)
	s_barrier
	s_setprio 1
	v_mfma_f32_16x16x32_bf16 v[60:63], v[168:171], v[200:203], v[60:63]
	v_mfma_f32_16x16x32_bf16 v[56:59], v[176:179], v[200:203], v[56:59]
	v_mfma_f32_16x16x32_bf16 v[44:47], v[168:171], v[208:211], v[44:47]
	v_mfma_f32_16x16x32_bf16 v[40:43], v[176:179], v[208:211], v[40:43]
	v_mfma_f32_16x16x32_bf16 v[28:31], v[168:171], v[216:219], v[28:31]
	v_mfma_f32_16x16x32_bf16 v[24:27], v[176:179], v[216:219], v[24:27]
	v_mfma_f32_16x16x32_bf16 v[12:15], v[168:171], v[224:227], v[12:15]
	v_mfma_f32_16x16x32_bf16 v[8:11], v[176:179], v[224:227], v[8:11]
	v_mfma_f32_16x16x32_bf16 v[60:63], v[172:175], v[204:207], v[60:63]
	v_mfma_f32_16x16x32_bf16 v[56:59], v[180:183], v[204:207], v[56:59]
	v_mfma_f32_16x16x32_bf16 v[44:47], v[172:175], v[212:215], v[44:47]
	v_mfma_f32_16x16x32_bf16 v[40:43], v[180:183], v[212:215], v[40:43]
	v_mfma_f32_16x16x32_bf16 v[28:31], v[172:175], v[220:223], v[28:31]
	v_mfma_f32_16x16x32_bf16 v[24:27], v[180:183], v[220:223], v[24:27]
	v_mfma_f32_16x16x32_bf16 v[12:15], v[172:175], v[228:231], v[12:15]
	v_mfma_f32_16x16x32_bf16 v[8:11], v[180:183], v[228:231], v[8:11]
	v_mfma_f32_16x16x32_bf16 v[52:55], v[184:187], v[200:203], v[52:55]
	v_mfma_f32_16x16x32_bf16 v[48:51], v[192:195], v[200:203], v[48:51]
	v_mfma_f32_16x16x32_bf16 v[36:39], v[184:187], v[208:211], v[36:39]
	v_mfma_f32_16x16x32_bf16 v[32:35], v[192:195], v[208:211], v[32:35]
	v_mfma_f32_16x16x32_bf16 v[20:23], v[184:187], v[216:219], v[20:23]
	v_mfma_f32_16x16x32_bf16 v[16:19], v[192:195], v[216:219], v[16:19]
	v_mfma_f32_16x16x32_bf16 v[4:7], v[184:187], v[224:227], v[4:7]
	v_mfma_f32_16x16x32_bf16 v[0:3], v[192:195], v[224:227], v[0:3]
	v_mfma_f32_16x16x32_bf16 v[52:55], v[188:191], v[204:207], v[52:55]
	v_mfma_f32_16x16x32_bf16 v[48:51], v[196:199], v[204:207], v[48:51]
	v_mfma_f32_16x16x32_bf16 v[36:39], v[188:191], v[212:215], v[36:39]
	v_mfma_f32_16x16x32_bf16 v[32:35], v[196:199], v[212:215], v[32:35]
	v_mfma_f32_16x16x32_bf16 v[20:23], v[188:191], v[220:223], v[20:23]
	v_mfma_f32_16x16x32_bf16 v[16:19], v[196:199], v[220:223], v[16:19]
	v_mfma_f32_16x16x32_bf16 v[4:7], v[188:191], v[228:231], v[4:7]
	v_mfma_f32_16x16x32_bf16 v[0:3], v[196:199], v[228:231], v[0:3]
	s_setprio 0
	s_barrier
	s_add_i32 s20, s20, 2
	s_add_u32 s18, s18, 0x100
	s_addc_u32 s19, s19, 0
	s_cmpk_gt_u32 s20, 0xfd
	s_cbranch_scc0 .LBB0_1148
	s_and_b64 vcc, exec, s[14:15]
	s_cbranch_vccz .LBB0_1151
	s_barrier
